# k24 + M-phase entry: s_setprio 1 raised before the barrier and the redundant post-barrier lgkmcnt(0) dropped, so the first MFMA issues right after barrier release
# speedup vs baseline: 1.0032x; 1.0032x over previous
.LBB0_444:
	s_add_u32 s48, s46, 0x20080
	s_addc_u32 s49, s47, 0
	s_add_u32 s25, s50, 0x100
	s_addc_u32 s64, s51, 0
	s_mov_b32 s65, -2
	s_add_u32 s46, s48, 0xfffe0080
	s_addc_u32 s47, s49, -1
	s_add_i32 s84, 0, 0x10000
	s_cmp_eq_u32 s65, 4
	s_cselect_b32 s47, s15, s47
	s_cselect_b32 s46, s14, s46
	v_add_u32_e32 v0, s84, v147
	s_cselect_b32 s51, s17, s64
	s_cselect_b32 s50, s16, s25
	s_add_i32 s86, 0, 0x14000
	ds_read_b128 v[150:153], v0
	ds_read_b128 v[154:157], v0 offset:1024
	ds_read_b128 v[158:161], v0 offset:2048
	ds_read_b128 v[162:165], v0 offset:3072
	ds_read_b128 v[166:169], v0 offset:16384
	ds_read_b128 v[170:173], v0 offset:17408
	ds_read_b128 v[174:177], v0 offset:18432
	ds_read_b128 v[178:181], v0 offset:19456
	ds_read_b128 v[182:185], v148
	ds_read_b128 v[186:189], v148 offset:1024
	ds_read_b128 v[190:193], v148 offset:2048
	ds_read_b128 v[194:197], v148 offset:3072
	ds_read_b128 v[198:201], v148 offset:4096
	ds_read_b128 v[202:205], v148 offset:5120
	ds_read_b128 v[206:209], v148 offset:6144
	ds_read_b128 v[210:213], v148 offset:7168
	s_add_i32 m0, s59, 0xc000
	s_nop 0
	global_load_lds_dwordx4 v132, s[48:49]
	s_add_i32 m0, s59, 0xe000
	s_nop 0
	global_load_lds_dwordx4 v133, s[48:49]
	s_waitcnt vmcnt(8)
	s_waitcnt lgkmcnt(0)
	s_setprio 1
	s_barrier
	v_mfma_i32_16x16x64_i8 v[126:129], v[150:153], v[182:185], 0
	v_mfma_i32_16x16x64_i8 v[122:125], v[158:161], v[182:185], 0
	v_mfma_i32_16x16x64_i8 v[110:113], v[150:153], v[190:193], 0
	v_mfma_i32_16x16x64_i8 v[106:109], v[158:161], v[190:193], 0
	v_mfma_i32_16x16x64_i8 v[94:97], v[150:153], v[198:201], 0
	v_mfma_i32_16x16x64_i8 v[90:93], v[158:161], v[198:201], 0
	v_mfma_i32_16x16x64_i8 v[78:81], v[150:153], v[206:209], 0
	v_mfma_i32_16x16x64_i8 v[74:77], v[158:161], v[206:209], 0
	v_mfma_i32_16x16x64_i8 v[126:129], v[154:157], v[186:189], v[126:129]
	v_mfma_i32_16x16x64_i8 v[122:125], v[162:165], v[186:189], v[122:125]
	v_mfma_i32_16x16x64_i8 v[110:113], v[154:157], v[194:197], v[110:113]
	v_mfma_i32_16x16x64_i8 v[106:109], v[162:165], v[194:197], v[106:109]
	v_mfma_i32_16x16x64_i8 v[94:97], v[154:157], v[202:205], v[94:97]
	v_mfma_i32_16x16x64_i8 v[90:93], v[162:165], v[202:205], v[90:93]
	v_mfma_i32_16x16x64_i8 v[78:81], v[154:157], v[210:213], v[78:81]
	v_mfma_i32_16x16x64_i8 v[74:77], v[162:165], v[210:213], v[74:77]
	s_setprio 0
	s_setprio 1
	v_mfma_i32_16x16x64_i8 v[118:121], v[166:169], v[182:185], 0
	v_mfma_i32_16x16x64_i8 v[114:117], v[174:177], v[182:185], 0
	v_mfma_i32_16x16x64_i8 v[102:105], v[166:169], v[190:193], 0
	v_mfma_i32_16x16x64_i8 v[98:101], v[174:177], v[190:193], 0
	v_mfma_i32_16x16x64_i8 v[86:89], v[166:169], v[198:201], 0
	v_mfma_i32_16x16x64_i8 v[82:85], v[174:177], v[198:201], 0
	v_mfma_i32_16x16x64_i8 v[70:73], v[166:169], v[206:209], 0
	v_mfma_i32_16x16x64_i8 v[66:69], v[174:177], v[206:209], 0
	v_mfma_i32_16x16x64_i8 v[118:121], v[170:173], v[186:189], v[118:121]
	v_mfma_i32_16x16x64_i8 v[114:117], v[178:181], v[186:189], v[114:117]
	v_mfma_i32_16x16x64_i8 v[102:105], v[170:173], v[194:197], v[102:105]
	v_mfma_i32_16x16x64_i8 v[98:101], v[178:181], v[194:197], v[98:101]
	v_mfma_i32_16x16x64_i8 v[86:89], v[170:173], v[202:205], v[86:89]
	v_mfma_i32_16x16x64_i8 v[82:85], v[178:181], v[202:205], v[82:85]
	v_mfma_i32_16x16x64_i8 v[70:73], v[170:173], v[210:213], v[70:73]
	v_mfma_i32_16x16x64_i8 v[66:69], v[178:181], v[210:213], v[66:69]
	s_setprio 0
	s_barrier
	s_add_i32 s84, s84, s40
	ds_read_b128 v[182:185], v148 offset:16384
	ds_read_b128 v[186:189], v148 offset:17408
	ds_read_b128 v[190:193], v148 offset:18432
	ds_read_b128 v[194:197], v148 offset:19456
	ds_read_b128 v[198:201], v148 offset:20480
	ds_read_b128 v[202:205], v148 offset:21504
	ds_read_b128 v[206:209], v148 offset:22528
	ds_read_b128 v[210:213], v148 offset:23552
	s_mov_b32 m0, s84
	s_nop 0
	global_load_lds_dwordx4 v143, s[50:51]
	s_add_i32 m0, s84, 0x2000
	s_add_u32 s84, s50, 0x20000
	global_load_lds_dwordx4 v144, s[50:51]
	s_addc_u32 s85, s51, 0
	s_add_i32 s86, s86, s40
	s_mov_b32 m0, s86
	s_nop 0
	global_load_lds_dwordx4 v143, s[84:85]
	s_add_i32 m0, s86, 0x2000
	s_nop 0
	global_load_lds_dwordx4 v144, s[84:85]
	s_mov_b32 m0, s59
	s_nop 0
	global_load_lds_dwordx4 v132, s[46:47]
	s_mov_b32 m0, s60
	s_nop 0
	global_load_lds_dwordx4 v133, s[46:47]
	s_waitcnt vmcnt(8)
	s_waitcnt lgkmcnt(0)
	s_setprio 1
	s_barrier
	v_mfma_i32_16x16x64_i8 v[62:65], v[150:153], v[182:185], 0
	v_mfma_i32_16x16x64_i8 v[58:61], v[158:161], v[182:185], 0
	v_mfma_i32_16x16x64_i8 v[46:49], v[150:153], v[190:193], 0
	v_mfma_i32_16x16x64_i8 v[42:45], v[158:161], v[190:193], 0
	v_mfma_i32_16x16x64_i8 v[30:33], v[150:153], v[198:201], 0
	v_mfma_i32_16x16x64_i8 v[26:29], v[158:161], v[198:201], 0
	v_mfma_i32_16x16x64_i8 v[14:17], v[150:153], v[206:209], 0
	v_mfma_i32_16x16x64_i8 v[10:13], v[158:161], v[206:209], 0
	v_mfma_i32_16x16x64_i8 v[62:65], v[154:157], v[186:189], v[62:65]
	v_mfma_i32_16x16x64_i8 v[58:61], v[162:165], v[186:189], v[58:61]
	v_mfma_i32_16x16x64_i8 v[46:49], v[154:157], v[194:197], v[46:49]
	v_mfma_i32_16x16x64_i8 v[42:45], v[162:165], v[194:197], v[42:45]
	v_mfma_i32_16x16x64_i8 v[30:33], v[154:157], v[202:205], v[30:33]
	v_mfma_i32_16x16x64_i8 v[26:29], v[162:165], v[202:205], v[26:29]
	v_mfma_i32_16x16x64_i8 v[14:17], v[154:157], v[210:213], v[14:17]
	v_mfma_i32_16x16x64_i8 v[10:13], v[162:165], v[210:213], v[10:13]
	s_setprio 0
	s_setprio 1
	v_mfma_i32_16x16x64_i8 v[54:57], v[166:169], v[182:185], 0
	v_mfma_i32_16x16x64_i8 v[50:53], v[174:177], v[182:185], 0
	v_mfma_i32_16x16x64_i8 v[38:41], v[166:169], v[190:193], 0
	v_mfma_i32_16x16x64_i8 v[34:37], v[174:177], v[190:193], 0
	v_mfma_i32_16x16x64_i8 v[22:25], v[166:169], v[198:201], 0
	v_mfma_i32_16x16x64_i8 v[18:21], v[174:177], v[198:201], 0
	v_mfma_i32_16x16x64_i8 v[6:9], v[166:169], v[206:209], 0
	v_mfma_i32_16x16x64_i8 v[2:5], v[174:177], v[206:209], 0
	v_mfma_i32_16x16x64_i8 v[54:57], v[170:173], v[186:189], v[54:57]
	v_mfma_i32_16x16x64_i8 v[50:53], v[178:181], v[186:189], v[50:53]
	v_mfma_i32_16x16x64_i8 v[38:41], v[170:173], v[194:197], v[38:41]
	v_mfma_i32_16x16x64_i8 v[34:37], v[178:181], v[194:197], v[34:37]
	v_mfma_i32_16x16x64_i8 v[22:25], v[170:173], v[202:205], v[22:25]
	v_mfma_i32_16x16x64_i8 v[18:21], v[178:181], v[202:205], v[18:21]
	v_mfma_i32_16x16x64_i8 v[6:9], v[170:173], v[210:213], v[6:9]
	v_mfma_i32_16x16x64_i8 v[2:5], v[178:181], v[210:213], v[2:5]
	s_setprio 0
	s_barrier
	s_add_i32 s86, 0, 0x18000
	s_add_i32 s87, 0, 0x1c000
	ds_read_b128 v[150:153], v0 offset:32768
	ds_read_b128 v[154:157], v0 offset:33792
	ds_read_b128 v[158:161], v0 offset:34816
	ds_read_b128 v[162:165], v0 offset:35840
	ds_read_b128 v[166:169], v0 offset:49152
	ds_read_b128 v[170:173], v0 offset:50176
	ds_read_b128 v[174:177], v0 offset:51200
	ds_read_b128 v[178:181], v0 offset:52224
	s_add_u32 s84, s46, 0x20000
	s_mov_b32 m0, s61
	ds_read_b128 v[182:185], v148 offset:32768
	ds_read_b128 v[186:189], v148 offset:33792
	ds_read_b128 v[190:193], v148 offset:34816
	ds_read_b128 v[194:197], v148 offset:35840
	ds_read_b128 v[198:201], v148 offset:36864
	ds_read_b128 v[202:205], v148 offset:37888
	ds_read_b128 v[206:209], v148 offset:38912
	ds_read_b128 v[210:213], v148 offset:39936
	s_addc_u32 s85, s47, 0
	s_nop 0
	global_load_lds_dwordx4 v132, s[84:85]
	s_mov_b32 m0, s66
	s_nop 0
	global_load_lds_dwordx4 v133, s[84:85]
	s_waitcnt vmcnt(8)
	s_waitcnt lgkmcnt(0)
	s_setprio 1
	s_barrier
	v_mfma_i32_16x16x64_i8 v[126:129], v[150:153], v[182:185], v[126:129]
	v_mfma_i32_16x16x64_i8 v[122:125], v[158:161], v[182:185], v[122:125]
	v_mfma_i32_16x16x64_i8 v[110:113], v[150:153], v[190:193], v[110:113]
	v_mfma_i32_16x16x64_i8 v[106:109], v[158:161], v[190:193], v[106:109]
	v_mfma_i32_16x16x64_i8 v[94:97], v[150:153], v[198:201], v[94:97]
	v_mfma_i32_16x16x64_i8 v[90:93], v[158:161], v[198:201], v[90:93]
	v_mfma_i32_16x16x64_i8 v[78:81], v[150:153], v[206:209], v[78:81]
	v_mfma_i32_16x16x64_i8 v[74:77], v[158:161], v[206:209], v[74:77]
	v_mfma_i32_16x16x64_i8 v[126:129], v[154:157], v[186:189], v[126:129]
	v_mfma_i32_16x16x64_i8 v[122:125], v[162:165], v[186:189], v[122:125]
	v_mfma_i32_16x16x64_i8 v[110:113], v[154:157], v[194:197], v[110:113]
	v_mfma_i32_16x16x64_i8 v[106:109], v[162:165], v[194:197], v[106:109]
	v_mfma_i32_16x16x64_i8 v[94:97], v[154:157], v[202:205], v[94:97]
	v_mfma_i32_16x16x64_i8 v[90:93], v[162:165], v[202:205], v[90:93]
	v_mfma_i32_16x16x64_i8 v[78:81], v[154:157], v[210:213], v[78:81]
	v_mfma_i32_16x16x64_i8 v[74:77], v[162:165], v[210:213], v[74:77]
	s_setprio 0
	s_setprio 1
	v_mfma_i32_16x16x64_i8 v[118:121], v[166:169], v[182:185], v[118:121]
	v_mfma_i32_16x16x64_i8 v[114:117], v[174:177], v[182:185], v[114:117]
	v_mfma_i32_16x16x64_i8 v[102:105], v[166:169], v[190:193], v[102:105]
	v_mfma_i32_16x16x64_i8 v[98:101], v[174:177], v[190:193], v[98:101]
	v_mfma_i32_16x16x64_i8 v[86:89], v[166:169], v[198:201], v[86:89]
	v_mfma_i32_16x16x64_i8 v[82:85], v[174:177], v[198:201], v[82:85]
	v_mfma_i32_16x16x64_i8 v[70:73], v[166:169], v[206:209], v[70:73]
	v_mfma_i32_16x16x64_i8 v[66:69], v[174:177], v[206:209], v[66:69]
	v_mfma_i32_16x16x64_i8 v[118:121], v[170:173], v[186:189], v[118:121]
	v_mfma_i32_16x16x64_i8 v[114:117], v[178:181], v[186:189], v[114:117]
	v_mfma_i32_16x16x64_i8 v[102:105], v[170:173], v[194:197], v[102:105]
	v_mfma_i32_16x16x64_i8 v[98:101], v[178:181], v[194:197], v[98:101]
	v_mfma_i32_16x16x64_i8 v[86:89], v[170:173], v[202:205], v[86:89]
	v_mfma_i32_16x16x64_i8 v[82:85], v[178:181], v[202:205], v[82:85]
	v_mfma_i32_16x16x64_i8 v[70:73], v[170:173], v[210:213], v[70:73]
	v_mfma_i32_16x16x64_i8 v[66:69], v[178:181], v[210:213], v[66:69]
	s_setprio 0
	s_barrier
	ds_read_b128 v[182:185], v148 offset:49152
	ds_read_b128 v[186:189], v148 offset:50176
	ds_read_b128 v[190:193], v148 offset:51200
	ds_read_b128 v[194:197], v148 offset:52224
	ds_read_b128 v[198:201], v148 offset:53248
	ds_read_b128 v[202:205], v148 offset:54272
	ds_read_b128 v[206:209], v148 offset:55296
	ds_read_b128 v[210:213], v148 offset:56320
	s_add_i32 s84, s86, s40
	s_add_u32 s100, s50, s38
	s_addc_u32 s101, s51, s39
	s_mov_b32 m0, s84
	s_nop 0
	global_load_lds_dwordx4 v143, s[100:101]
	s_add_i32 m0, s84, 0x2000
	s_nop 0
	s_add_u32 s50, s50, 0x20080
	s_addc_u32 s51, s51, 0
	s_add_i32 s84, s87, s40
	global_load_lds_dwordx4 v144, s[100:101]
	s_mov_b32 m0, s84
	s_nop 0
	global_load_lds_dwordx4 v143, s[50:51]
	s_add_i32 m0, s84, 0x2000
	s_nop 0
	global_load_lds_dwordx4 v144, s[50:51]
	s_mov_b32 m0, s75
	s_add_u32 s100, s46, s38
	s_addc_u32 s101, s47, s39
	v_mov_b32_e32 v0, v133
	global_load_lds_dwordx4 v132, s[100:101]
	s_mov_b32 m0, s78
	s_nop 0
	global_load_lds_dwordx4 v133, s[100:101]
	s_waitcnt vmcnt(8)
	s_waitcnt lgkmcnt(0)
	s_setprio 1
	s_barrier
	v_mfma_i32_16x16x64_i8 v[62:65], v[150:153], v[182:185], v[62:65]
	v_mfma_i32_16x16x64_i8 v[58:61], v[158:161], v[182:185], v[58:61]
	v_mfma_i32_16x16x64_i8 v[46:49], v[150:153], v[190:193], v[46:49]
	v_mfma_i32_16x16x64_i8 v[42:45], v[158:161], v[190:193], v[42:45]
	v_mfma_i32_16x16x64_i8 v[30:33], v[150:153], v[198:201], v[30:33]
	v_mfma_i32_16x16x64_i8 v[26:29], v[158:161], v[198:201], v[26:29]
	v_mfma_i32_16x16x64_i8 v[14:17], v[150:153], v[206:209], v[14:17]
	v_mfma_i32_16x16x64_i8 v[10:13], v[158:161], v[206:209], v[10:13]
	v_mfma_i32_16x16x64_i8 v[62:65], v[154:157], v[186:189], v[62:65]
	v_mfma_i32_16x16x64_i8 v[58:61], v[162:165], v[186:189], v[58:61]
	v_mfma_i32_16x16x64_i8 v[46:49], v[154:157], v[194:197], v[46:49]
	v_mfma_i32_16x16x64_i8 v[42:45], v[162:165], v[194:197], v[42:45]
	v_mfma_i32_16x16x64_i8 v[30:33], v[154:157], v[202:205], v[30:33]
	v_mfma_i32_16x16x64_i8 v[26:29], v[162:165], v[202:205], v[26:29]
	v_mfma_i32_16x16x64_i8 v[14:17], v[154:157], v[210:213], v[14:17]
	v_mfma_i32_16x16x64_i8 v[10:13], v[162:165], v[210:213], v[10:13]
	s_setprio 0
	s_setprio 1
	v_mfma_i32_16x16x64_i8 v[54:57], v[166:169], v[182:185], v[54:57]
	v_mfma_i32_16x16x64_i8 v[50:53], v[174:177], v[182:185], v[50:53]
	v_mfma_i32_16x16x64_i8 v[38:41], v[166:169], v[190:193], v[38:41]
	v_mfma_i32_16x16x64_i8 v[34:37], v[174:177], v[190:193], v[34:37]
	v_mfma_i32_16x16x64_i8 v[22:25], v[166:169], v[198:201], v[22:25]
	v_mfma_i32_16x16x64_i8 v[18:21], v[174:177], v[198:201], v[18:21]
	v_mfma_i32_16x16x64_i8 v[6:9], v[166:169], v[206:209], v[6:9]
	v_mfma_i32_16x16x64_i8 v[2:5], v[174:177], v[206:209], v[2:5]
	v_mfma_i32_16x16x64_i8 v[54:57], v[170:173], v[186:189], v[54:57]
	v_mfma_i32_16x16x64_i8 v[50:53], v[178:181], v[186:189], v[50:53]
	v_mfma_i32_16x16x64_i8 v[38:41], v[170:173], v[194:197], v[38:41]
	v_mfma_i32_16x16x64_i8 v[34:37], v[178:181], v[194:197], v[34:37]
	v_mfma_i32_16x16x64_i8 v[22:25], v[170:173], v[202:205], v[22:25]
	v_mfma_i32_16x16x64_i8 v[18:21], v[178:181], v[202:205], v[18:21]
	v_mfma_i32_16x16x64_i8 v[6:9], v[170:173], v[210:213], v[6:9]
	v_mfma_i32_16x16x64_i8 v[2:5], v[178:181], v[210:213], v[2:5]
	s_setprio 0
	s_barrier
	s_add_i32 s65, s65, 2
	s_add_u32 s48, s48, 0x100
	s_addc_u32 s49, s49, 0
	s_add_u32 s25, s25, 0x100
	s_addc_u32 s64, s64, 0
	s_cmp_gt_u32 s65, 5
	s_cbranch_scc0 .LBB0_445
	s_branch .Lpeel_exit_445
.LBB0_445:
	s_add_u32 s46, s48, 0xfffe0080
	s_addc_u32 s47, s49, -1
	s_add_i32 s84, 0, 0x10000
	s_cmp_eq_u32 s65, 4
	s_cselect_b32 s47, s15, s47
	s_cselect_b32 s46, s14, s46
	v_add_u32_e32 v0, s84, v147
	s_cselect_b32 s51, s17, s64
	s_cselect_b32 s50, s16, s25
	s_add_i32 s86, 0, 0x14000
	ds_read_b128 v[150:153], v0
	ds_read_b128 v[154:157], v0 offset:1024
	ds_read_b128 v[158:161], v0 offset:2048
	ds_read_b128 v[162:165], v0 offset:3072
	ds_read_b128 v[166:169], v0 offset:16384
	ds_read_b128 v[170:173], v0 offset:17408
	ds_read_b128 v[174:177], v0 offset:18432
	ds_read_b128 v[178:181], v0 offset:19456
	ds_read_b128 v[182:185], v148
	ds_read_b128 v[186:189], v148 offset:1024
	ds_read_b128 v[190:193], v148 offset:2048
	ds_read_b128 v[194:197], v148 offset:3072
	ds_read_b128 v[198:201], v148 offset:4096
	ds_read_b128 v[202:205], v148 offset:5120
	ds_read_b128 v[206:209], v148 offset:6144
	ds_read_b128 v[210:213], v148 offset:7168
	s_add_i32 m0, s59, 0xc000
	s_nop 0
	global_load_lds_dwordx4 v132, s[48:49]
	s_add_i32 m0, s59, 0xe000
	s_nop 0
	global_load_lds_dwordx4 v133, s[48:49]
	s_waitcnt vmcnt(8)
	s_waitcnt lgkmcnt(0)
	s_setprio 1
	s_barrier
	v_mfma_i32_16x16x64_i8 v[126:129], v[150:153], v[182:185], v[126:129]
	v_mfma_i32_16x16x64_i8 v[122:125], v[158:161], v[182:185], v[122:125]
	v_mfma_i32_16x16x64_i8 v[110:113], v[150:153], v[190:193], v[110:113]
	v_mfma_i32_16x16x64_i8 v[106:109], v[158:161], v[190:193], v[106:109]
	v_mfma_i32_16x16x64_i8 v[94:97], v[150:153], v[198:201], v[94:97]
	v_mfma_i32_16x16x64_i8 v[90:93], v[158:161], v[198:201], v[90:93]
	v_mfma_i32_16x16x64_i8 v[78:81], v[150:153], v[206:209], v[78:81]
	v_mfma_i32_16x16x64_i8 v[74:77], v[158:161], v[206:209], v[74:77]
	v_mfma_i32_16x16x64_i8 v[126:129], v[154:157], v[186:189], v[126:129]
	v_mfma_i32_16x16x64_i8 v[122:125], v[162:165], v[186:189], v[122:125]
	v_mfma_i32_16x16x64_i8 v[110:113], v[154:157], v[194:197], v[110:113]
	v_mfma_i32_16x16x64_i8 v[106:109], v[162:165], v[194:197], v[106:109]
	v_mfma_i32_16x16x64_i8 v[94:97], v[154:157], v[202:205], v[94:97]
	v_mfma_i32_16x16x64_i8 v[90:93], v[162:165], v[202:205], v[90:93]
	v_mfma_i32_16x16x64_i8 v[78:81], v[154:157], v[210:213], v[78:81]
	v_mfma_i32_16x16x64_i8 v[74:77], v[162:165], v[210:213], v[74:77]
	s_setprio 0
	s_setprio 1
	v_mfma_i32_16x16x64_i8 v[118:121], v[166:169], v[182:185], v[118:121]
	v_mfma_i32_16x16x64_i8 v[114:117], v[174:177], v[182:185], v[114:117]
	v_mfma_i32_16x16x64_i8 v[102:105], v[166:169], v[190:193], v[102:105]
	v_mfma_i32_16x16x64_i8 v[98:101], v[174:177], v[190:193], v[98:101]
	v_mfma_i32_16x16x64_i8 v[86:89], v[166:169], v[198:201], v[86:89]
	v_mfma_i32_16x16x64_i8 v[82:85], v[174:177], v[198:201], v[82:85]
	v_mfma_i32_16x16x64_i8 v[70:73], v[166:169], v[206:209], v[70:73]
	v_mfma_i32_16x16x64_i8 v[66:69], v[174:177], v[206:209], v[66:69]
	v_mfma_i32_16x16x64_i8 v[118:121], v[170:173], v[186:189], v[118:121]
	v_mfma_i32_16x16x64_i8 v[114:117], v[178:181], v[186:189], v[114:117]
	v_mfma_i32_16x16x64_i8 v[102:105], v[170:173], v[194:197], v[102:105]
	v_mfma_i32_16x16x64_i8 v[98:101], v[178:181], v[194:197], v[98:101]
	v_mfma_i32_16x16x64_i8 v[86:89], v[170:173], v[202:205], v[86:89]
	v_mfma_i32_16x16x64_i8 v[82:85], v[178:181], v[202:205], v[82:85]
	v_mfma_i32_16x16x64_i8 v[70:73], v[170:173], v[210:213], v[70:73]
	v_mfma_i32_16x16x64_i8 v[66:69], v[178:181], v[210:213], v[66:69]
	s_setprio 0
	s_barrier
	s_add_i32 s84, s84, s40
	ds_read_b128 v[182:185], v148 offset:16384
	ds_read_b128 v[186:189], v148 offset:17408
	ds_read_b128 v[190:193], v148 offset:18432
	ds_read_b128 v[194:197], v148 offset:19456
	ds_read_b128 v[198:201], v148 offset:20480
	ds_read_b128 v[202:205], v148 offset:21504
	ds_read_b128 v[206:209], v148 offset:22528
	ds_read_b128 v[210:213], v148 offset:23552
	s_mov_b32 m0, s84
	s_nop 0
	global_load_lds_dwordx4 v143, s[50:51]
	s_add_i32 m0, s84, 0x2000
	s_add_u32 s84, s50, 0x20000
	global_load_lds_dwordx4 v144, s[50:51]
	s_addc_u32 s85, s51, 0
	s_add_i32 s86, s86, s40
	s_mov_b32 m0, s86
	s_nop 0
	global_load_lds_dwordx4 v143, s[84:85]
	s_add_i32 m0, s86, 0x2000
	s_nop 0
	global_load_lds_dwordx4 v144, s[84:85]
	s_mov_b32 m0, s59
	s_nop 0
	global_load_lds_dwordx4 v132, s[46:47]
	s_mov_b32 m0, s60
	s_nop 0
	global_load_lds_dwordx4 v133, s[46:47]
	s_waitcnt vmcnt(8)
	s_waitcnt lgkmcnt(0)
	s_setprio 1
	s_barrier
	v_mfma_i32_16x16x64_i8 v[62:65], v[150:153], v[182:185], v[62:65]
	v_mfma_i32_16x16x64_i8 v[58:61], v[158:161], v[182:185], v[58:61]
	v_mfma_i32_16x16x64_i8 v[46:49], v[150:153], v[190:193], v[46:49]
	v_mfma_i32_16x16x64_i8 v[42:45], v[158:161], v[190:193], v[42:45]
	v_mfma_i32_16x16x64_i8 v[30:33], v[150:153], v[198:201], v[30:33]
	v_mfma_i32_16x16x64_i8 v[26:29], v[158:161], v[198:201], v[26:29]
	v_mfma_i32_16x16x64_i8 v[14:17], v[150:153], v[206:209], v[14:17]
	v_mfma_i32_16x16x64_i8 v[10:13], v[158:161], v[206:209], v[10:13]
	v_mfma_i32_16x16x64_i8 v[62:65], v[154:157], v[186:189], v[62:65]
	v_mfma_i32_16x16x64_i8 v[58:61], v[162:165], v[186:189], v[58:61]
	v_mfma_i32_16x16x64_i8 v[46:49], v[154:157], v[194:197], v[46:49]
	v_mfma_i32_16x16x64_i8 v[42:45], v[162:165], v[194:197], v[42:45]
	v_mfma_i32_16x16x64_i8 v[30:33], v[154:157], v[202:205], v[30:33]
	v_mfma_i32_16x16x64_i8 v[26:29], v[162:165], v[202:205], v[26:29]
	v_mfma_i32_16x16x64_i8 v[14:17], v[154:157], v[210:213], v[14:17]
	v_mfma_i32_16x16x64_i8 v[10:13], v[162:165], v[210:213], v[10:13]
	s_setprio 0
	s_setprio 1
	v_mfma_i32_16x16x64_i8 v[54:57], v[166:169], v[182:185], v[54:57]
	v_mfma_i32_16x16x64_i8 v[50:53], v[174:177], v[182:185], v[50:53]
	v_mfma_i32_16x16x64_i8 v[38:41], v[166:169], v[190:193], v[38:41]
	v_mfma_i32_16x16x64_i8 v[34:37], v[174:177], v[190:193], v[34:37]
	v_mfma_i32_16x16x64_i8 v[22:25], v[166:169], v[198:201], v[22:25]
	v_mfma_i32_16x16x64_i8 v[18:21], v[174:177], v[198:201], v[18:21]
	v_mfma_i32_16x16x64_i8 v[6:9], v[166:169], v[206:209], v[6:9]
	v_mfma_i32_16x16x64_i8 v[2:5], v[174:177], v[206:209], v[2:5]
	v_mfma_i32_16x16x64_i8 v[54:57], v[170:173], v[186:189], v[54:57]
	v_mfma_i32_16x16x64_i8 v[50:53], v[178:181], v[186:189], v[50:53]
	v_mfma_i32_16x16x64_i8 v[38:41], v[170:173], v[194:197], v[38:41]
	v_mfma_i32_16x16x64_i8 v[34:37], v[178:181], v[194:197], v[34:37]
	v_mfma_i32_16x16x64_i8 v[22:25], v[170:173], v[202:205], v[22:25]
	v_mfma_i32_16x16x64_i8 v[18:21], v[178:181], v[202:205], v[18:21]
	v_mfma_i32_16x16x64_i8 v[6:9], v[170:173], v[210:213], v[6:9]
	v_mfma_i32_16x16x64_i8 v[2:5], v[178:181], v[210:213], v[2:5]
	s_setprio 0
	s_barrier
	s_add_i32 s86, 0, 0x18000
	s_add_i32 s87, 0, 0x1c000
	ds_read_b128 v[150:153], v0 offset:32768
	ds_read_b128 v[154:157], v0 offset:33792
	ds_read_b128 v[158:161], v0 offset:34816
	ds_read_b128 v[162:165], v0 offset:35840
	ds_read_b128 v[166:169], v0 offset:49152
	ds_read_b128 v[170:173], v0 offset:50176
	ds_read_b128 v[174:177], v0 offset:51200
	ds_read_b128 v[178:181], v0 offset:52224
	s_add_u32 s84, s46, 0x20000
	s_mov_b32 m0, s61
	ds_read_b128 v[182:185], v148 offset:32768
	ds_read_b128 v[186:189], v148 offset:33792
	ds_read_b128 v[190:193], v148 offset:34816
	ds_read_b128 v[194:197], v148 offset:35840
	ds_read_b128 v[198:201], v148 offset:36864
	ds_read_b128 v[202:205], v148 offset:37888
	ds_read_b128 v[206:209], v148 offset:38912
	ds_read_b128 v[210:213], v148 offset:39936
	s_addc_u32 s85, s47, 0
	s_nop 0
	global_load_lds_dwordx4 v132, s[84:85]
	s_mov_b32 m0, s66
	s_nop 0
	global_load_lds_dwordx4 v133, s[84:85]
	s_waitcnt vmcnt(8)
	s_waitcnt lgkmcnt(0)
	s_setprio 1
	s_barrier
	v_mfma_i32_16x16x64_i8 v[126:129], v[150:153], v[182:185], v[126:129]
	v_mfma_i32_16x16x64_i8 v[122:125], v[158:161], v[182:185], v[122:125]
	v_mfma_i32_16x16x64_i8 v[110:113], v[150:153], v[190:193], v[110:113]
	v_mfma_i32_16x16x64_i8 v[106:109], v[158:161], v[190:193], v[106:109]
	v_mfma_i32_16x16x64_i8 v[94:97], v[150:153], v[198:201], v[94:97]
	v_mfma_i32_16x16x64_i8 v[90:93], v[158:161], v[198:201], v[90:93]
	v_mfma_i32_16x16x64_i8 v[78:81], v[150:153], v[206:209], v[78:81]
	v_mfma_i32_16x16x64_i8 v[74:77], v[158:161], v[206:209], v[74:77]
	v_mfma_i32_16x16x64_i8 v[126:129], v[154:157], v[186:189], v[126:129]
	v_mfma_i32_16x16x64_i8 v[122:125], v[162:165], v[186:189], v[122:125]
	v_mfma_i32_16x16x64_i8 v[110:113], v[154:157], v[194:197], v[110:113]
	v_mfma_i32_16x16x64_i8 v[106:109], v[162:165], v[194:197], v[106:109]
	v_mfma_i32_16x16x64_i8 v[94:97], v[154:157], v[202:205], v[94:97]
	v_mfma_i32_16x16x64_i8 v[90:93], v[162:165], v[202:205], v[90:93]
	v_mfma_i32_16x16x64_i8 v[78:81], v[154:157], v[210:213], v[78:81]
	v_mfma_i32_16x16x64_i8 v[74:77], v[162:165], v[210:213], v[74:77]
	s_setprio 0
	s_setprio 1
	v_mfma_i32_16x16x64_i8 v[118:121], v[166:169], v[182:185], v[118:121]
	v_mfma_i32_16x16x64_i8 v[114:117], v[174:177], v[182:185], v[114:117]
	v_mfma_i32_16x16x64_i8 v[102:105], v[166:169], v[190:193], v[102:105]
	v_mfma_i32_16x16x64_i8 v[98:101], v[174:177], v[190:193], v[98:101]
	v_mfma_i32_16x16x64_i8 v[86:89], v[166:169], v[198:201], v[86:89]
	v_mfma_i32_16x16x64_i8 v[82:85], v[174:177], v[198:201], v[82:85]
	v_mfma_i32_16x16x64_i8 v[70:73], v[166:169], v[206:209], v[70:73]
	v_mfma_i32_16x16x64_i8 v[66:69], v[174:177], v[206:209], v[66:69]
	v_mfma_i32_16x16x64_i8 v[118:121], v[170:173], v[186:189], v[118:121]
	v_mfma_i32_16x16x64_i8 v[114:117], v[178:181], v[186:189], v[114:117]
	v_mfma_i32_16x16x64_i8 v[102:105], v[170:173], v[194:197], v[102:105]
	v_mfma_i32_16x16x64_i8 v[98:101], v[178:181], v[194:197], v[98:101]
	v_mfma_i32_16x16x64_i8 v[86:89], v[170:173], v[202:205], v[86:89]
	v_mfma_i32_16x16x64_i8 v[82:85], v[178:181], v[202:205], v[82:85]
	v_mfma_i32_16x16x64_i8 v[70:73], v[170:173], v[210:213], v[70:73]
	v_mfma_i32_16x16x64_i8 v[66:69], v[178:181], v[210:213], v[66:69]
	s_setprio 0
	s_barrier
	ds_read_b128 v[182:185], v148 offset:49152
	ds_read_b128 v[186:189], v148 offset:50176
	ds_read_b128 v[190:193], v148 offset:51200
	ds_read_b128 v[194:197], v148 offset:52224
	ds_read_b128 v[198:201], v148 offset:53248
	ds_read_b128 v[202:205], v148 offset:54272
	ds_read_b128 v[206:209], v148 offset:55296
	ds_read_b128 v[210:213], v148 offset:56320
	s_add_i32 s84, s86, s40
	s_add_u32 s100, s50, s38
	s_addc_u32 s101, s51, s39
	s_mov_b32 m0, s84
	s_nop 0
	global_load_lds_dwordx4 v143, s[100:101]
	s_add_i32 m0, s84, 0x2000
	s_nop 0
	s_add_u32 s50, s50, 0x20080
	s_addc_u32 s51, s51, 0
	s_add_i32 s84, s87, s40
	global_load_lds_dwordx4 v144, s[100:101]
	s_mov_b32 m0, s84
	s_nop 0
	global_load_lds_dwordx4 v143, s[50:51]
	s_add_i32 m0, s84, 0x2000
	s_nop 0
	global_load_lds_dwordx4 v144, s[50:51]
	s_mov_b32 m0, s75
	s_add_u32 s100, s46, s38
	s_addc_u32 s101, s47, s39
	v_mov_b32_e32 v0, v133
	global_load_lds_dwordx4 v132, s[100:101]
	s_mov_b32 m0, s78
	s_nop 0
	global_load_lds_dwordx4 v133, s[100:101]
	s_waitcnt vmcnt(8)
	s_waitcnt lgkmcnt(0)
	s_setprio 1
	s_barrier
	v_mfma_i32_16x16x64_i8 v[62:65], v[150:153], v[182:185], v[62:65]
	v_mfma_i32_16x16x64_i8 v[58:61], v[158:161], v[182:185], v[58:61]
	v_mfma_i32_16x16x64_i8 v[46:49], v[150:153], v[190:193], v[46:49]
	v_mfma_i32_16x16x64_i8 v[42:45], v[158:161], v[190:193], v[42:45]
	v_mfma_i32_16x16x64_i8 v[30:33], v[150:153], v[198:201], v[30:33]
	v_mfma_i32_16x16x64_i8 v[26:29], v[158:161], v[198:201], v[26:29]
	v_mfma_i32_16x16x64_i8 v[14:17], v[150:153], v[206:209], v[14:17]
	v_mfma_i32_16x16x64_i8 v[10:13], v[158:161], v[206:209], v[10:13]
	v_mfma_i32_16x16x64_i8 v[62:65], v[154:157], v[186:189], v[62:65]
	v_mfma_i32_16x16x64_i8 v[58:61], v[162:165], v[186:189], v[58:61]
	v_mfma_i32_16x16x64_i8 v[46:49], v[154:157], v[194:197], v[46:49]
	v_mfma_i32_16x16x64_i8 v[42:45], v[162:165], v[194:197], v[42:45]
	v_mfma_i32_16x16x64_i8 v[30:33], v[154:157], v[202:205], v[30:33]
	v_mfma_i32_16x16x64_i8 v[26:29], v[162:165], v[202:205], v[26:29]
	v_mfma_i32_16x16x64_i8 v[14:17], v[154:157], v[210:213], v[14:17]
	v_mfma_i32_16x16x64_i8 v[10:13], v[162:165], v[210:213], v[10:13]
	s_setprio 0
	s_setprio 1
	v_mfma_i32_16x16x64_i8 v[54:57], v[166:169], v[182:185], v[54:57]
	v_mfma_i32_16x16x64_i8 v[50:53], v[174:177], v[182:185], v[50:53]
	v_mfma_i32_16x16x64_i8 v[38:41], v[166:169], v[190:193], v[38:41]
	v_mfma_i32_16x16x64_i8 v[34:37], v[174:177], v[190:193], v[34:37]
	v_mfma_i32_16x16x64_i8 v[22:25], v[166:169], v[198:201], v[22:25]
	v_mfma_i32_16x16x64_i8 v[18:21], v[174:177], v[198:201], v[18:21]
	v_mfma_i32_16x16x64_i8 v[6:9], v[166:169], v[206:209], v[6:9]
	v_mfma_i32_16x16x64_i8 v[2:5], v[174:177], v[206:209], v[2:5]
	v_mfma_i32_16x16x64_i8 v[54:57], v[170:173], v[186:189], v[54:57]
	v_mfma_i32_16x16x64_i8 v[50:53], v[178:181], v[186:189], v[50:53]
	v_mfma_i32_16x16x64_i8 v[38:41], v[170:173], v[194:197], v[38:41]
	v_mfma_i32_16x16x64_i8 v[34:37], v[178:181], v[194:197], v[34:37]
	v_mfma_i32_16x16x64_i8 v[22:25], v[170:173], v[202:205], v[22:25]
	v_mfma_i32_16x16x64_i8 v[18:21], v[178:181], v[202:205], v[18:21]
	v_mfma_i32_16x16x64_i8 v[6:9], v[170:173], v[210:213], v[6:9]
	v_mfma_i32_16x16x64_i8 v[2:5], v[178:181], v[210:213], v[2:5]
	s_setprio 0
	s_barrier
	s_add_i32 s65, s65, 2
	s_add_u32 s48, s48, 0x100
	s_addc_u32 s49, s49, 0
	s_add_u32 s25, s25, 0x100
	s_addc_u32 s64, s64, 0
	s_cmp_gt_u32 s65, 5
	s_cbranch_scc0 .LBB0_445

.LBB0_626:
	s_add_u32 s58, s14, s50
	s_addc_u32 s59, s15, s51
	s_add_u32 s46, s58, 0x100
	s_addc_u32 s47, s59, 0
	s_and_b64 s[4:5], s[48:49], exec
	s_cselect_b32 s47, s15, s47
	s_cselect_b32 s46, s14, s46
	s_add_u32 s4, s16, s50
	s_addc_u32 s5, s17, s51
	s_add_u32 s50, s4, 0x100
	s_addc_u32 s51, s5, 0
	s_add_i32 s78, 0, 0x10000
	s_and_b64 s[4:5], s[48:49], exec
	s_cselect_b32 s49, s17, s51
	s_cselect_b32 s48, s16, s50
	s_add_i32 s4, 0, 0x14000
	s_add_u32 s96, s58, 0x80080
	s_addc_u32 s97, s59, 0
	s_add_i32 s82, s78, s42
	s_add_i32 m0, s43, 0xc000
	s_add_i32 s5, s43, 0xe000
	s_add_i32 s76, s82, 0x2000
	v_add_u32_e32 v0, s78, v136
	s_add_u32 s94, s48, 0x40000
	ds_read_b128 v[138:141], v0
	ds_read_b128 v[142:145], v0 offset:1024
	ds_read_b128 v[146:149], v0 offset:2048
	ds_read_b128 v[150:153], v0 offset:3072
	s_addc_u32 s95, s49, 0
	s_add_i32 s77, s4, s42
	ds_read_b128 v[154:157], v0 offset:16384
	ds_read_b128 v[158:161], v0 offset:17408
	ds_read_b128 v[162:165], v0 offset:18432
	ds_read_b128 v[166:169], v0 offset:19456
	s_add_i32 s75, s77, 0x2000
	s_add_i32 s74, 0, 0x18000
	s_add_i32 s71, 0, 0x1c000
	s_add_u32 s58, s46, 0x80000
	s_addc_u32 s59, s47, 0
	s_add_i32 s70, s74, s42
	s_add_i32 s69, s70, 0x2000
	s_add_u32 s50, s48, 0x40080
	s_addc_u32 s51, s49, 0
	s_add_i32 s79, s71, s42
	s_add_i32 s78, s79, 0x2000
	ds_read_b128 v[170:173], v137
	ds_read_b128 v[174:177], v137 offset:1024
	ds_read_b128 v[178:181], v137 offset:2048
	ds_read_b128 v[182:185], v137 offset:3072
	ds_read_b128 v[186:189], v137 offset:4096
	ds_read_b128 v[190:193], v137 offset:5120
	ds_read_b128 v[194:197], v137 offset:6144
	ds_read_b128 v[198:201], v137 offset:7168
	s_nop 0
	global_load_lds_dwordx4 v130, s[96:97]
	s_mov_b32 m0, s5
	s_nop 0
	global_load_lds_dwordx4 v132, s[96:97]
	s_waitcnt vmcnt(8)
	s_waitcnt lgkmcnt(0)
	s_setprio 1
	s_barrier
	v_mfma_f32_16x16x32_bf16 v[126:129], v[138:141], v[170:173], v[126:129]
	v_mfma_f32_16x16x32_bf16 v[122:125], v[146:149], v[170:173], v[122:125]
	v_mfma_f32_16x16x32_bf16 v[118:121], v[138:141], v[178:181], v[118:121]
	v_mfma_f32_16x16x32_bf16 v[110:113], v[146:149], v[178:181], v[110:113]
	v_mfma_f32_16x16x32_bf16 v[102:105], v[138:141], v[186:189], v[102:105]
	v_mfma_f32_16x16x32_bf16 v[94:97], v[146:149], v[186:189], v[94:97]
	v_mfma_f32_16x16x32_bf16 v[86:89], v[138:141], v[194:197], v[86:89]
	v_mfma_f32_16x16x32_bf16 v[78:81], v[146:149], v[194:197], v[78:81]
	v_mfma_f32_16x16x32_bf16 v[126:129], v[142:145], v[174:177], v[126:129]
	v_mfma_f32_16x16x32_bf16 v[122:125], v[150:153], v[174:177], v[122:125]
	v_mfma_f32_16x16x32_bf16 v[118:121], v[142:145], v[182:185], v[118:121]
	v_mfma_f32_16x16x32_bf16 v[110:113], v[150:153], v[182:185], v[110:113]
	v_mfma_f32_16x16x32_bf16 v[102:105], v[142:145], v[190:193], v[102:105]
	v_mfma_f32_16x16x32_bf16 v[94:97], v[150:153], v[190:193], v[94:97]
	v_mfma_f32_16x16x32_bf16 v[86:89], v[142:145], v[198:201], v[86:89]
	v_mfma_f32_16x16x32_bf16 v[78:81], v[150:153], v[198:201], v[78:81]
	s_setprio 0
	s_setprio 1
	v_mfma_f32_16x16x32_bf16 v[114:117], v[154:157], v[170:173], v[114:117]
	v_mfma_f32_16x16x32_bf16 v[106:109], v[162:165], v[170:173], v[106:109]
	v_mfma_f32_16x16x32_bf16 v[98:101], v[154:157], v[178:181], v[98:101]
	v_mfma_f32_16x16x32_bf16 v[90:93], v[162:165], v[178:181], v[90:93]
	v_mfma_f32_16x16x32_bf16 v[82:85], v[154:157], v[186:189], v[82:85]
	v_mfma_f32_16x16x32_bf16 v[74:77], v[162:165], v[186:189], v[74:77]
	v_mfma_f32_16x16x32_bf16 v[70:73], v[154:157], v[194:197], v[70:73]
	v_mfma_f32_16x16x32_bf16 v[62:65], v[162:165], v[194:197], v[62:65]
	v_mfma_f32_16x16x32_bf16 v[114:117], v[158:161], v[174:177], v[114:117]
	v_mfma_f32_16x16x32_bf16 v[106:109], v[166:169], v[174:177], v[106:109]
	v_mfma_f32_16x16x32_bf16 v[98:101], v[158:161], v[182:185], v[98:101]
	v_mfma_f32_16x16x32_bf16 v[90:93], v[166:169], v[182:185], v[90:93]
	v_mfma_f32_16x16x32_bf16 v[82:85], v[158:161], v[190:193], v[82:85]
	v_mfma_f32_16x16x32_bf16 v[74:77], v[166:169], v[190:193], v[74:77]
	v_mfma_f32_16x16x32_bf16 v[70:73], v[158:161], v[198:201], v[70:73]
	v_mfma_f32_16x16x32_bf16 v[62:65], v[166:169], v[198:201], v[62:65]
	s_setprio 0
	s_barrier
	s_mov_b32 m0, s82
	ds_read_b128 v[170:173], v137 offset:16384
	ds_read_b128 v[174:177], v137 offset:17408
	ds_read_b128 v[178:181], v137 offset:18432
	ds_read_b128 v[182:185], v137 offset:19456
	ds_read_b128 v[186:189], v137 offset:20480
	ds_read_b128 v[190:193], v137 offset:21504
	ds_read_b128 v[194:197], v137 offset:22528
	ds_read_b128 v[198:201], v137 offset:23552
	s_nop 0
	global_load_lds_dwordx4 v131, s[48:49]
	s_mov_b32 m0, s76
	s_nop 0
	global_load_lds_dwordx4 v133, s[48:49]
	s_mov_b32 m0, s77
	s_nop 0
	global_load_lds_dwordx4 v131, s[94:95]
	s_mov_b32 m0, s75
	s_nop 0
	global_load_lds_dwordx4 v133, s[94:95]
	s_mov_b32 m0, s43
	s_nop 0
	global_load_lds_dwordx4 v130, s[46:47]
	s_mov_b32 m0, s60
	s_nop 0
	global_load_lds_dwordx4 v132, s[46:47]
	s_waitcnt vmcnt(8)
	s_waitcnt lgkmcnt(0)
	s_setprio 1
	s_barrier
	v_mfma_f32_16x16x32_bf16 v[66:69], v[138:141], v[170:173], v[66:69]
	v_mfma_f32_16x16x32_bf16 v[58:61], v[146:149], v[170:173], v[58:61]
	v_mfma_f32_16x16x32_bf16 v[54:57], v[138:141], v[178:181], v[54:57]
	v_mfma_f32_16x16x32_bf16 v[46:49], v[146:149], v[178:181], v[46:49]
	v_mfma_f32_16x16x32_bf16 v[38:41], v[138:141], v[186:189], v[38:41]
	v_mfma_f32_16x16x32_bf16 v[30:33], v[146:149], v[186:189], v[30:33]
	v_mfma_f32_16x16x32_bf16 v[22:25], v[138:141], v[194:197], v[22:25]
	v_mfma_f32_16x16x32_bf16 v[14:17], v[146:149], v[194:197], v[14:17]
	v_mfma_f32_16x16x32_bf16 v[66:69], v[142:145], v[174:177], v[66:69]
	v_mfma_f32_16x16x32_bf16 v[58:61], v[150:153], v[174:177], v[58:61]
	v_mfma_f32_16x16x32_bf16 v[54:57], v[142:145], v[182:185], v[54:57]
	v_mfma_f32_16x16x32_bf16 v[46:49], v[150:153], v[182:185], v[46:49]
	v_mfma_f32_16x16x32_bf16 v[38:41], v[142:145], v[190:193], v[38:41]
	v_mfma_f32_16x16x32_bf16 v[30:33], v[150:153], v[190:193], v[30:33]
	v_mfma_f32_16x16x32_bf16 v[22:25], v[142:145], v[198:201], v[22:25]
	v_mfma_f32_16x16x32_bf16 v[14:17], v[150:153], v[198:201], v[14:17]
	s_setprio 0
	s_setprio 1
	v_mfma_f32_16x16x32_bf16 v[50:53], v[154:157], v[170:173], v[50:53]
	v_mfma_f32_16x16x32_bf16 v[42:45], v[162:165], v[170:173], v[42:45]
	v_mfma_f32_16x16x32_bf16 v[34:37], v[154:157], v[178:181], v[34:37]
	v_mfma_f32_16x16x32_bf16 v[26:29], v[162:165], v[178:181], v[26:29]
	v_mfma_f32_16x16x32_bf16 v[18:21], v[154:157], v[186:189], v[18:21]
	v_mfma_f32_16x16x32_bf16 v[10:13], v[162:165], v[186:189], v[10:13]
	v_mfma_f32_16x16x32_bf16 v[6:9], v[154:157], v[194:197], v[6:9]
	v_mfma_f32_16x16x32_bf16 v[2:5], v[162:165], v[194:197], v[2:5]
	v_mfma_f32_16x16x32_bf16 v[50:53], v[158:161], v[174:177], v[50:53]
	v_mfma_f32_16x16x32_bf16 v[42:45], v[166:169], v[174:177], v[42:45]
	v_mfma_f32_16x16x32_bf16 v[34:37], v[158:161], v[182:185], v[34:37]
	v_mfma_f32_16x16x32_bf16 v[26:29], v[166:169], v[182:185], v[26:29]
	v_mfma_f32_16x16x32_bf16 v[18:21], v[158:161], v[190:193], v[18:21]
	v_mfma_f32_16x16x32_bf16 v[10:13], v[166:169], v[190:193], v[10:13]
	v_mfma_f32_16x16x32_bf16 v[6:9], v[158:161], v[198:201], v[6:9]
	v_mfma_f32_16x16x32_bf16 v[2:5], v[166:169], v[198:201], v[2:5]
	s_setprio 0
	s_barrier
	ds_read_b128 v[138:141], v0 offset:32768
	ds_read_b128 v[142:145], v0 offset:33792
	ds_read_b128 v[146:149], v0 offset:34816
	ds_read_b128 v[150:153], v0 offset:35840
	ds_read_b128 v[154:157], v0 offset:49152
	ds_read_b128 v[158:161], v0 offset:50176
	ds_read_b128 v[162:165], v0 offset:51200
	ds_read_b128 v[166:169], v0 offset:52224
	s_mov_b32 m0, s65
	ds_read_b128 v[170:173], v137 offset:32768
	ds_read_b128 v[174:177], v137 offset:33792
	ds_read_b128 v[178:181], v137 offset:34816
	ds_read_b128 v[182:185], v137 offset:35840
	ds_read_b128 v[186:189], v137 offset:36864
	ds_read_b128 v[190:193], v137 offset:37888
	ds_read_b128 v[194:197], v137 offset:38912
	ds_read_b128 v[198:201], v137 offset:39936
	s_nop 0
	global_load_lds_dwordx4 v130, s[58:59]
	s_mov_b32 m0, s66
	s_nop 0
	global_load_lds_dwordx4 v132, s[58:59]
	s_waitcnt vmcnt(8)
	s_waitcnt lgkmcnt(0)
	s_setprio 1
	s_barrier
	v_mfma_f32_16x16x32_bf16 v[126:129], v[138:141], v[170:173], v[126:129]
	v_mfma_f32_16x16x32_bf16 v[122:125], v[146:149], v[170:173], v[122:125]
	v_mfma_f32_16x16x32_bf16 v[118:121], v[138:141], v[178:181], v[118:121]
	v_mfma_f32_16x16x32_bf16 v[110:113], v[146:149], v[178:181], v[110:113]
	v_mfma_f32_16x16x32_bf16 v[102:105], v[138:141], v[186:189], v[102:105]
	v_mfma_f32_16x16x32_bf16 v[94:97], v[146:149], v[186:189], v[94:97]
	v_mfma_f32_16x16x32_bf16 v[86:89], v[138:141], v[194:197], v[86:89]
	v_mfma_f32_16x16x32_bf16 v[78:81], v[146:149], v[194:197], v[78:81]
	v_mfma_f32_16x16x32_bf16 v[126:129], v[142:145], v[174:177], v[126:129]
	v_mfma_f32_16x16x32_bf16 v[122:125], v[150:153], v[174:177], v[122:125]
	v_mfma_f32_16x16x32_bf16 v[118:121], v[142:145], v[182:185], v[118:121]
	v_mfma_f32_16x16x32_bf16 v[110:113], v[150:153], v[182:185], v[110:113]
	v_mfma_f32_16x16x32_bf16 v[102:105], v[142:145], v[190:193], v[102:105]
	v_mfma_f32_16x16x32_bf16 v[94:97], v[150:153], v[190:193], v[94:97]
	v_mfma_f32_16x16x32_bf16 v[86:89], v[142:145], v[198:201], v[86:89]
	v_mfma_f32_16x16x32_bf16 v[78:81], v[150:153], v[198:201], v[78:81]
	s_setprio 0
	s_setprio 1
	v_mfma_f32_16x16x32_bf16 v[114:117], v[154:157], v[170:173], v[114:117]
	v_mfma_f32_16x16x32_bf16 v[106:109], v[162:165], v[170:173], v[106:109]
	v_mfma_f32_16x16x32_bf16 v[98:101], v[154:157], v[178:181], v[98:101]
	v_mfma_f32_16x16x32_bf16 v[90:93], v[162:165], v[178:181], v[90:93]
	v_mfma_f32_16x16x32_bf16 v[82:85], v[154:157], v[186:189], v[82:85]
	v_mfma_f32_16x16x32_bf16 v[74:77], v[162:165], v[186:189], v[74:77]
	v_mfma_f32_16x16x32_bf16 v[70:73], v[154:157], v[194:197], v[70:73]
	v_mfma_f32_16x16x32_bf16 v[62:65], v[162:165], v[194:197], v[62:65]
	v_mfma_f32_16x16x32_bf16 v[114:117], v[158:161], v[174:177], v[114:117]
	v_mfma_f32_16x16x32_bf16 v[106:109], v[166:169], v[174:177], v[106:109]
	v_mfma_f32_16x16x32_bf16 v[98:101], v[158:161], v[182:185], v[98:101]
	v_mfma_f32_16x16x32_bf16 v[90:93], v[166:169], v[182:185], v[90:93]
	v_mfma_f32_16x16x32_bf16 v[82:85], v[158:161], v[190:193], v[82:85]
	v_mfma_f32_16x16x32_bf16 v[74:77], v[166:169], v[190:193], v[74:77]
	v_mfma_f32_16x16x32_bf16 v[70:73], v[158:161], v[198:201], v[70:73]
	v_mfma_f32_16x16x32_bf16 v[62:65], v[166:169], v[198:201], v[62:65]
	s_setprio 0
	s_barrier
	ds_read_b128 v[170:173], v137 offset:49152
	ds_read_b128 v[174:177], v137 offset:50176
	ds_read_b128 v[178:181], v137 offset:51200
	ds_read_b128 v[182:185], v137 offset:52224
	ds_read_b128 v[186:189], v137 offset:53248
	ds_read_b128 v[190:193], v137 offset:54272
	ds_read_b128 v[194:197], v137 offset:55296
	ds_read_b128 v[198:201], v137 offset:56320
	s_mov_b32 m0, s70
	s_add_u32 s100, s48, s38
	s_addc_u32 s101, s49, s39
	global_load_lds_dwordx4 v131, s[100:101]
	s_mov_b32 m0, s69
	s_nop 0
	global_load_lds_dwordx4 v133, s[100:101]
	s_mov_b32 m0, s79
	s_nop 0
	global_load_lds_dwordx4 v131, s[50:51]
	s_mov_b32 m0, s78
	s_nop 0
	global_load_lds_dwordx4 v133, s[50:51]
	s_mov_b32 m0, s67
	s_add_u32 s100, s46, s38
	s_addc_u32 s101, s47, s39
	v_mov_b32_e32 v0, v132
	global_load_lds_dwordx4 v130, s[100:101]
	s_mov_b32 m0, s68
	s_nop 0
	global_load_lds_dwordx4 v132, s[100:101]
	s_waitcnt vmcnt(8)
	s_waitcnt lgkmcnt(0)
	s_setprio 1
	s_barrier
	v_mfma_f32_16x16x32_bf16 v[66:69], v[138:141], v[170:173], v[66:69]
	v_mfma_f32_16x16x32_bf16 v[58:61], v[146:149], v[170:173], v[58:61]
	v_mfma_f32_16x16x32_bf16 v[54:57], v[138:141], v[178:181], v[54:57]
	v_mfma_f32_16x16x32_bf16 v[46:49], v[146:149], v[178:181], v[46:49]
	v_mfma_f32_16x16x32_bf16 v[38:41], v[138:141], v[186:189], v[38:41]
	v_mfma_f32_16x16x32_bf16 v[30:33], v[146:149], v[186:189], v[30:33]
	v_mfma_f32_16x16x32_bf16 v[22:25], v[138:141], v[194:197], v[22:25]
	v_mfma_f32_16x16x32_bf16 v[14:17], v[146:149], v[194:197], v[14:17]
	v_mfma_f32_16x16x32_bf16 v[66:69], v[142:145], v[174:177], v[66:69]
	v_mfma_f32_16x16x32_bf16 v[58:61], v[150:153], v[174:177], v[58:61]
	v_mfma_f32_16x16x32_bf16 v[54:57], v[142:145], v[182:185], v[54:57]
	v_mfma_f32_16x16x32_bf16 v[46:49], v[150:153], v[182:185], v[46:49]
	v_mfma_f32_16x16x32_bf16 v[38:41], v[142:145], v[190:193], v[38:41]
	v_mfma_f32_16x16x32_bf16 v[30:33], v[150:153], v[190:193], v[30:33]
	v_mfma_f32_16x16x32_bf16 v[22:25], v[142:145], v[198:201], v[22:25]
	v_mfma_f32_16x16x32_bf16 v[14:17], v[150:153], v[198:201], v[14:17]
	s_setprio 0
	s_setprio 1
	v_mfma_f32_16x16x32_bf16 v[50:53], v[154:157], v[170:173], v[50:53]
	v_mfma_f32_16x16x32_bf16 v[42:45], v[162:165], v[170:173], v[42:45]
	v_mfma_f32_16x16x32_bf16 v[34:37], v[154:157], v[178:181], v[34:37]
	v_mfma_f32_16x16x32_bf16 v[26:29], v[162:165], v[178:181], v[26:29]
	v_mfma_f32_16x16x32_bf16 v[18:21], v[154:157], v[186:189], v[18:21]
	v_mfma_f32_16x16x32_bf16 v[10:13], v[162:165], v[186:189], v[10:13]
	v_mfma_f32_16x16x32_bf16 v[6:9], v[154:157], v[194:197], v[6:9]
	v_mfma_f32_16x16x32_bf16 v[2:5], v[162:165], v[194:197], v[2:5]
	v_mfma_f32_16x16x32_bf16 v[50:53], v[158:161], v[174:177], v[50:53]
	v_mfma_f32_16x16x32_bf16 v[42:45], v[166:169], v[174:177], v[42:45]
	v_mfma_f32_16x16x32_bf16 v[34:37], v[158:161], v[182:185], v[34:37]
	v_mfma_f32_16x16x32_bf16 v[26:29], v[166:169], v[182:185], v[26:29]
	v_mfma_f32_16x16x32_bf16 v[18:21], v[158:161], v[190:193], v[18:21]
	v_mfma_f32_16x16x32_bf16 v[10:13], v[166:169], v[190:193], v[10:13]
	v_mfma_f32_16x16x32_bf16 v[6:9], v[158:161], v[198:201], v[6:9]
	v_mfma_f32_16x16x32_bf16 v[2:5], v[166:169], v[198:201], v[2:5]
	s_setprio 0
	s_barrier
	s_andn2_b64 vcc, exec, s[22:23]
	s_mov_b64 s[48:49], -1
	s_mov_b64 s[22:23], 0
	s_mov_b64 s[50:51], 0x100
	s_cbranch_vccz .LBB0_626
	s_cmpk_lt_u32 s25, 0x100
	s_cbranch_scc0 .LBB0_629
	s_barrier

.LBB0_634:
	s_add_u32 s50, s2, s48
	s_addc_u32 s51, s3, s49
	s_add_u32 s22, s50, 0x100
	s_addc_u32 s23, s51, 0
	s_and_b64 s[4:5], s[46:47], exec
	s_cselect_b32 s23, s3, s23
	s_cselect_b32 s22, s2, s22
	s_add_u32 s4, s14, s48
	s_addc_u32 s5, s15, s49
	s_add_u32 s48, s4, 0x900
	s_addc_u32 s49, s5, 0
	s_add_i32 s78, 0, 0x10000
	s_and_b64 s[4:5], s[46:47], exec
	s_cselect_b32 s47, s66, s49
	s_cselect_b32 s46, s65, s48
	s_add_i32 s4, 0, 0x14000
	s_add_u32 s94, s50, 0x40080
	s_addc_u32 s95, s51, 0
	s_add_i32 s82, s78, s40
	s_add_i32 m0, s41, 0xc000
	s_add_i32 s5, s41, 0xe000
	s_add_i32 s76, s82, 0x2000
	v_add_u32_e32 v0, s78, v136
	s_add_u32 s58, s46, 0x80000
	ds_read_b128 v[138:141], v0
	ds_read_b128 v[142:145], v0 offset:1024
	ds_read_b128 v[146:149], v0 offset:2048
	ds_read_b128 v[150:153], v0 offset:3072
	s_addc_u32 s59, s47, 0
	s_add_i32 s77, s4, s40
	ds_read_b128 v[154:157], v0 offset:16384
	ds_read_b128 v[158:161], v0 offset:17408
	ds_read_b128 v[162:165], v0 offset:18432
	ds_read_b128 v[166:169], v0 offset:19456
	s_add_i32 s75, s77, 0x2000
	s_add_i32 s74, 0, 0x18000
	s_add_i32 s71, 0, 0x1c000
	s_add_u32 s50, s22, 0x40000
	s_addc_u32 s51, s23, 0
	s_add_i32 s70, s74, s40
	s_add_i32 s69, s70, 0x2000
	s_add_u32 s48, s46, 0x80080
	s_addc_u32 s49, s47, 0
	s_add_i32 s79, s71, s40
	s_add_i32 s78, s79, 0x2000
	ds_read_b128 v[170:173], v137
	ds_read_b128 v[174:177], v137 offset:1024
	ds_read_b128 v[178:181], v137 offset:2048
	ds_read_b128 v[182:185], v137 offset:3072
	ds_read_b128 v[186:189], v137 offset:4096
	ds_read_b128 v[190:193], v137 offset:5120
	ds_read_b128 v[194:197], v137 offset:6144
	ds_read_b128 v[198:201], v137 offset:7168
	s_nop 0
	global_load_lds_dwordx4 v130, s[94:95]
	s_mov_b32 m0, s5
	s_nop 0
	global_load_lds_dwordx4 v132, s[94:95]
	s_waitcnt vmcnt(8)
	s_waitcnt lgkmcnt(0)
	s_setprio 1
	s_barrier
	v_mfma_f32_16x16x32_bf16 v[126:129], v[138:141], v[170:173], v[126:129]
	v_mfma_f32_16x16x32_bf16 v[122:125], v[146:149], v[170:173], v[122:125]
	v_mfma_f32_16x16x32_bf16 v[118:121], v[138:141], v[178:181], v[118:121]
	v_mfma_f32_16x16x32_bf16 v[110:113], v[146:149], v[178:181], v[110:113]
	v_mfma_f32_16x16x32_bf16 v[102:105], v[138:141], v[186:189], v[102:105]
	v_mfma_f32_16x16x32_bf16 v[94:97], v[146:149], v[186:189], v[94:97]
	v_mfma_f32_16x16x32_bf16 v[86:89], v[138:141], v[194:197], v[86:89]
	v_mfma_f32_16x16x32_bf16 v[78:81], v[146:149], v[194:197], v[78:81]
	v_mfma_f32_16x16x32_bf16 v[126:129], v[142:145], v[174:177], v[126:129]
	v_mfma_f32_16x16x32_bf16 v[122:125], v[150:153], v[174:177], v[122:125]
	v_mfma_f32_16x16x32_bf16 v[118:121], v[142:145], v[182:185], v[118:121]
	v_mfma_f32_16x16x32_bf16 v[110:113], v[150:153], v[182:185], v[110:113]
	v_mfma_f32_16x16x32_bf16 v[102:105], v[142:145], v[190:193], v[102:105]
	v_mfma_f32_16x16x32_bf16 v[94:97], v[150:153], v[190:193], v[94:97]
	v_mfma_f32_16x16x32_bf16 v[86:89], v[142:145], v[198:201], v[86:89]
	v_mfma_f32_16x16x32_bf16 v[78:81], v[150:153], v[198:201], v[78:81]
	s_setprio 0
	s_setprio 1
	v_mfma_f32_16x16x32_bf16 v[114:117], v[154:157], v[170:173], v[114:117]
	v_mfma_f32_16x16x32_bf16 v[106:109], v[162:165], v[170:173], v[106:109]
	v_mfma_f32_16x16x32_bf16 v[98:101], v[154:157], v[178:181], v[98:101]
	v_mfma_f32_16x16x32_bf16 v[90:93], v[162:165], v[178:181], v[90:93]
	v_mfma_f32_16x16x32_bf16 v[82:85], v[154:157], v[186:189], v[82:85]
	v_mfma_f32_16x16x32_bf16 v[74:77], v[162:165], v[186:189], v[74:77]
	v_mfma_f32_16x16x32_bf16 v[70:73], v[154:157], v[194:197], v[70:73]
	v_mfma_f32_16x16x32_bf16 v[62:65], v[162:165], v[194:197], v[62:65]
	v_mfma_f32_16x16x32_bf16 v[114:117], v[158:161], v[174:177], v[114:117]
	v_mfma_f32_16x16x32_bf16 v[106:109], v[166:169], v[174:177], v[106:109]
	v_mfma_f32_16x16x32_bf16 v[98:101], v[158:161], v[182:185], v[98:101]
	v_mfma_f32_16x16x32_bf16 v[90:93], v[166:169], v[182:185], v[90:93]
	v_mfma_f32_16x16x32_bf16 v[82:85], v[158:161], v[190:193], v[82:85]
	v_mfma_f32_16x16x32_bf16 v[74:77], v[166:169], v[190:193], v[74:77]
	v_mfma_f32_16x16x32_bf16 v[70:73], v[158:161], v[198:201], v[70:73]
	v_mfma_f32_16x16x32_bf16 v[62:65], v[166:169], v[198:201], v[62:65]
	s_setprio 0
	s_barrier
	s_mov_b32 m0, s82
	ds_read_b128 v[170:173], v137 offset:16384
	ds_read_b128 v[174:177], v137 offset:17408
	ds_read_b128 v[178:181], v137 offset:18432
	ds_read_b128 v[182:185], v137 offset:19456
	ds_read_b128 v[186:189], v137 offset:20480
	ds_read_b128 v[190:193], v137 offset:21504
	ds_read_b128 v[194:197], v137 offset:22528
	ds_read_b128 v[198:201], v137 offset:23552
	s_nop 0
	global_load_lds_dwordx4 v131, s[46:47]
	s_mov_b32 m0, s76
	s_nop 0
	global_load_lds_dwordx4 v133, s[46:47]
	s_mov_b32 m0, s77
	s_nop 0
	global_load_lds_dwordx4 v131, s[58:59]
	s_mov_b32 m0, s75
	s_nop 0
	global_load_lds_dwordx4 v133, s[58:59]
	s_mov_b32 m0, s41
	s_nop 0
	global_load_lds_dwordx4 v130, s[22:23]
	s_mov_b32 m0, s42
	s_nop 0
	global_load_lds_dwordx4 v132, s[22:23]
	s_waitcnt vmcnt(8)
	s_waitcnt lgkmcnt(0)
	s_setprio 1
	s_barrier
	v_mfma_f32_16x16x32_bf16 v[66:69], v[138:141], v[170:173], v[66:69]
	v_mfma_f32_16x16x32_bf16 v[58:61], v[146:149], v[170:173], v[58:61]
	v_mfma_f32_16x16x32_bf16 v[54:57], v[138:141], v[178:181], v[54:57]
	v_mfma_f32_16x16x32_bf16 v[46:49], v[146:149], v[178:181], v[46:49]
	v_mfma_f32_16x16x32_bf16 v[38:41], v[138:141], v[186:189], v[38:41]
	v_mfma_f32_16x16x32_bf16 v[30:33], v[146:149], v[186:189], v[30:33]
	v_mfma_f32_16x16x32_bf16 v[22:25], v[138:141], v[194:197], v[22:25]
	v_mfma_f32_16x16x32_bf16 v[14:17], v[146:149], v[194:197], v[14:17]
	v_mfma_f32_16x16x32_bf16 v[66:69], v[142:145], v[174:177], v[66:69]
	v_mfma_f32_16x16x32_bf16 v[58:61], v[150:153], v[174:177], v[58:61]
	v_mfma_f32_16x16x32_bf16 v[54:57], v[142:145], v[182:185], v[54:57]
	v_mfma_f32_16x16x32_bf16 v[46:49], v[150:153], v[182:185], v[46:49]
	v_mfma_f32_16x16x32_bf16 v[38:41], v[142:145], v[190:193], v[38:41]
	v_mfma_f32_16x16x32_bf16 v[30:33], v[150:153], v[190:193], v[30:33]
	v_mfma_f32_16x16x32_bf16 v[22:25], v[142:145], v[198:201], v[22:25]
	v_mfma_f32_16x16x32_bf16 v[14:17], v[150:153], v[198:201], v[14:17]
	s_setprio 0
	s_setprio 1
	v_mfma_f32_16x16x32_bf16 v[50:53], v[154:157], v[170:173], v[50:53]
	v_mfma_f32_16x16x32_bf16 v[42:45], v[162:165], v[170:173], v[42:45]
	v_mfma_f32_16x16x32_bf16 v[34:37], v[154:157], v[178:181], v[34:37]
	v_mfma_f32_16x16x32_bf16 v[26:29], v[162:165], v[178:181], v[26:29]
	v_mfma_f32_16x16x32_bf16 v[18:21], v[154:157], v[186:189], v[18:21]
	v_mfma_f32_16x16x32_bf16 v[10:13], v[162:165], v[186:189], v[10:13]
	v_mfma_f32_16x16x32_bf16 v[6:9], v[154:157], v[194:197], v[6:9]
	v_mfma_f32_16x16x32_bf16 v[2:5], v[162:165], v[194:197], v[2:5]
	v_mfma_f32_16x16x32_bf16 v[50:53], v[158:161], v[174:177], v[50:53]
	v_mfma_f32_16x16x32_bf16 v[42:45], v[166:169], v[174:177], v[42:45]
	v_mfma_f32_16x16x32_bf16 v[34:37], v[158:161], v[182:185], v[34:37]
	v_mfma_f32_16x16x32_bf16 v[26:29], v[166:169], v[182:185], v[26:29]
	v_mfma_f32_16x16x32_bf16 v[18:21], v[158:161], v[190:193], v[18:21]
	v_mfma_f32_16x16x32_bf16 v[10:13], v[166:169], v[190:193], v[10:13]
	v_mfma_f32_16x16x32_bf16 v[6:9], v[158:161], v[198:201], v[6:9]
	v_mfma_f32_16x16x32_bf16 v[2:5], v[166:169], v[198:201], v[2:5]
	s_setprio 0
	s_barrier
	ds_read_b128 v[138:141], v0 offset:32768
	ds_read_b128 v[142:145], v0 offset:33792
	ds_read_b128 v[146:149], v0 offset:34816
	ds_read_b128 v[150:153], v0 offset:35840
	ds_read_b128 v[154:157], v0 offset:49152
	ds_read_b128 v[158:161], v0 offset:50176
	ds_read_b128 v[162:165], v0 offset:51200
	ds_read_b128 v[166:169], v0 offset:52224
	s_mov_b32 m0, s43
	ds_read_b128 v[170:173], v137 offset:32768
	ds_read_b128 v[174:177], v137 offset:33792
	ds_read_b128 v[178:181], v137 offset:34816
	ds_read_b128 v[182:185], v137 offset:35840
	ds_read_b128 v[186:189], v137 offset:36864
	ds_read_b128 v[190:193], v137 offset:37888
	ds_read_b128 v[194:197], v137 offset:38912
	ds_read_b128 v[198:201], v137 offset:39936
	s_nop 0
	global_load_lds_dwordx4 v130, s[50:51]
	s_mov_b32 m0, s64
	s_nop 0
	global_load_lds_dwordx4 v132, s[50:51]
	s_waitcnt vmcnt(8)
	s_waitcnt lgkmcnt(0)
	s_setprio 1
	s_barrier
	v_mfma_f32_16x16x32_bf16 v[126:129], v[138:141], v[170:173], v[126:129]
	v_mfma_f32_16x16x32_bf16 v[122:125], v[146:149], v[170:173], v[122:125]
	v_mfma_f32_16x16x32_bf16 v[118:121], v[138:141], v[178:181], v[118:121]
	v_mfma_f32_16x16x32_bf16 v[110:113], v[146:149], v[178:181], v[110:113]
	v_mfma_f32_16x16x32_bf16 v[102:105], v[138:141], v[186:189], v[102:105]
	v_mfma_f32_16x16x32_bf16 v[94:97], v[146:149], v[186:189], v[94:97]
	v_mfma_f32_16x16x32_bf16 v[86:89], v[138:141], v[194:197], v[86:89]
	v_mfma_f32_16x16x32_bf16 v[78:81], v[146:149], v[194:197], v[78:81]
	v_mfma_f32_16x16x32_bf16 v[126:129], v[142:145], v[174:177], v[126:129]
	v_mfma_f32_16x16x32_bf16 v[122:125], v[150:153], v[174:177], v[122:125]
	v_mfma_f32_16x16x32_bf16 v[118:121], v[142:145], v[182:185], v[118:121]
	v_mfma_f32_16x16x32_bf16 v[110:113], v[150:153], v[182:185], v[110:113]
	v_mfma_f32_16x16x32_bf16 v[102:105], v[142:145], v[190:193], v[102:105]
	v_mfma_f32_16x16x32_bf16 v[94:97], v[150:153], v[190:193], v[94:97]
	v_mfma_f32_16x16x32_bf16 v[86:89], v[142:145], v[198:201], v[86:89]
	v_mfma_f32_16x16x32_bf16 v[78:81], v[150:153], v[198:201], v[78:81]
	s_setprio 0
	s_setprio 1
	v_mfma_f32_16x16x32_bf16 v[114:117], v[154:157], v[170:173], v[114:117]
	v_mfma_f32_16x16x32_bf16 v[106:109], v[162:165], v[170:173], v[106:109]
	v_mfma_f32_16x16x32_bf16 v[98:101], v[154:157], v[178:181], v[98:101]
	v_mfma_f32_16x16x32_bf16 v[90:93], v[162:165], v[178:181], v[90:93]
	v_mfma_f32_16x16x32_bf16 v[82:85], v[154:157], v[186:189], v[82:85]
	v_mfma_f32_16x16x32_bf16 v[74:77], v[162:165], v[186:189], v[74:77]
	v_mfma_f32_16x16x32_bf16 v[70:73], v[154:157], v[194:197], v[70:73]
	v_mfma_f32_16x16x32_bf16 v[62:65], v[162:165], v[194:197], v[62:65]
	v_mfma_f32_16x16x32_bf16 v[114:117], v[158:161], v[174:177], v[114:117]
	v_mfma_f32_16x16x32_bf16 v[106:109], v[166:169], v[174:177], v[106:109]
	v_mfma_f32_16x16x32_bf16 v[98:101], v[158:161], v[182:185], v[98:101]
	v_mfma_f32_16x16x32_bf16 v[90:93], v[166:169], v[182:185], v[90:93]
	v_mfma_f32_16x16x32_bf16 v[82:85], v[158:161], v[190:193], v[82:85]
	v_mfma_f32_16x16x32_bf16 v[74:77], v[166:169], v[190:193], v[74:77]
	v_mfma_f32_16x16x32_bf16 v[70:73], v[158:161], v[198:201], v[70:73]
	v_mfma_f32_16x16x32_bf16 v[62:65], v[166:169], v[198:201], v[62:65]
	s_setprio 0
	s_barrier
	ds_read_b128 v[170:173], v137 offset:49152
	ds_read_b128 v[174:177], v137 offset:50176
	ds_read_b128 v[178:181], v137 offset:51200
	ds_read_b128 v[182:185], v137 offset:52224
	ds_read_b128 v[186:189], v137 offset:53248
	ds_read_b128 v[190:193], v137 offset:54272
	ds_read_b128 v[194:197], v137 offset:55296
	ds_read_b128 v[198:201], v137 offset:56320
	s_mov_b32 m0, s70
	s_add_u32 s100, s46, s38
	s_addc_u32 s101, s47, s39
	global_load_lds_dwordx4 v131, s[100:101]
	s_mov_b32 m0, s69
	s_nop 0
	global_load_lds_dwordx4 v133, s[100:101]
	s_mov_b32 m0, s79
	s_nop 0
	global_load_lds_dwordx4 v131, s[48:49]
	s_mov_b32 m0, s78
	s_nop 0
	global_load_lds_dwordx4 v133, s[48:49]
	s_mov_b32 m0, s67
	s_add_u32 s100, s22, s38
	s_addc_u32 s101, s23, s39
	v_mov_b32_e32 v0, v132
	global_load_lds_dwordx4 v130, s[100:101]
	s_mov_b32 m0, s68
	s_nop 0
	global_load_lds_dwordx4 v132, s[100:101]
	s_waitcnt vmcnt(8)
	s_waitcnt lgkmcnt(0)
	s_setprio 1
	s_barrier
	v_mfma_f32_16x16x32_bf16 v[66:69], v[138:141], v[170:173], v[66:69]
	v_mfma_f32_16x16x32_bf16 v[58:61], v[146:149], v[170:173], v[58:61]
	v_mfma_f32_16x16x32_bf16 v[54:57], v[138:141], v[178:181], v[54:57]
	v_mfma_f32_16x16x32_bf16 v[46:49], v[146:149], v[178:181], v[46:49]
	v_mfma_f32_16x16x32_bf16 v[38:41], v[138:141], v[186:189], v[38:41]
	v_mfma_f32_16x16x32_bf16 v[30:33], v[146:149], v[186:189], v[30:33]
	v_mfma_f32_16x16x32_bf16 v[22:25], v[138:141], v[194:197], v[22:25]
	v_mfma_f32_16x16x32_bf16 v[14:17], v[146:149], v[194:197], v[14:17]
	v_mfma_f32_16x16x32_bf16 v[66:69], v[142:145], v[174:177], v[66:69]
	v_mfma_f32_16x16x32_bf16 v[58:61], v[150:153], v[174:177], v[58:61]
	v_mfma_f32_16x16x32_bf16 v[54:57], v[142:145], v[182:185], v[54:57]
	v_mfma_f32_16x16x32_bf16 v[46:49], v[150:153], v[182:185], v[46:49]
	v_mfma_f32_16x16x32_bf16 v[38:41], v[142:145], v[190:193], v[38:41]
	v_mfma_f32_16x16x32_bf16 v[30:33], v[150:153], v[190:193], v[30:33]
	v_mfma_f32_16x16x32_bf16 v[22:25], v[142:145], v[198:201], v[22:25]
	v_mfma_f32_16x16x32_bf16 v[14:17], v[150:153], v[198:201], v[14:17]
	s_setprio 0
	s_setprio 1
	v_mfma_f32_16x16x32_bf16 v[50:53], v[154:157], v[170:173], v[50:53]
	v_mfma_f32_16x16x32_bf16 v[42:45], v[162:165], v[170:173], v[42:45]
	v_mfma_f32_16x16x32_bf16 v[34:37], v[154:157], v[178:181], v[34:37]
	v_mfma_f32_16x16x32_bf16 v[26:29], v[162:165], v[178:181], v[26:29]
	v_mfma_f32_16x16x32_bf16 v[18:21], v[154:157], v[186:189], v[18:21]
	v_mfma_f32_16x16x32_bf16 v[10:13], v[162:165], v[186:189], v[10:13]
	v_mfma_f32_16x16x32_bf16 v[6:9], v[154:157], v[194:197], v[6:9]
	v_mfma_f32_16x16x32_bf16 v[2:5], v[162:165], v[194:197], v[2:5]
	v_mfma_f32_16x16x32_bf16 v[50:53], v[158:161], v[174:177], v[50:53]
	v_mfma_f32_16x16x32_bf16 v[42:45], v[166:169], v[174:177], v[42:45]
	v_mfma_f32_16x16x32_bf16 v[34:37], v[158:161], v[182:185], v[34:37]
	v_mfma_f32_16x16x32_bf16 v[26:29], v[166:169], v[182:185], v[26:29]
	v_mfma_f32_16x16x32_bf16 v[18:21], v[158:161], v[190:193], v[18:21]
	v_mfma_f32_16x16x32_bf16 v[10:13], v[166:169], v[190:193], v[10:13]
	v_mfma_f32_16x16x32_bf16 v[6:9], v[158:161], v[198:201], v[6:9]
	v_mfma_f32_16x16x32_bf16 v[2:5], v[166:169], v[198:201], v[2:5]
	s_setprio 0
	s_barrier
	s_andn2_b64 vcc, exec, s[16:17]
	s_mov_b64 s[46:47], -1
	s_mov_b64 s[16:17], 0
	s_mov_b64 s[48:49], 0x100
	s_cbranch_vccz .LBB0_634
	s_cmpk_lt_u32 s25, 0x100
	s_cbranch_scc0 .LBB0_637
	s_barrier

.LBB0_667:
	s_add_u32 s4, s70, s50
	s_addc_u32 s5, s71, s51
	s_add_u32 s46, s4, 0x9400100
	s_addc_u32 s47, s5, 0
	s_add_u32 s58, s74, s50
	s_addc_u32 s59, s75, s51
	s_add_i32 s77, 0, 0x10000
	s_cmpk_eq_i32 s50, 0x300
	s_cselect_b32 s47, s23, s47
	s_cselect_b32 s46, s22, s46
	v_add_u32_e32 v0, s77, v144
	s_cselect_b32 s59, s49, s59
	s_cselect_b32 s58, s48, s58
	s_add_i32 s78, 0, 0x14000
	ds_read_b128 v[146:149], v0
	ds_read_b128 v[150:153], v0 offset:1024
	ds_read_b128 v[154:157], v0 offset:2048
	ds_read_b128 v[158:161], v0 offset:3072
	ds_read_b128 v[162:165], v0 offset:16384
	ds_read_b128 v[166:169], v0 offset:17408
	ds_read_b128 v[170:173], v0 offset:18432
	ds_read_b128 v[174:177], v0 offset:19456
	ds_read_b128 v[178:181], v145
	ds_read_b128 v[182:185], v145 offset:1024
	ds_read_b128 v[186:189], v145 offset:2048
	ds_read_b128 v[190:193], v145 offset:3072
	ds_read_b128 v[194:197], v145 offset:4096
	ds_read_b128 v[198:201], v145 offset:5120
	ds_read_b128 v[202:205], v145 offset:6144
	ds_read_b128 v[206:209], v145 offset:7168
	s_add_i32 m0, s61, 0xc000
	s_add_u32 s100, s4, s54
	s_addc_u32 s101, s5, s55
	global_load_lds_dwordx4 v130, s[100:101]
	s_add_i32 m0, s61, 0xe000
	s_nop 0
	global_load_lds_dwordx4 v141, s[100:101]
	s_waitcnt vmcnt(8)
	s_waitcnt lgkmcnt(0)
	s_setprio 1
	s_barrier
	v_mfma_i32_16x16x64_i8 v[126:129], v[146:149], v[178:181], v[126:129]
	v_mfma_i32_16x16x64_i8 v[122:125], v[154:157], v[178:181], v[122:125]
	v_mfma_i32_16x16x64_i8 v[110:113], v[146:149], v[186:189], v[110:113]
	v_mfma_i32_16x16x64_i8 v[106:109], v[154:157], v[186:189], v[106:109]
	v_mfma_i32_16x16x64_i8 v[94:97], v[146:149], v[194:197], v[94:97]
	v_mfma_i32_16x16x64_i8 v[90:93], v[154:157], v[194:197], v[90:93]
	v_mfma_i32_16x16x64_i8 v[78:81], v[146:149], v[202:205], v[78:81]
	v_mfma_i32_16x16x64_i8 v[74:77], v[154:157], v[202:205], v[74:77]
	v_mfma_i32_16x16x64_i8 v[126:129], v[150:153], v[182:185], v[126:129]
	v_mfma_i32_16x16x64_i8 v[122:125], v[158:161], v[182:185], v[122:125]
	v_mfma_i32_16x16x64_i8 v[110:113], v[150:153], v[190:193], v[110:113]
	v_mfma_i32_16x16x64_i8 v[106:109], v[158:161], v[190:193], v[106:109]
	v_mfma_i32_16x16x64_i8 v[94:97], v[150:153], v[198:201], v[94:97]
	v_mfma_i32_16x16x64_i8 v[90:93], v[158:161], v[198:201], v[90:93]
	v_mfma_i32_16x16x64_i8 v[78:81], v[150:153], v[206:209], v[78:81]
	v_mfma_i32_16x16x64_i8 v[74:77], v[158:161], v[206:209], v[74:77]
	s_setprio 0
	s_setprio 1
	v_mfma_i32_16x16x64_i8 v[118:121], v[162:165], v[178:181], v[118:121]
	v_mfma_i32_16x16x64_i8 v[114:117], v[170:173], v[178:181], v[114:117]
	v_mfma_i32_16x16x64_i8 v[102:105], v[162:165], v[186:189], v[102:105]
	v_mfma_i32_16x16x64_i8 v[98:101], v[170:173], v[186:189], v[98:101]
	v_mfma_i32_16x16x64_i8 v[86:89], v[162:165], v[194:197], v[86:89]
	v_mfma_i32_16x16x64_i8 v[82:85], v[170:173], v[194:197], v[82:85]
	v_mfma_i32_16x16x64_i8 v[70:73], v[162:165], v[202:205], v[70:73]
	v_mfma_i32_16x16x64_i8 v[66:69], v[170:173], v[202:205], v[66:69]
	v_mfma_i32_16x16x64_i8 v[118:121], v[166:169], v[182:185], v[118:121]
	v_mfma_i32_16x16x64_i8 v[114:117], v[174:177], v[182:185], v[114:117]
	v_mfma_i32_16x16x64_i8 v[102:105], v[166:169], v[190:193], v[102:105]
	v_mfma_i32_16x16x64_i8 v[98:101], v[174:177], v[190:193], v[98:101]
	v_mfma_i32_16x16x64_i8 v[86:89], v[166:169], v[198:201], v[86:89]
	v_mfma_i32_16x16x64_i8 v[82:85], v[174:177], v[198:201], v[82:85]
	v_mfma_i32_16x16x64_i8 v[70:73], v[166:169], v[206:209], v[70:73]
	v_mfma_i32_16x16x64_i8 v[66:69], v[174:177], v[206:209], v[66:69]
	s_setprio 0
	s_barrier
	s_add_i32 s4, s77, s60
	ds_read_b128 v[178:181], v145 offset:16384
	ds_read_b128 v[182:185], v145 offset:17408
	ds_read_b128 v[186:189], v145 offset:18432
	ds_read_b128 v[190:193], v145 offset:19456
	ds_read_b128 v[194:197], v145 offset:20480
	ds_read_b128 v[198:201], v145 offset:21504
	ds_read_b128 v[202:205], v145 offset:22528
	ds_read_b128 v[206:209], v145 offset:23552
	s_mov_b32 m0, s4
	s_nop 0
	global_load_lds_dwordx4 v131, s[58:59]
	s_add_i32 m0, s4, 0x2000
	s_add_u32 s4, s58, 0x20000
	global_load_lds_dwordx4 v142, s[58:59]
	s_addc_u32 s5, s59, 0
	s_add_i32 s77, s78, s60
	s_mov_b32 m0, s77
	s_nop 0
	global_load_lds_dwordx4 v131, s[4:5]
	s_add_i32 m0, s77, 0x2000
	s_nop 0
	global_load_lds_dwordx4 v142, s[4:5]
	s_mov_b32 m0, s61
	s_nop 0
	global_load_lds_dwordx4 v130, s[46:47]
	s_mov_b32 m0, s65
	s_nop 0
	global_load_lds_dwordx4 v141, s[46:47]
	s_waitcnt vmcnt(8)
	s_waitcnt lgkmcnt(0)
	s_setprio 1
	s_barrier
	v_mfma_i32_16x16x64_i8 v[62:65], v[146:149], v[178:181], v[62:65]
	v_mfma_i32_16x16x64_i8 v[58:61], v[154:157], v[178:181], v[58:61]
	v_mfma_i32_16x16x64_i8 v[46:49], v[146:149], v[186:189], v[46:49]
	v_mfma_i32_16x16x64_i8 v[42:45], v[154:157], v[186:189], v[42:45]
	v_mfma_i32_16x16x64_i8 v[30:33], v[146:149], v[194:197], v[30:33]
	v_mfma_i32_16x16x64_i8 v[26:29], v[154:157], v[194:197], v[26:29]
	v_mfma_i32_16x16x64_i8 v[14:17], v[146:149], v[202:205], v[14:17]
	v_mfma_i32_16x16x64_i8 v[10:13], v[154:157], v[202:205], v[10:13]
	v_mfma_i32_16x16x64_i8 v[62:65], v[150:153], v[182:185], v[62:65]
	v_mfma_i32_16x16x64_i8 v[58:61], v[158:161], v[182:185], v[58:61]
	v_mfma_i32_16x16x64_i8 v[46:49], v[150:153], v[190:193], v[46:49]
	v_mfma_i32_16x16x64_i8 v[42:45], v[158:161], v[190:193], v[42:45]
	v_mfma_i32_16x16x64_i8 v[30:33], v[150:153], v[198:201], v[30:33]
	v_mfma_i32_16x16x64_i8 v[26:29], v[158:161], v[198:201], v[26:29]
	v_mfma_i32_16x16x64_i8 v[14:17], v[150:153], v[206:209], v[14:17]
	v_mfma_i32_16x16x64_i8 v[10:13], v[158:161], v[206:209], v[10:13]
	s_setprio 0
	s_setprio 1
	v_mfma_i32_16x16x64_i8 v[54:57], v[162:165], v[178:181], v[54:57]
	v_mfma_i32_16x16x64_i8 v[50:53], v[170:173], v[178:181], v[50:53]
	v_mfma_i32_16x16x64_i8 v[38:41], v[162:165], v[186:189], v[38:41]
	v_mfma_i32_16x16x64_i8 v[34:37], v[170:173], v[186:189], v[34:37]
	v_mfma_i32_16x16x64_i8 v[22:25], v[162:165], v[194:197], v[22:25]
	v_mfma_i32_16x16x64_i8 v[18:21], v[170:173], v[194:197], v[18:21]
	v_mfma_i32_16x16x64_i8 v[6:9], v[162:165], v[202:205], v[6:9]
	v_mfma_i32_16x16x64_i8 v[2:5], v[170:173], v[202:205], v[2:5]
	v_mfma_i32_16x16x64_i8 v[54:57], v[166:169], v[182:185], v[54:57]
	v_mfma_i32_16x16x64_i8 v[50:53], v[174:177], v[182:185], v[50:53]
	v_mfma_i32_16x16x64_i8 v[38:41], v[166:169], v[190:193], v[38:41]
	v_mfma_i32_16x16x64_i8 v[34:37], v[174:177], v[190:193], v[34:37]
	v_mfma_i32_16x16x64_i8 v[22:25], v[166:169], v[198:201], v[22:25]
	v_mfma_i32_16x16x64_i8 v[18:21], v[174:177], v[198:201], v[18:21]
	v_mfma_i32_16x16x64_i8 v[6:9], v[166:169], v[206:209], v[6:9]
	v_mfma_i32_16x16x64_i8 v[2:5], v[174:177], v[206:209], v[2:5]
	s_setprio 0
	s_barrier
	s_add_i32 s77, 0, 0x18000
	s_add_i32 s78, 0, 0x1c000
	ds_read_b128 v[146:149], v0 offset:32768
	ds_read_b128 v[150:153], v0 offset:33792
	ds_read_b128 v[154:157], v0 offset:34816
	ds_read_b128 v[158:161], v0 offset:35840
	ds_read_b128 v[162:165], v0 offset:49152
	ds_read_b128 v[166:169], v0 offset:50176
	ds_read_b128 v[170:173], v0 offset:51200
	ds_read_b128 v[174:177], v0 offset:52224
	s_add_u32 s4, s46, 0x20000
	s_mov_b32 m0, s66
	ds_read_b128 v[178:181], v145 offset:32768
	ds_read_b128 v[182:185], v145 offset:33792
	ds_read_b128 v[186:189], v145 offset:34816
	ds_read_b128 v[190:193], v145 offset:35840
	ds_read_b128 v[194:197], v145 offset:36864
	ds_read_b128 v[198:201], v145 offset:37888
	ds_read_b128 v[202:205], v145 offset:38912
	ds_read_b128 v[206:209], v145 offset:39936
	s_addc_u32 s5, s47, 0
	s_nop 0
	global_load_lds_dwordx4 v130, s[4:5]
	s_mov_b32 m0, s67
	s_nop 0
	global_load_lds_dwordx4 v141, s[4:5]
	s_waitcnt vmcnt(8)
	s_waitcnt lgkmcnt(0)
	s_setprio 1
	s_barrier
	v_mfma_i32_16x16x64_i8 v[126:129], v[146:149], v[178:181], v[126:129]
	v_mfma_i32_16x16x64_i8 v[122:125], v[154:157], v[178:181], v[122:125]
	v_mfma_i32_16x16x64_i8 v[110:113], v[146:149], v[186:189], v[110:113]
	v_mfma_i32_16x16x64_i8 v[106:109], v[154:157], v[186:189], v[106:109]
	v_mfma_i32_16x16x64_i8 v[94:97], v[146:149], v[194:197], v[94:97]
	v_mfma_i32_16x16x64_i8 v[90:93], v[154:157], v[194:197], v[90:93]
	v_mfma_i32_16x16x64_i8 v[78:81], v[146:149], v[202:205], v[78:81]
	v_mfma_i32_16x16x64_i8 v[74:77], v[154:157], v[202:205], v[74:77]
	v_mfma_i32_16x16x64_i8 v[126:129], v[150:153], v[182:185], v[126:129]
	v_mfma_i32_16x16x64_i8 v[122:125], v[158:161], v[182:185], v[122:125]
	v_mfma_i32_16x16x64_i8 v[110:113], v[150:153], v[190:193], v[110:113]
	v_mfma_i32_16x16x64_i8 v[106:109], v[158:161], v[190:193], v[106:109]
	v_mfma_i32_16x16x64_i8 v[94:97], v[150:153], v[198:201], v[94:97]
	v_mfma_i32_16x16x64_i8 v[90:93], v[158:161], v[198:201], v[90:93]
	v_mfma_i32_16x16x64_i8 v[78:81], v[150:153], v[206:209], v[78:81]
	v_mfma_i32_16x16x64_i8 v[74:77], v[158:161], v[206:209], v[74:77]
	s_setprio 0
	s_setprio 1
	v_mfma_i32_16x16x64_i8 v[118:121], v[162:165], v[178:181], v[118:121]
	v_mfma_i32_16x16x64_i8 v[114:117], v[170:173], v[178:181], v[114:117]
	v_mfma_i32_16x16x64_i8 v[102:105], v[162:165], v[186:189], v[102:105]
	v_mfma_i32_16x16x64_i8 v[98:101], v[170:173], v[186:189], v[98:101]
	v_mfma_i32_16x16x64_i8 v[86:89], v[162:165], v[194:197], v[86:89]
	v_mfma_i32_16x16x64_i8 v[82:85], v[170:173], v[194:197], v[82:85]
	v_mfma_i32_16x16x64_i8 v[70:73], v[162:165], v[202:205], v[70:73]
	v_mfma_i32_16x16x64_i8 v[66:69], v[170:173], v[202:205], v[66:69]
	v_mfma_i32_16x16x64_i8 v[118:121], v[166:169], v[182:185], v[118:121]
	v_mfma_i32_16x16x64_i8 v[114:117], v[174:177], v[182:185], v[114:117]
	v_mfma_i32_16x16x64_i8 v[102:105], v[166:169], v[190:193], v[102:105]
	v_mfma_i32_16x16x64_i8 v[98:101], v[174:177], v[190:193], v[98:101]
	v_mfma_i32_16x16x64_i8 v[86:89], v[166:169], v[198:201], v[86:89]
	v_mfma_i32_16x16x64_i8 v[82:85], v[174:177], v[198:201], v[82:85]
	v_mfma_i32_16x16x64_i8 v[70:73], v[166:169], v[206:209], v[70:73]
	v_mfma_i32_16x16x64_i8 v[66:69], v[174:177], v[206:209], v[66:69]
	s_setprio 0
	s_barrier
	ds_read_b128 v[178:181], v145 offset:49152
	ds_read_b128 v[182:185], v145 offset:50176
	ds_read_b128 v[186:189], v145 offset:51200
	ds_read_b128 v[190:193], v145 offset:52224
	ds_read_b128 v[194:197], v145 offset:53248
	ds_read_b128 v[198:201], v145 offset:54272
	ds_read_b128 v[202:205], v145 offset:55296
	ds_read_b128 v[206:209], v145 offset:56320
	s_add_i32 s4, s77, s60
	s_add_u32 s100, s58, s38
	s_addc_u32 s101, s59, s39
	s_mov_b32 m0, s4
	s_nop 0
	global_load_lds_dwordx4 v131, s[100:101]
	s_add_i32 m0, s4, 0x2000
	s_add_u32 s4, s58, 0x20080
	s_addc_u32 s5, s59, 0
	s_add_i32 s58, s78, s60
	global_load_lds_dwordx4 v142, s[100:101]
	s_mov_b32 m0, s58
	s_nop 0
	global_load_lds_dwordx4 v131, s[4:5]
	s_add_i32 m0, s58, 0x2000
	s_nop 0
	global_load_lds_dwordx4 v142, s[4:5]
	s_mov_b32 m0, s68
	s_add_u32 s100, s46, s38
	s_addc_u32 s101, s47, s39
	v_mov_b32_e32 v0, v141
	global_load_lds_dwordx4 v130, s[100:101]
	s_mov_b32 m0, s69
	s_nop 0
	global_load_lds_dwordx4 v141, s[100:101]
	s_waitcnt vmcnt(8)
	s_waitcnt lgkmcnt(0)
	s_setprio 1
	s_barrier
	v_mfma_i32_16x16x64_i8 v[62:65], v[146:149], v[178:181], v[62:65]
	v_mfma_i32_16x16x64_i8 v[58:61], v[154:157], v[178:181], v[58:61]
	v_mfma_i32_16x16x64_i8 v[46:49], v[146:149], v[186:189], v[46:49]
	v_mfma_i32_16x16x64_i8 v[42:45], v[154:157], v[186:189], v[42:45]
	v_mfma_i32_16x16x64_i8 v[30:33], v[146:149], v[194:197], v[30:33]
	v_mfma_i32_16x16x64_i8 v[26:29], v[154:157], v[194:197], v[26:29]
	v_mfma_i32_16x16x64_i8 v[14:17], v[146:149], v[202:205], v[14:17]
	v_mfma_i32_16x16x64_i8 v[10:13], v[154:157], v[202:205], v[10:13]
	v_mfma_i32_16x16x64_i8 v[62:65], v[150:153], v[182:185], v[62:65]
	v_mfma_i32_16x16x64_i8 v[58:61], v[158:161], v[182:185], v[58:61]
	v_mfma_i32_16x16x64_i8 v[46:49], v[150:153], v[190:193], v[46:49]
	v_mfma_i32_16x16x64_i8 v[42:45], v[158:161], v[190:193], v[42:45]
	v_mfma_i32_16x16x64_i8 v[30:33], v[150:153], v[198:201], v[30:33]
	v_mfma_i32_16x16x64_i8 v[26:29], v[158:161], v[198:201], v[26:29]
	v_mfma_i32_16x16x64_i8 v[14:17], v[150:153], v[206:209], v[14:17]
	v_mfma_i32_16x16x64_i8 v[10:13], v[158:161], v[206:209], v[10:13]
	s_setprio 0
	s_setprio 1
	v_mfma_i32_16x16x64_i8 v[54:57], v[162:165], v[178:181], v[54:57]
	v_mfma_i32_16x16x64_i8 v[50:53], v[170:173], v[178:181], v[50:53]
	v_mfma_i32_16x16x64_i8 v[38:41], v[162:165], v[186:189], v[38:41]
	v_mfma_i32_16x16x64_i8 v[34:37], v[170:173], v[186:189], v[34:37]
	v_mfma_i32_16x16x64_i8 v[22:25], v[162:165], v[194:197], v[22:25]
	v_mfma_i32_16x16x64_i8 v[18:21], v[170:173], v[194:197], v[18:21]
	v_mfma_i32_16x16x64_i8 v[6:9], v[162:165], v[202:205], v[6:9]
	v_mfma_i32_16x16x64_i8 v[2:5], v[170:173], v[202:205], v[2:5]
	v_mfma_i32_16x16x64_i8 v[54:57], v[166:169], v[182:185], v[54:57]
	v_mfma_i32_16x16x64_i8 v[50:53], v[174:177], v[182:185], v[50:53]
	v_mfma_i32_16x16x64_i8 v[38:41], v[166:169], v[190:193], v[38:41]
	v_mfma_i32_16x16x64_i8 v[34:37], v[174:177], v[190:193], v[34:37]
	v_mfma_i32_16x16x64_i8 v[22:25], v[166:169], v[198:201], v[22:25]
	v_mfma_i32_16x16x64_i8 v[18:21], v[174:177], v[198:201], v[18:21]
	v_mfma_i32_16x16x64_i8 v[6:9], v[166:169], v[206:209], v[6:9]
	v_mfma_i32_16x16x64_i8 v[2:5], v[174:177], v[206:209], v[2:5]
	s_setprio 0
	s_barrier
	s_add_i32 s76, s76, 2
	s_add_u32 s50, s50, 0x100
	s_addc_u32 s51, s51, 0
	s_cmp_gt_u32 s76, 5
	s_cbranch_scc0 .LBB0_667
	s_cmpk_lt_u32 s17, 0x100
	s_cbranch_scc0 .LBB0_661
	s_barrier
	s_branch .LBB0_661

.LBB0_821:
	s_add_u32 s4, s79, s50
	s_addc_u32 s5, s82, s51
	s_add_u32 s46, s4, 0x9800100
	s_addc_u32 s47, s5, 0
	s_add_u32 s58, s64, s50
	s_addc_u32 s59, s83, s51
	s_add_i32 s85, 0, 0x10000
	s_cmpk_eq_i32 s50, 0x1500
	s_cselect_b32 s47, s49, s47
	s_cselect_b32 s46, s48, s46
	v_add_u32_e32 v0, s85, v134
	s_cselect_b32 s59, s71, s59
	s_cselect_b32 s58, s70, s58
	s_add_i32 s86, 0, 0x14000
	ds_read_b128 v[136:139], v0
	ds_read_b128 v[140:143], v0 offset:1024
	ds_read_b128 v[144:147], v0 offset:2048
	ds_read_b128 v[148:151], v0 offset:3072
	ds_read_b128 v[152:155], v0 offset:16384
	ds_read_b128 v[156:159], v0 offset:17408
	ds_read_b128 v[160:163], v0 offset:18432
	ds_read_b128 v[164:167], v0 offset:19456
	ds_read_b128 v[168:171], v135
	ds_read_b128 v[172:175], v135 offset:1024
	ds_read_b128 v[176:179], v135 offset:2048
	ds_read_b128 v[180:183], v135 offset:3072
	ds_read_b128 v[184:187], v135 offset:4096
	ds_read_b128 v[188:191], v135 offset:5120
	ds_read_b128 v[192:195], v135 offset:6144
	ds_read_b128 v[198:201], v135 offset:7168
	s_add_i32 m0, s60, 0xc000
	s_add_u32 s100, s4, s88
	s_addc_u32 s101, s5, s89
	global_load_lds_dwordx4 v130, s[100:101]
	s_add_i32 m0, s60, 0xe000
	s_nop 0
	global_load_lds_dwordx4 v131, s[100:101]
	s_waitcnt vmcnt(8)
	s_waitcnt lgkmcnt(0)
	s_setprio 1
	s_barrier
	v_mfma_f32_16x16x32_bf16 v[126:129], v[136:139], v[168:171], v[126:129]
	v_mfma_f32_16x16x32_bf16 v[122:125], v[144:147], v[168:171], v[122:125]
	v_mfma_f32_16x16x32_bf16 v[110:113], v[136:139], v[176:179], v[110:113]
	v_mfma_f32_16x16x32_bf16 v[106:109], v[144:147], v[176:179], v[106:109]
	v_mfma_f32_16x16x32_bf16 v[94:97], v[136:139], v[184:187], v[94:97]
	v_mfma_f32_16x16x32_bf16 v[90:93], v[144:147], v[184:187], v[90:93]
	v_mfma_f32_16x16x32_bf16 v[78:81], v[136:139], v[192:195], v[78:81]
	v_mfma_f32_16x16x32_bf16 v[74:77], v[144:147], v[192:195], v[74:77]
	v_mfma_f32_16x16x32_bf16 v[126:129], v[140:143], v[172:175], v[126:129]
	v_mfma_f32_16x16x32_bf16 v[122:125], v[148:151], v[172:175], v[122:125]
	v_mfma_f32_16x16x32_bf16 v[110:113], v[140:143], v[180:183], v[110:113]
	v_mfma_f32_16x16x32_bf16 v[106:109], v[148:151], v[180:183], v[106:109]
	v_mfma_f32_16x16x32_bf16 v[94:97], v[140:143], v[188:191], v[94:97]
	v_mfma_f32_16x16x32_bf16 v[90:93], v[148:151], v[188:191], v[90:93]
	v_mfma_f32_16x16x32_bf16 v[78:81], v[140:143], v[198:201], v[78:81]
	v_mfma_f32_16x16x32_bf16 v[74:77], v[148:151], v[198:201], v[74:77]
	s_setprio 0
	s_setprio 1
	v_mfma_f32_16x16x32_bf16 v[118:121], v[152:155], v[168:171], v[118:121]
	v_mfma_f32_16x16x32_bf16 v[114:117], v[160:163], v[168:171], v[114:117]
	v_mfma_f32_16x16x32_bf16 v[102:105], v[152:155], v[176:179], v[102:105]
	v_mfma_f32_16x16x32_bf16 v[98:101], v[160:163], v[176:179], v[98:101]
	v_mfma_f32_16x16x32_bf16 v[86:89], v[152:155], v[184:187], v[86:89]
	v_mfma_f32_16x16x32_bf16 v[82:85], v[160:163], v[184:187], v[82:85]
	v_mfma_f32_16x16x32_bf16 v[70:73], v[152:155], v[192:195], v[70:73]
	v_mfma_f32_16x16x32_bf16 v[66:69], v[160:163], v[192:195], v[66:69]
	v_mfma_f32_16x16x32_bf16 v[118:121], v[156:159], v[172:175], v[118:121]
	v_mfma_f32_16x16x32_bf16 v[114:117], v[164:167], v[172:175], v[114:117]
	v_mfma_f32_16x16x32_bf16 v[102:105], v[156:159], v[180:183], v[102:105]
	v_mfma_f32_16x16x32_bf16 v[98:101], v[164:167], v[180:183], v[98:101]
	v_mfma_f32_16x16x32_bf16 v[86:89], v[156:159], v[188:191], v[86:89]
	v_mfma_f32_16x16x32_bf16 v[82:85], v[164:167], v[188:191], v[82:85]
	v_mfma_f32_16x16x32_bf16 v[70:73], v[156:159], v[198:201], v[70:73]
	v_mfma_f32_16x16x32_bf16 v[66:69], v[164:167], v[198:201], v[66:69]
	s_setprio 0
	s_barrier
	s_add_i32 s4, s85, s26
	ds_read_b128 v[168:171], v135 offset:16384
	ds_read_b128 v[172:175], v135 offset:17408
	ds_read_b128 v[176:179], v135 offset:18432
	ds_read_b128 v[180:183], v135 offset:19456
	ds_read_b128 v[184:187], v135 offset:20480
	ds_read_b128 v[188:191], v135 offset:21504
	ds_read_b128 v[192:195], v135 offset:22528
	ds_read_b128 v[198:201], v135 offset:23552
	s_mov_b32 m0, s4
	s_nop 0
	global_load_lds_dwordx4 v132, s[58:59]
	s_add_i32 m0, s4, 0x2000
	s_add_u32 s4, s58, 0xb0000
	global_load_lds_dwordx4 v133, s[58:59]
	s_addc_u32 s5, s59, 0
	s_add_i32 s85, s86, s26
	s_mov_b32 m0, s85
	s_nop 0
	global_load_lds_dwordx4 v132, s[4:5]
	s_add_i32 m0, s85, 0x2000
	s_nop 0
	global_load_lds_dwordx4 v133, s[4:5]
	s_mov_b32 m0, s60
	s_nop 0
	global_load_lds_dwordx4 v130, s[46:47]
	s_mov_b32 m0, s65
	s_nop 0
	global_load_lds_dwordx4 v131, s[46:47]
	s_waitcnt vmcnt(8)
	s_waitcnt lgkmcnt(0)
	s_setprio 1
	s_barrier
	v_mfma_f32_16x16x32_bf16 v[62:65], v[136:139], v[168:171], v[62:65]
	v_mfma_f32_16x16x32_bf16 v[58:61], v[144:147], v[168:171], v[58:61]
	v_mfma_f32_16x16x32_bf16 v[46:49], v[136:139], v[176:179], v[46:49]
	v_mfma_f32_16x16x32_bf16 v[42:45], v[144:147], v[176:179], v[42:45]
	v_mfma_f32_16x16x32_bf16 v[30:33], v[136:139], v[184:187], v[30:33]
	v_mfma_f32_16x16x32_bf16 v[26:29], v[144:147], v[184:187], v[26:29]
	v_mfma_f32_16x16x32_bf16 v[14:17], v[136:139], v[192:195], v[14:17]
	v_mfma_f32_16x16x32_bf16 v[10:13], v[144:147], v[192:195], v[10:13]
	v_mfma_f32_16x16x32_bf16 v[62:65], v[140:143], v[172:175], v[62:65]
	v_mfma_f32_16x16x32_bf16 v[58:61], v[148:151], v[172:175], v[58:61]
	v_mfma_f32_16x16x32_bf16 v[46:49], v[140:143], v[180:183], v[46:49]
	v_mfma_f32_16x16x32_bf16 v[42:45], v[148:151], v[180:183], v[42:45]
	v_mfma_f32_16x16x32_bf16 v[30:33], v[140:143], v[188:191], v[30:33]
	v_mfma_f32_16x16x32_bf16 v[26:29], v[148:151], v[188:191], v[26:29]
	v_mfma_f32_16x16x32_bf16 v[14:17], v[140:143], v[198:201], v[14:17]
	v_mfma_f32_16x16x32_bf16 v[10:13], v[148:151], v[198:201], v[10:13]
	s_setprio 0
	s_setprio 1
	v_mfma_f32_16x16x32_bf16 v[54:57], v[152:155], v[168:171], v[54:57]
	v_mfma_f32_16x16x32_bf16 v[50:53], v[160:163], v[168:171], v[50:53]
	v_mfma_f32_16x16x32_bf16 v[38:41], v[152:155], v[176:179], v[38:41]
	v_mfma_f32_16x16x32_bf16 v[34:37], v[160:163], v[176:179], v[34:37]
	v_mfma_f32_16x16x32_bf16 v[22:25], v[152:155], v[184:187], v[22:25]
	v_mfma_f32_16x16x32_bf16 v[18:21], v[160:163], v[184:187], v[18:21]
	v_mfma_f32_16x16x32_bf16 v[6:9], v[152:155], v[192:195], v[6:9]
	v_mfma_f32_16x16x32_bf16 v[2:5], v[160:163], v[192:195], v[2:5]
	v_mfma_f32_16x16x32_bf16 v[54:57], v[156:159], v[172:175], v[54:57]
	v_mfma_f32_16x16x32_bf16 v[50:53], v[164:167], v[172:175], v[50:53]
	v_mfma_f32_16x16x32_bf16 v[38:41], v[156:159], v[180:183], v[38:41]
	v_mfma_f32_16x16x32_bf16 v[34:37], v[164:167], v[180:183], v[34:37]
	v_mfma_f32_16x16x32_bf16 v[22:25], v[156:159], v[188:191], v[22:25]
	v_mfma_f32_16x16x32_bf16 v[18:21], v[164:167], v[188:191], v[18:21]
	v_mfma_f32_16x16x32_bf16 v[6:9], v[156:159], v[198:201], v[6:9]
	v_mfma_f32_16x16x32_bf16 v[2:5], v[164:167], v[198:201], v[2:5]
	s_setprio 0
	s_barrier
	s_add_i32 s85, 0, 0x18000
	s_add_i32 s86, 0, 0x1c000
	ds_read_b128 v[136:139], v0 offset:32768
	ds_read_b128 v[140:143], v0 offset:33792
	ds_read_b128 v[144:147], v0 offset:34816
	ds_read_b128 v[148:151], v0 offset:35840
	ds_read_b128 v[152:155], v0 offset:49152
	ds_read_b128 v[156:159], v0 offset:50176
	ds_read_b128 v[160:163], v0 offset:51200
	ds_read_b128 v[164:167], v0 offset:52224
	s_add_u32 s4, s46, 0xb0000
	s_mov_b32 m0, s68
	ds_read_b128 v[168:171], v135 offset:32768
	ds_read_b128 v[172:175], v135 offset:33792
	ds_read_b128 v[176:179], v135 offset:34816
	ds_read_b128 v[180:183], v135 offset:35840
	ds_read_b128 v[184:187], v135 offset:36864
	ds_read_b128 v[188:191], v135 offset:37888
	ds_read_b128 v[192:195], v135 offset:38912
	ds_read_b128 v[198:201], v135 offset:39936
	s_addc_u32 s5, s47, 0
	s_nop 0
	global_load_lds_dwordx4 v130, s[4:5]
	s_mov_b32 m0, s69
	s_nop 0
	global_load_lds_dwordx4 v131, s[4:5]
	s_waitcnt vmcnt(8)
	s_waitcnt lgkmcnt(0)
	s_setprio 1
	s_barrier
	v_mfma_f32_16x16x32_bf16 v[126:129], v[136:139], v[168:171], v[126:129]
	v_mfma_f32_16x16x32_bf16 v[122:125], v[144:147], v[168:171], v[122:125]
	v_mfma_f32_16x16x32_bf16 v[110:113], v[136:139], v[176:179], v[110:113]
	v_mfma_f32_16x16x32_bf16 v[106:109], v[144:147], v[176:179], v[106:109]
	v_mfma_f32_16x16x32_bf16 v[94:97], v[136:139], v[184:187], v[94:97]
	v_mfma_f32_16x16x32_bf16 v[90:93], v[144:147], v[184:187], v[90:93]
	v_mfma_f32_16x16x32_bf16 v[78:81], v[136:139], v[192:195], v[78:81]
	v_mfma_f32_16x16x32_bf16 v[74:77], v[144:147], v[192:195], v[74:77]
	v_mfma_f32_16x16x32_bf16 v[126:129], v[140:143], v[172:175], v[126:129]
	v_mfma_f32_16x16x32_bf16 v[122:125], v[148:151], v[172:175], v[122:125]
	v_mfma_f32_16x16x32_bf16 v[110:113], v[140:143], v[180:183], v[110:113]
	v_mfma_f32_16x16x32_bf16 v[106:109], v[148:151], v[180:183], v[106:109]
	v_mfma_f32_16x16x32_bf16 v[94:97], v[140:143], v[188:191], v[94:97]
	v_mfma_f32_16x16x32_bf16 v[90:93], v[148:151], v[188:191], v[90:93]
	v_mfma_f32_16x16x32_bf16 v[78:81], v[140:143], v[198:201], v[78:81]
	v_mfma_f32_16x16x32_bf16 v[74:77], v[148:151], v[198:201], v[74:77]
	s_setprio 0
	s_setprio 1
	v_mfma_f32_16x16x32_bf16 v[118:121], v[152:155], v[168:171], v[118:121]
	v_mfma_f32_16x16x32_bf16 v[114:117], v[160:163], v[168:171], v[114:117]
	v_mfma_f32_16x16x32_bf16 v[102:105], v[152:155], v[176:179], v[102:105]
	v_mfma_f32_16x16x32_bf16 v[98:101], v[160:163], v[176:179], v[98:101]
	v_mfma_f32_16x16x32_bf16 v[86:89], v[152:155], v[184:187], v[86:89]
	v_mfma_f32_16x16x32_bf16 v[82:85], v[160:163], v[184:187], v[82:85]
	v_mfma_f32_16x16x32_bf16 v[70:73], v[152:155], v[192:195], v[70:73]
	v_mfma_f32_16x16x32_bf16 v[66:69], v[160:163], v[192:195], v[66:69]
	v_mfma_f32_16x16x32_bf16 v[118:121], v[156:159], v[172:175], v[118:121]
	v_mfma_f32_16x16x32_bf16 v[114:117], v[164:167], v[172:175], v[114:117]
	v_mfma_f32_16x16x32_bf16 v[102:105], v[156:159], v[180:183], v[102:105]
	v_mfma_f32_16x16x32_bf16 v[98:101], v[164:167], v[180:183], v[98:101]
	v_mfma_f32_16x16x32_bf16 v[86:89], v[156:159], v[188:191], v[86:89]
	v_mfma_f32_16x16x32_bf16 v[82:85], v[164:167], v[188:191], v[82:85]
	v_mfma_f32_16x16x32_bf16 v[70:73], v[156:159], v[198:201], v[70:73]
	v_mfma_f32_16x16x32_bf16 v[66:69], v[164:167], v[198:201], v[66:69]
	s_setprio 0
	s_barrier
	ds_read_b128 v[168:171], v135 offset:49152
	ds_read_b128 v[172:175], v135 offset:50176
	ds_read_b128 v[176:179], v135 offset:51200
	ds_read_b128 v[180:183], v135 offset:52224
	ds_read_b128 v[184:187], v135 offset:53248
	ds_read_b128 v[188:191], v135 offset:54272
	ds_read_b128 v[192:195], v135 offset:55296
	ds_read_b128 v[198:201], v135 offset:56320
	s_add_i32 s4, s85, s26
	s_add_u32 s100, s58, s38
	s_addc_u32 s101, s59, s39
	s_mov_b32 m0, s4
	s_nop 0
	global_load_lds_dwordx4 v132, s[100:101]
	s_add_i32 m0, s4, 0x2000
	s_add_u32 s4, s58, 0xb0080
	s_addc_u32 s5, s59, 0
	s_add_i32 s58, s86, s26
	global_load_lds_dwordx4 v133, s[100:101]
	s_mov_b32 m0, s58
	s_nop 0
	global_load_lds_dwordx4 v132, s[4:5]
	s_add_i32 m0, s58, 0x2000
	s_nop 0
	global_load_lds_dwordx4 v133, s[4:5]
	s_mov_b32 m0, s75
	s_add_u32 s100, s46, s38
	s_addc_u32 s101, s47, s39
	v_mov_b32_e32 v0, v131
	global_load_lds_dwordx4 v130, s[100:101]
	s_mov_b32 m0, s78
	s_nop 0
	global_load_lds_dwordx4 v131, s[100:101]
	s_waitcnt vmcnt(8)
	s_waitcnt lgkmcnt(0)
	s_setprio 1
	s_barrier
	v_mfma_f32_16x16x32_bf16 v[62:65], v[136:139], v[168:171], v[62:65]
	v_mfma_f32_16x16x32_bf16 v[58:61], v[144:147], v[168:171], v[58:61]
	v_mfma_f32_16x16x32_bf16 v[46:49], v[136:139], v[176:179], v[46:49]
	v_mfma_f32_16x16x32_bf16 v[42:45], v[144:147], v[176:179], v[42:45]
	v_mfma_f32_16x16x32_bf16 v[30:33], v[136:139], v[184:187], v[30:33]
	v_mfma_f32_16x16x32_bf16 v[26:29], v[144:147], v[184:187], v[26:29]
	v_mfma_f32_16x16x32_bf16 v[14:17], v[136:139], v[192:195], v[14:17]
	v_mfma_f32_16x16x32_bf16 v[10:13], v[144:147], v[192:195], v[10:13]
	v_mfma_f32_16x16x32_bf16 v[62:65], v[140:143], v[172:175], v[62:65]
	v_mfma_f32_16x16x32_bf16 v[58:61], v[148:151], v[172:175], v[58:61]
	v_mfma_f32_16x16x32_bf16 v[46:49], v[140:143], v[180:183], v[46:49]
	v_mfma_f32_16x16x32_bf16 v[42:45], v[148:151], v[180:183], v[42:45]
	v_mfma_f32_16x16x32_bf16 v[30:33], v[140:143], v[188:191], v[30:33]
	v_mfma_f32_16x16x32_bf16 v[26:29], v[148:151], v[188:191], v[26:29]
	v_mfma_f32_16x16x32_bf16 v[14:17], v[140:143], v[198:201], v[14:17]
	v_mfma_f32_16x16x32_bf16 v[10:13], v[148:151], v[198:201], v[10:13]
	s_setprio 0
	s_setprio 1
	v_mfma_f32_16x16x32_bf16 v[54:57], v[152:155], v[168:171], v[54:57]
	v_mfma_f32_16x16x32_bf16 v[50:53], v[160:163], v[168:171], v[50:53]
	v_mfma_f32_16x16x32_bf16 v[38:41], v[152:155], v[176:179], v[38:41]
	v_mfma_f32_16x16x32_bf16 v[34:37], v[160:163], v[176:179], v[34:37]
	v_mfma_f32_16x16x32_bf16 v[22:25], v[152:155], v[184:187], v[22:25]
	v_mfma_f32_16x16x32_bf16 v[18:21], v[160:163], v[184:187], v[18:21]
	v_mfma_f32_16x16x32_bf16 v[6:9], v[152:155], v[192:195], v[6:9]
	v_mfma_f32_16x16x32_bf16 v[2:5], v[160:163], v[192:195], v[2:5]
	v_mfma_f32_16x16x32_bf16 v[54:57], v[156:159], v[172:175], v[54:57]
	v_mfma_f32_16x16x32_bf16 v[50:53], v[164:167], v[172:175], v[50:53]
	v_mfma_f32_16x16x32_bf16 v[38:41], v[156:159], v[180:183], v[38:41]
	v_mfma_f32_16x16x32_bf16 v[34:37], v[164:167], v[180:183], v[34:37]
	v_mfma_f32_16x16x32_bf16 v[22:25], v[156:159], v[188:191], v[22:25]
	v_mfma_f32_16x16x32_bf16 v[18:21], v[164:167], v[188:191], v[18:21]
	v_mfma_f32_16x16x32_bf16 v[6:9], v[156:159], v[198:201], v[6:9]
	v_mfma_f32_16x16x32_bf16 v[2:5], v[164:167], v[198:201], v[2:5]
	s_setprio 0
	s_barrier
	s_add_i32 s84, s84, 2
	s_add_u32 s50, s50, 0x100
	s_addc_u32 s51, s51, 0
	s_cmp_gt_u32 s84, 41
	s_cbranch_scc0 .LBB0_821
	s_cmpk_lt_u32 s24, 0x100
	s_cbranch_scc0 .LBB0_824
	s_barrier

.LBB0_869:
	s_add_u32 s4, s10, s2
	s_addc_u32 s5, s11, s3
	s_add_u32 s22, s4, 0x100
	s_addc_u32 s23, s5, 0
	s_add_u32 s46, s58, s2
	s_addc_u32 s47, s59, s3
	s_add_i32 s69, 0, 0x10000
	s_cmp_eq_u32 s68, 40
	s_cselect_b32 s23, s11, s23
	s_cselect_b32 s22, s10, s22
	v_add_u32_e32 v0, s69, v126
	s_cselect_b32 s47, s17, s47
	s_cselect_b32 s46, s16, s46
	s_add_i32 s70, 0, 0x14000
	ds_read_b128 v[128:131], v0
	ds_read_b128 v[142:145], v0 offset:1024
	ds_read_b128 v[146:149], v0 offset:2048
	ds_read_b128 v[150:153], v0 offset:3072
	ds_read_b128 v[154:157], v0 offset:16384
	ds_read_b128 v[160:163], v0 offset:17408
	ds_read_b128 v[164:167], v0 offset:18432
	ds_read_b128 v[168:171], v0 offset:19456
	ds_read_b128 v[172:175], v127
	ds_read_b128 v[176:179], v127 offset:1024
	ds_read_b128 v[180:183], v127 offset:2048
	ds_read_b128 v[184:187], v127 offset:3072
	ds_read_b128 v[188:191], v127 offset:4096
	ds_read_b128 v[192:195], v127 offset:5120
	ds_read_b128 v[196:199], v127 offset:6144
	ds_read_b128 v[200:203], v127 offset:7168
	s_add_i32 m0, s41, 0xc000
	s_add_u32 s100, s4, s62
	s_addc_u32 s101, s5, s63
	global_load_lds_dwordx4 v122, s[100:101]
	s_add_i32 m0, s41, 0xe000
	s_nop 0
	global_load_lds_dwordx4 v123, s[100:101]
	s_waitcnt vmcnt(8)
	s_waitcnt lgkmcnt(0)
	s_setprio 1
	s_barrier
	v_mfma_f32_16x16x32_bf16 v[138:141], v[128:131], v[172:175], v[138:141]
	v_mfma_f32_16x16x32_bf16 v[132:135], v[146:149], v[172:175], v[134:137]
	v_mfma_f32_16x16x32_bf16 v[110:113], v[128:131], v[180:183], v[110:113]
	v_mfma_f32_16x16x32_bf16 v[106:109], v[146:149], v[180:183], v[106:109]
	v_mfma_f32_16x16x32_bf16 v[94:97], v[128:131], v[188:191], v[94:97]
	v_mfma_f32_16x16x32_bf16 v[90:93], v[146:149], v[188:191], v[90:93]
	v_mfma_f32_16x16x32_bf16 v[78:81], v[128:131], v[196:199], v[78:81]
	v_mfma_f32_16x16x32_bf16 v[74:77], v[146:149], v[196:199], v[74:77]
	v_mfma_f32_16x16x32_bf16 v[138:141], v[142:145], v[176:179], v[138:141]
	v_mfma_f32_16x16x32_bf16 v[132:135], v[150:153], v[176:179], v[132:135]
	v_mfma_f32_16x16x32_bf16 v[110:113], v[142:145], v[184:187], v[110:113]
	v_mfma_f32_16x16x32_bf16 v[106:109], v[150:153], v[184:187], v[106:109]
	v_mfma_f32_16x16x32_bf16 v[94:97], v[142:145], v[192:195], v[94:97]
	v_mfma_f32_16x16x32_bf16 v[90:93], v[150:153], v[192:195], v[90:93]
	v_mfma_f32_16x16x32_bf16 v[78:81], v[142:145], v[200:203], v[78:81]
	v_mfma_f32_16x16x32_bf16 v[74:77], v[150:153], v[200:203], v[74:77]
	s_setprio 0
	s_setprio 1
	v_mfma_f32_16x16x32_bf16 v[118:121], v[154:157], v[172:175], v[118:121]
	v_mfma_f32_16x16x32_bf16 v[114:117], v[164:167], v[172:175], v[114:117]
	v_mfma_f32_16x16x32_bf16 v[102:105], v[154:157], v[180:183], v[102:105]
	v_mfma_f32_16x16x32_bf16 v[98:101], v[164:167], v[180:183], v[98:101]
	v_mfma_f32_16x16x32_bf16 v[86:89], v[154:157], v[188:191], v[86:89]
	v_mfma_f32_16x16x32_bf16 v[82:85], v[164:167], v[188:191], v[82:85]
	v_mfma_f32_16x16x32_bf16 v[70:73], v[154:157], v[196:199], v[70:73]
	v_mfma_f32_16x16x32_bf16 v[66:69], v[164:167], v[196:199], v[66:69]
	v_mfma_f32_16x16x32_bf16 v[118:121], v[160:163], v[176:179], v[118:121]
	v_mfma_f32_16x16x32_bf16 v[114:117], v[168:171], v[176:179], v[114:117]
	v_mfma_f32_16x16x32_bf16 v[102:105], v[160:163], v[184:187], v[102:105]
	v_mfma_f32_16x16x32_bf16 v[98:101], v[168:171], v[184:187], v[98:101]
	v_mfma_f32_16x16x32_bf16 v[86:89], v[160:163], v[192:195], v[86:89]
	v_mfma_f32_16x16x32_bf16 v[82:85], v[168:171], v[192:195], v[82:85]
	v_mfma_f32_16x16x32_bf16 v[70:73], v[160:163], v[200:203], v[70:73]
	v_mfma_f32_16x16x32_bf16 v[66:69], v[168:171], v[200:203], v[66:69]
	s_setprio 0
	s_barrier
	s_add_i32 s4, s69, s26
	ds_read_b128 v[172:175], v127 offset:16384
	ds_read_b128 v[176:179], v127 offset:17408
	ds_read_b128 v[180:183], v127 offset:18432
	ds_read_b128 v[184:187], v127 offset:19456
	ds_read_b128 v[188:191], v127 offset:20480
	ds_read_b128 v[192:195], v127 offset:21504
	ds_read_b128 v[196:199], v127 offset:22528
	ds_read_b128 v[200:203], v127 offset:23552
	s_mov_b32 m0, s4
	s_nop 0
	global_load_lds_dwordx4 v124, s[46:47]
	s_add_i32 m0, s4, 0x2000
	s_add_u32 s4, s46, 0xb0000
	global_load_lds_dwordx4 v125, s[46:47]
	s_addc_u32 s5, s47, 0
	s_add_i32 s69, s70, s26
	s_mov_b32 m0, s69
	s_nop 0
	global_load_lds_dwordx4 v124, s[4:5]
	s_add_i32 m0, s69, 0x2000
	s_nop 0
	global_load_lds_dwordx4 v125, s[4:5]
	s_mov_b32 m0, s41
	s_nop 0
	global_load_lds_dwordx4 v122, s[22:23]
	s_mov_b32 m0, s48
	s_nop 0
	global_load_lds_dwordx4 v123, s[22:23]
	s_waitcnt vmcnt(8)
	s_waitcnt lgkmcnt(0)
	s_setprio 1
	s_barrier
	v_mfma_f32_16x16x32_bf16 v[62:65], v[128:131], v[172:175], v[62:65]
	v_mfma_f32_16x16x32_bf16 v[58:61], v[146:149], v[172:175], v[58:61]
	v_mfma_f32_16x16x32_bf16 v[46:49], v[128:131], v[180:183], v[46:49]
	v_mfma_f32_16x16x32_bf16 v[42:45], v[146:149], v[180:183], v[42:45]
	v_mfma_f32_16x16x32_bf16 v[30:33], v[128:131], v[188:191], v[30:33]
	v_mfma_f32_16x16x32_bf16 v[26:29], v[146:149], v[188:191], v[26:29]
	v_mfma_f32_16x16x32_bf16 v[14:17], v[128:131], v[196:199], v[14:17]
	v_mfma_f32_16x16x32_bf16 v[10:13], v[146:149], v[196:199], v[10:13]
	v_mfma_f32_16x16x32_bf16 v[62:65], v[142:145], v[176:179], v[62:65]
	v_mfma_f32_16x16x32_bf16 v[58:61], v[150:153], v[176:179], v[58:61]
	v_mfma_f32_16x16x32_bf16 v[46:49], v[142:145], v[184:187], v[46:49]
	v_mfma_f32_16x16x32_bf16 v[42:45], v[150:153], v[184:187], v[42:45]
	v_mfma_f32_16x16x32_bf16 v[30:33], v[142:145], v[192:195], v[30:33]
	v_mfma_f32_16x16x32_bf16 v[26:29], v[150:153], v[192:195], v[26:29]
	v_mfma_f32_16x16x32_bf16 v[14:17], v[142:145], v[200:203], v[14:17]
	v_mfma_f32_16x16x32_bf16 v[10:13], v[150:153], v[200:203], v[10:13]
	s_setprio 0
	s_setprio 1
	v_mfma_f32_16x16x32_bf16 v[54:57], v[154:157], v[172:175], v[54:57]
	v_mfma_f32_16x16x32_bf16 v[50:53], v[164:167], v[172:175], v[50:53]
	v_mfma_f32_16x16x32_bf16 v[38:41], v[154:157], v[180:183], v[38:41]
	v_mfma_f32_16x16x32_bf16 v[34:37], v[164:167], v[180:183], v[34:37]
	v_mfma_f32_16x16x32_bf16 v[22:25], v[154:157], v[188:191], v[22:25]
	v_mfma_f32_16x16x32_bf16 v[18:21], v[164:167], v[188:191], v[18:21]
	v_mfma_f32_16x16x32_bf16 v[6:9], v[154:157], v[196:199], v[6:9]
	v_mfma_f32_16x16x32_bf16 v[2:5], v[164:167], v[196:199], v[2:5]
	v_mfma_f32_16x16x32_bf16 v[54:57], v[160:163], v[176:179], v[54:57]
	v_mfma_f32_16x16x32_bf16 v[50:53], v[168:171], v[176:179], v[50:53]
	v_mfma_f32_16x16x32_bf16 v[38:41], v[160:163], v[184:187], v[38:41]
	v_mfma_f32_16x16x32_bf16 v[34:37], v[168:171], v[184:187], v[34:37]
	v_mfma_f32_16x16x32_bf16 v[22:25], v[160:163], v[192:195], v[22:25]
	v_mfma_f32_16x16x32_bf16 v[18:21], v[168:171], v[192:195], v[18:21]
	v_mfma_f32_16x16x32_bf16 v[6:9], v[160:163], v[200:203], v[6:9]
	v_mfma_f32_16x16x32_bf16 v[2:5], v[168:171], v[200:203], v[2:5]
	s_setprio 0
	s_barrier
	s_add_i32 s69, 0, 0x18000
	s_add_i32 s70, 0, 0x1c000
	ds_read_b128 v[128:131], v0 offset:32768
	ds_read_b128 v[142:145], v0 offset:33792
	ds_read_b128 v[146:149], v0 offset:34816
	ds_read_b128 v[150:153], v0 offset:35840
	ds_read_b128 v[154:157], v0 offset:49152
	ds_read_b128 v[160:163], v0 offset:50176
	ds_read_b128 v[164:167], v0 offset:51200
	ds_read_b128 v[168:171], v0 offset:52224
	s_add_u32 s4, s22, 0xb0000
	s_mov_b32 m0, s49
	ds_read_b128 v[172:175], v127 offset:32768
	ds_read_b128 v[176:179], v127 offset:33792
	ds_read_b128 v[180:183], v127 offset:34816
	ds_read_b128 v[184:187], v127 offset:35840
	ds_read_b128 v[188:191], v127 offset:36864
	ds_read_b128 v[192:195], v127 offset:37888
	ds_read_b128 v[196:199], v127 offset:38912
	ds_read_b128 v[200:203], v127 offset:39936
	s_addc_u32 s5, s23, 0
	s_nop 0
	global_load_lds_dwordx4 v122, s[4:5]
	s_mov_b32 m0, s50
	s_nop 0
	global_load_lds_dwordx4 v123, s[4:5]
	s_waitcnt vmcnt(8)
	s_waitcnt lgkmcnt(0)
	s_setprio 1
	s_barrier
	v_mfma_f32_16x16x32_bf16 v[136:139], v[128:131], v[172:175], v[138:141]
	v_mfma_f32_16x16x32_bf16 v[132:135], v[146:149], v[172:175], v[132:135]
	v_mfma_f32_16x16x32_bf16 v[110:113], v[128:131], v[180:183], v[110:113]
	v_mfma_f32_16x16x32_bf16 v[106:109], v[146:149], v[180:183], v[106:109]
	v_mfma_f32_16x16x32_bf16 v[94:97], v[128:131], v[188:191], v[94:97]
	v_mfma_f32_16x16x32_bf16 v[90:93], v[146:149], v[188:191], v[90:93]
	v_mfma_f32_16x16x32_bf16 v[78:81], v[128:131], v[196:199], v[78:81]
	v_mfma_f32_16x16x32_bf16 v[74:77], v[146:149], v[196:199], v[74:77]
	v_mfma_f32_16x16x32_bf16 v[138:141], v[142:145], v[176:179], v[136:139]
	v_mfma_f32_16x16x32_bf16 v[134:137], v[150:153], v[176:179], v[132:135]
	v_mfma_f32_16x16x32_bf16 v[110:113], v[142:145], v[184:187], v[110:113]
	v_mfma_f32_16x16x32_bf16 v[106:109], v[150:153], v[184:187], v[106:109]
	v_mfma_f32_16x16x32_bf16 v[94:97], v[142:145], v[192:195], v[94:97]
	v_mfma_f32_16x16x32_bf16 v[90:93], v[150:153], v[192:195], v[90:93]
	v_mfma_f32_16x16x32_bf16 v[78:81], v[142:145], v[200:203], v[78:81]
	v_mfma_f32_16x16x32_bf16 v[74:77], v[150:153], v[200:203], v[74:77]
	s_setprio 0
	s_setprio 1
	v_mfma_f32_16x16x32_bf16 v[118:121], v[154:157], v[172:175], v[118:121]
	v_mfma_f32_16x16x32_bf16 v[114:117], v[164:167], v[172:175], v[114:117]
	v_mfma_f32_16x16x32_bf16 v[102:105], v[154:157], v[180:183], v[102:105]
	v_mfma_f32_16x16x32_bf16 v[98:101], v[164:167], v[180:183], v[98:101]
	v_mfma_f32_16x16x32_bf16 v[86:89], v[154:157], v[188:191], v[86:89]
	v_mfma_f32_16x16x32_bf16 v[82:85], v[164:167], v[188:191], v[82:85]
	v_mfma_f32_16x16x32_bf16 v[70:73], v[154:157], v[196:199], v[70:73]
	v_mfma_f32_16x16x32_bf16 v[66:69], v[164:167], v[196:199], v[66:69]
	v_mfma_f32_16x16x32_bf16 v[118:121], v[160:163], v[176:179], v[118:121]
	v_mfma_f32_16x16x32_bf16 v[114:117], v[168:171], v[176:179], v[114:117]
	v_mfma_f32_16x16x32_bf16 v[102:105], v[160:163], v[184:187], v[102:105]
	v_mfma_f32_16x16x32_bf16 v[98:101], v[168:171], v[184:187], v[98:101]
	v_mfma_f32_16x16x32_bf16 v[86:89], v[160:163], v[192:195], v[86:89]
	v_mfma_f32_16x16x32_bf16 v[82:85], v[168:171], v[192:195], v[82:85]
	v_mfma_f32_16x16x32_bf16 v[70:73], v[160:163], v[200:203], v[70:73]
	v_mfma_f32_16x16x32_bf16 v[66:69], v[168:171], v[200:203], v[66:69]
	s_setprio 0
	s_barrier
	ds_read_b128 v[172:175], v127 offset:49152
	ds_read_b128 v[176:179], v127 offset:50176
	ds_read_b128 v[180:183], v127 offset:51200
	ds_read_b128 v[184:187], v127 offset:52224
	ds_read_b128 v[188:191], v127 offset:53248
	ds_read_b128 v[192:195], v127 offset:54272
	ds_read_b128 v[196:199], v127 offset:55296
	ds_read_b128 v[200:203], v127 offset:56320
	s_add_i32 s4, s69, s26
	s_add_u32 s100, s46, s38
	s_addc_u32 s101, s47, s39
	s_mov_b32 m0, s4
	s_nop 0
	global_load_lds_dwordx4 v124, s[100:101]
	s_add_i32 m0, s4, 0x2000
	s_add_u32 s4, s46, 0xb0080
	s_addc_u32 s5, s47, 0
	s_add_i32 s46, s70, s26
	global_load_lds_dwordx4 v125, s[100:101]
	s_mov_b32 m0, s46
	s_nop 0
	global_load_lds_dwordx4 v124, s[4:5]
	s_add_i32 m0, s46, 0x2000
	s_nop 0
	global_load_lds_dwordx4 v125, s[4:5]
	s_mov_b32 m0, s64
	s_add_u32 s100, s22, s38
	s_addc_u32 s101, s23, s39
	v_mov_b32_e32 v0, v123
	global_load_lds_dwordx4 v122, s[100:101]
	s_mov_b32 m0, s65
	s_nop 0
	global_load_lds_dwordx4 v123, s[100:101]
	s_waitcnt vmcnt(8)
	s_waitcnt lgkmcnt(0)
	s_setprio 1
	s_barrier
	v_mfma_f32_16x16x32_bf16 v[62:65], v[128:131], v[172:175], v[62:65]
	v_mfma_f32_16x16x32_bf16 v[58:61], v[146:149], v[172:175], v[58:61]
	v_mfma_f32_16x16x32_bf16 v[46:49], v[128:131], v[180:183], v[46:49]
	v_mfma_f32_16x16x32_bf16 v[42:45], v[146:149], v[180:183], v[42:45]
	v_mfma_f32_16x16x32_bf16 v[30:33], v[128:131], v[188:191], v[30:33]
	v_mfma_f32_16x16x32_bf16 v[26:29], v[146:149], v[188:191], v[26:29]
	v_mfma_f32_16x16x32_bf16 v[14:17], v[128:131], v[196:199], v[14:17]
	v_mfma_f32_16x16x32_bf16 v[10:13], v[146:149], v[196:199], v[10:13]
	v_mfma_f32_16x16x32_bf16 v[62:65], v[142:145], v[176:179], v[62:65]
	v_mfma_f32_16x16x32_bf16 v[58:61], v[150:153], v[176:179], v[58:61]
	v_mfma_f32_16x16x32_bf16 v[46:49], v[142:145], v[184:187], v[46:49]
	v_mfma_f32_16x16x32_bf16 v[42:45], v[150:153], v[184:187], v[42:45]
	v_mfma_f32_16x16x32_bf16 v[30:33], v[142:145], v[192:195], v[30:33]
	v_mfma_f32_16x16x32_bf16 v[26:29], v[150:153], v[192:195], v[26:29]
	v_mfma_f32_16x16x32_bf16 v[14:17], v[142:145], v[200:203], v[14:17]
	v_mfma_f32_16x16x32_bf16 v[10:13], v[150:153], v[200:203], v[10:13]
	s_setprio 0
	s_setprio 1
	v_mfma_f32_16x16x32_bf16 v[54:57], v[154:157], v[172:175], v[54:57]
	v_mfma_f32_16x16x32_bf16 v[50:53], v[164:167], v[172:175], v[50:53]
	v_mfma_f32_16x16x32_bf16 v[38:41], v[154:157], v[180:183], v[38:41]
	v_mfma_f32_16x16x32_bf16 v[34:37], v[164:167], v[180:183], v[34:37]
	v_mfma_f32_16x16x32_bf16 v[22:25], v[154:157], v[188:191], v[22:25]
	v_mfma_f32_16x16x32_bf16 v[18:21], v[164:167], v[188:191], v[18:21]
	v_mfma_f32_16x16x32_bf16 v[6:9], v[154:157], v[196:199], v[6:9]
	v_mfma_f32_16x16x32_bf16 v[2:5], v[164:167], v[196:199], v[2:5]
	v_mfma_f32_16x16x32_bf16 v[54:57], v[160:163], v[176:179], v[54:57]
	v_mfma_f32_16x16x32_bf16 v[50:53], v[168:171], v[176:179], v[50:53]
	v_mfma_f32_16x16x32_bf16 v[38:41], v[160:163], v[184:187], v[38:41]
	v_mfma_f32_16x16x32_bf16 v[34:37], v[168:171], v[184:187], v[34:37]
	v_mfma_f32_16x16x32_bf16 v[22:25], v[160:163], v[192:195], v[22:25]
	v_mfma_f32_16x16x32_bf16 v[18:21], v[168:171], v[192:195], v[18:21]
	v_mfma_f32_16x16x32_bf16 v[6:9], v[160:163], v[200:203], v[6:9]
	v_mfma_f32_16x16x32_bf16 v[2:5], v[168:171], v[200:203], v[2:5]
	s_setprio 0
	s_barrier
	s_add_i32 s68, s68, 2
	s_add_u32 s2, s2, 0x100
	s_addc_u32 s3, s3, 0
	s_cmp_gt_u32 s68, 41
	s_cbranch_scc0 .LBB0_869
	s_cmpk_lt_u32 s25, 0x100
	s_cbranch_scc0 .LBB0_872
	s_barrier

.LBB0_953:
	s_add_u32 s58, s4, s2
	s_addc_u32 s59, s5, s3
	s_add_u32 s14, s58, 0x100
	s_addc_u32 s15, s59, 0
	s_add_u32 s16, s43, s2
	s_addc_u32 s17, s46, s3
	s_add_i32 s51, 0, 0x10000
	s_cmp_eq_u32 s50, 40
	s_cselect_b32 s15, s5, s15
	s_cselect_b32 s14, s4, s14
	v_add_u32_e32 v0, s51, v135
	s_cselect_b32 s17, s7, s17
	s_cselect_b32 s16, s6, s16
	s_add_i32 s60, 0, 0x14000
	ds_read_b128 v[138:141], v0
	ds_read_b128 v[142:145], v0 offset:1024
	ds_read_b128 v[146:149], v0 offset:2048
	ds_read_b128 v[150:153], v0 offset:3072
	ds_read_b128 v[154:157], v0 offset:16384
	ds_read_b128 v[158:161], v0 offset:17408
	ds_read_b128 v[162:165], v0 offset:18432
	ds_read_b128 v[166:169], v0 offset:19456
	ds_read_b128 v[170:173], v136
	ds_read_b128 v[174:177], v136 offset:1024
	ds_read_b128 v[178:181], v136 offset:2048
	ds_read_b128 v[182:185], v136 offset:3072
	ds_read_b128 v[186:189], v136 offset:4096
	ds_read_b128 v[190:193], v136 offset:5120
	ds_read_b128 v[194:197], v136 offset:6144
	ds_read_b128 v[198:201], v136 offset:7168
	s_add_i32 m0, s37, 0xc000
	s_add_u32 s100, s58, s62
	s_addc_u32 s101, s59, s63
	global_load_lds_dwordx4 v130, s[100:101]
	s_add_i32 m0, s37, 0xe000
	s_nop 0
	global_load_lds_dwordx4 v131, s[100:101]
	s_waitcnt vmcnt(8)
	s_waitcnt lgkmcnt(0)
	s_setprio 1
	s_barrier
	v_mfma_f32_16x16x32_bf16 v[126:129], v[138:141], v[170:173], v[126:129]
	v_mfma_f32_16x16x32_bf16 v[122:125], v[146:149], v[170:173], v[122:125]
	v_mfma_f32_16x16x32_bf16 v[110:113], v[138:141], v[178:181], v[110:113]
	v_mfma_f32_16x16x32_bf16 v[106:109], v[146:149], v[178:181], v[106:109]
	v_mfma_f32_16x16x32_bf16 v[94:97], v[138:141], v[186:189], v[94:97]
	v_mfma_f32_16x16x32_bf16 v[90:93], v[146:149], v[186:189], v[90:93]
	v_mfma_f32_16x16x32_bf16 v[78:81], v[138:141], v[194:197], v[78:81]
	v_mfma_f32_16x16x32_bf16 v[74:77], v[146:149], v[194:197], v[74:77]
	v_mfma_f32_16x16x32_bf16 v[126:129], v[142:145], v[174:177], v[126:129]
	v_mfma_f32_16x16x32_bf16 v[122:125], v[150:153], v[174:177], v[122:125]
	v_mfma_f32_16x16x32_bf16 v[110:113], v[142:145], v[182:185], v[110:113]
	v_mfma_f32_16x16x32_bf16 v[106:109], v[150:153], v[182:185], v[106:109]
	v_mfma_f32_16x16x32_bf16 v[94:97], v[142:145], v[190:193], v[94:97]
	v_mfma_f32_16x16x32_bf16 v[90:93], v[150:153], v[190:193], v[90:93]
	v_mfma_f32_16x16x32_bf16 v[78:81], v[142:145], v[198:201], v[78:81]
	v_mfma_f32_16x16x32_bf16 v[74:77], v[150:153], v[198:201], v[74:77]
	s_setprio 0
	s_setprio 1
	v_mfma_f32_16x16x32_bf16 v[118:121], v[154:157], v[170:173], v[118:121]
	v_mfma_f32_16x16x32_bf16 v[114:117], v[162:165], v[170:173], v[114:117]
	v_mfma_f32_16x16x32_bf16 v[102:105], v[154:157], v[178:181], v[102:105]
	v_mfma_f32_16x16x32_bf16 v[98:101], v[162:165], v[178:181], v[98:101]
	v_mfma_f32_16x16x32_bf16 v[86:89], v[154:157], v[186:189], v[86:89]
	v_mfma_f32_16x16x32_bf16 v[82:85], v[162:165], v[186:189], v[82:85]
	v_mfma_f32_16x16x32_bf16 v[70:73], v[154:157], v[194:197], v[70:73]
	v_mfma_f32_16x16x32_bf16 v[66:69], v[162:165], v[194:197], v[66:69]
	v_mfma_f32_16x16x32_bf16 v[118:121], v[158:161], v[174:177], v[118:121]
	v_mfma_f32_16x16x32_bf16 v[114:117], v[166:169], v[174:177], v[114:117]
	v_mfma_f32_16x16x32_bf16 v[102:105], v[158:161], v[182:185], v[102:105]
	v_mfma_f32_16x16x32_bf16 v[98:101], v[166:169], v[182:185], v[98:101]
	v_mfma_f32_16x16x32_bf16 v[86:89], v[158:161], v[190:193], v[86:89]
	v_mfma_f32_16x16x32_bf16 v[82:85], v[166:169], v[190:193], v[82:85]
	v_mfma_f32_16x16x32_bf16 v[70:73], v[158:161], v[198:201], v[70:73]
	v_mfma_f32_16x16x32_bf16 v[66:69], v[166:169], v[198:201], v[66:69]
	s_setprio 0
	s_barrier
	s_add_i32 s51, s51, s26
	ds_read_b128 v[170:173], v136 offset:16384
	ds_read_b128 v[174:177], v136 offset:17408
	ds_read_b128 v[178:181], v136 offset:18432
	ds_read_b128 v[182:185], v136 offset:19456
	ds_read_b128 v[186:189], v136 offset:20480
	ds_read_b128 v[190:193], v136 offset:21504
	ds_read_b128 v[194:197], v136 offset:22528
	ds_read_b128 v[198:201], v136 offset:23552
	s_mov_b32 m0, s51
	s_nop 0
	global_load_lds_dwordx4 v133, s[16:17]
	s_add_i32 m0, s51, 0x2000
	s_add_u32 s58, s16, 0xb0000
	global_load_lds_dwordx4 v134, s[16:17]
	s_addc_u32 s59, s17, 0
	s_add_i32 s51, s60, s26
	s_mov_b32 m0, s51
	s_nop 0
	global_load_lds_dwordx4 v133, s[58:59]
	s_add_i32 m0, s51, 0x2000
	s_nop 0
	global_load_lds_dwordx4 v134, s[58:59]
	s_mov_b32 m0, s37
	s_nop 0
	global_load_lds_dwordx4 v130, s[14:15]
	s_mov_b32 m0, s40
	s_nop 0
	global_load_lds_dwordx4 v131, s[14:15]
	s_waitcnt vmcnt(8)
	s_waitcnt lgkmcnt(0)
	s_setprio 1
	s_barrier
	v_mfma_f32_16x16x32_bf16 v[62:65], v[138:141], v[170:173], v[62:65]
	v_mfma_f32_16x16x32_bf16 v[58:61], v[146:149], v[170:173], v[58:61]
	v_mfma_f32_16x16x32_bf16 v[46:49], v[138:141], v[178:181], v[46:49]
	v_mfma_f32_16x16x32_bf16 v[42:45], v[146:149], v[178:181], v[42:45]
	v_mfma_f32_16x16x32_bf16 v[30:33], v[138:141], v[186:189], v[30:33]
	v_mfma_f32_16x16x32_bf16 v[26:29], v[146:149], v[186:189], v[26:29]
	v_mfma_f32_16x16x32_bf16 v[14:17], v[138:141], v[194:197], v[14:17]
	v_mfma_f32_16x16x32_bf16 v[10:13], v[146:149], v[194:197], v[10:13]
	v_mfma_f32_16x16x32_bf16 v[62:65], v[142:145], v[174:177], v[62:65]
	v_mfma_f32_16x16x32_bf16 v[58:61], v[150:153], v[174:177], v[58:61]
	v_mfma_f32_16x16x32_bf16 v[46:49], v[142:145], v[182:185], v[46:49]
	v_mfma_f32_16x16x32_bf16 v[42:45], v[150:153], v[182:185], v[42:45]
	v_mfma_f32_16x16x32_bf16 v[30:33], v[142:145], v[190:193], v[30:33]
	v_mfma_f32_16x16x32_bf16 v[26:29], v[150:153], v[190:193], v[26:29]
	v_mfma_f32_16x16x32_bf16 v[14:17], v[142:145], v[198:201], v[14:17]
	v_mfma_f32_16x16x32_bf16 v[10:13], v[150:153], v[198:201], v[10:13]
	s_setprio 0
	s_setprio 1
	v_mfma_f32_16x16x32_bf16 v[54:57], v[154:157], v[170:173], v[54:57]
	v_mfma_f32_16x16x32_bf16 v[50:53], v[162:165], v[170:173], v[50:53]
	v_mfma_f32_16x16x32_bf16 v[38:41], v[154:157], v[178:181], v[38:41]
	v_mfma_f32_16x16x32_bf16 v[34:37], v[162:165], v[178:181], v[34:37]
	v_mfma_f32_16x16x32_bf16 v[22:25], v[154:157], v[186:189], v[22:25]
	v_mfma_f32_16x16x32_bf16 v[18:21], v[162:165], v[186:189], v[18:21]
	v_mfma_f32_16x16x32_bf16 v[6:9], v[154:157], v[194:197], v[6:9]
	v_mfma_f32_16x16x32_bf16 v[2:5], v[162:165], v[194:197], v[2:5]
	v_mfma_f32_16x16x32_bf16 v[54:57], v[158:161], v[174:177], v[54:57]
	v_mfma_f32_16x16x32_bf16 v[50:53], v[166:169], v[174:177], v[50:53]
	v_mfma_f32_16x16x32_bf16 v[38:41], v[158:161], v[182:185], v[38:41]
	v_mfma_f32_16x16x32_bf16 v[34:37], v[166:169], v[182:185], v[34:37]
	v_mfma_f32_16x16x32_bf16 v[22:25], v[158:161], v[190:193], v[22:25]
	v_mfma_f32_16x16x32_bf16 v[18:21], v[166:169], v[190:193], v[18:21]
	v_mfma_f32_16x16x32_bf16 v[6:9], v[158:161], v[198:201], v[6:9]
	v_mfma_f32_16x16x32_bf16 v[2:5], v[166:169], v[198:201], v[2:5]
	s_setprio 0
	s_barrier
	s_add_i32 s51, 0, 0x18000
	s_add_i32 s60, 0, 0x1c000
	ds_read_b128 v[138:141], v0 offset:32768
	ds_read_b128 v[142:145], v0 offset:33792
	ds_read_b128 v[146:149], v0 offset:34816
	ds_read_b128 v[150:153], v0 offset:35840
	ds_read_b128 v[154:157], v0 offset:49152
	ds_read_b128 v[158:161], v0 offset:50176
	ds_read_b128 v[162:165], v0 offset:51200
	ds_read_b128 v[166:169], v0 offset:52224
	s_add_u32 s58, s14, 0xb0000
	s_mov_b32 m0, s41
	ds_read_b128 v[170:173], v136 offset:32768
	ds_read_b128 v[174:177], v136 offset:33792
	ds_read_b128 v[178:181], v136 offset:34816
	ds_read_b128 v[182:185], v136 offset:35840
	ds_read_b128 v[186:189], v136 offset:36864
	ds_read_b128 v[190:193], v136 offset:37888
	ds_read_b128 v[194:197], v136 offset:38912
	ds_read_b128 v[198:201], v136 offset:39936
	s_addc_u32 s59, s15, 0
	s_nop 0
	global_load_lds_dwordx4 v130, s[58:59]
	s_mov_b32 m0, s42
	s_nop 0
	global_load_lds_dwordx4 v131, s[58:59]
	s_waitcnt vmcnt(8)
	s_waitcnt lgkmcnt(0)
	s_setprio 1
	s_barrier
	v_mfma_f32_16x16x32_bf16 v[126:129], v[138:141], v[170:173], v[126:129]
	v_mfma_f32_16x16x32_bf16 v[122:125], v[146:149], v[170:173], v[122:125]
	v_mfma_f32_16x16x32_bf16 v[110:113], v[138:141], v[178:181], v[110:113]
	v_mfma_f32_16x16x32_bf16 v[106:109], v[146:149], v[178:181], v[106:109]
	v_mfma_f32_16x16x32_bf16 v[94:97], v[138:141], v[186:189], v[94:97]
	v_mfma_f32_16x16x32_bf16 v[90:93], v[146:149], v[186:189], v[90:93]
	v_mfma_f32_16x16x32_bf16 v[78:81], v[138:141], v[194:197], v[78:81]
	v_mfma_f32_16x16x32_bf16 v[74:77], v[146:149], v[194:197], v[74:77]
	v_mfma_f32_16x16x32_bf16 v[126:129], v[142:145], v[174:177], v[126:129]
	v_mfma_f32_16x16x32_bf16 v[122:125], v[150:153], v[174:177], v[122:125]
	v_mfma_f32_16x16x32_bf16 v[110:113], v[142:145], v[182:185], v[110:113]
	v_mfma_f32_16x16x32_bf16 v[106:109], v[150:153], v[182:185], v[106:109]
	v_mfma_f32_16x16x32_bf16 v[94:97], v[142:145], v[190:193], v[94:97]
	v_mfma_f32_16x16x32_bf16 v[90:93], v[150:153], v[190:193], v[90:93]
	v_mfma_f32_16x16x32_bf16 v[78:81], v[142:145], v[198:201], v[78:81]
	v_mfma_f32_16x16x32_bf16 v[74:77], v[150:153], v[198:201], v[74:77]
	s_setprio 0
	s_setprio 1
	v_mfma_f32_16x16x32_bf16 v[118:121], v[154:157], v[170:173], v[118:121]
	v_mfma_f32_16x16x32_bf16 v[114:117], v[162:165], v[170:173], v[114:117]
	v_mfma_f32_16x16x32_bf16 v[102:105], v[154:157], v[178:181], v[102:105]
	v_mfma_f32_16x16x32_bf16 v[98:101], v[162:165], v[178:181], v[98:101]
	v_mfma_f32_16x16x32_bf16 v[86:89], v[154:157], v[186:189], v[86:89]
	v_mfma_f32_16x16x32_bf16 v[82:85], v[162:165], v[186:189], v[82:85]
	v_mfma_f32_16x16x32_bf16 v[70:73], v[154:157], v[194:197], v[70:73]
	v_mfma_f32_16x16x32_bf16 v[66:69], v[162:165], v[194:197], v[66:69]
	v_mfma_f32_16x16x32_bf16 v[118:121], v[158:161], v[174:177], v[118:121]
	v_mfma_f32_16x16x32_bf16 v[114:117], v[166:169], v[174:177], v[114:117]
	v_mfma_f32_16x16x32_bf16 v[102:105], v[158:161], v[182:185], v[102:105]
	v_mfma_f32_16x16x32_bf16 v[98:101], v[166:169], v[182:185], v[98:101]
	v_mfma_f32_16x16x32_bf16 v[86:89], v[158:161], v[190:193], v[86:89]
	v_mfma_f32_16x16x32_bf16 v[82:85], v[166:169], v[190:193], v[82:85]
	v_mfma_f32_16x16x32_bf16 v[70:73], v[158:161], v[198:201], v[70:73]
	v_mfma_f32_16x16x32_bf16 v[66:69], v[166:169], v[198:201], v[66:69]
	s_setprio 0
	s_barrier
	ds_read_b128 v[170:173], v136 offset:49152
	ds_read_b128 v[174:177], v136 offset:50176
	ds_read_b128 v[178:181], v136 offset:51200
	ds_read_b128 v[182:185], v136 offset:52224
	ds_read_b128 v[186:189], v136 offset:53248
	ds_read_b128 v[190:193], v136 offset:54272
	ds_read_b128 v[194:197], v136 offset:55296
	ds_read_b128 v[198:201], v136 offset:56320
	s_add_i32 s51, s51, s26
	s_add_u32 s100, s16, s38
	s_addc_u32 s101, s17, s39
	s_mov_b32 m0, s51
	s_nop 0
	global_load_lds_dwordx4 v133, s[100:101]
	s_add_i32 m0, s51, 0x2000
	s_nop 0
	s_add_u32 s16, s16, 0xb0080
	s_addc_u32 s17, s17, 0
	s_add_i32 s51, s60, s26
	global_load_lds_dwordx4 v134, s[100:101]
	s_mov_b32 m0, s51
	s_nop 0
	global_load_lds_dwordx4 v133, s[16:17]
	s_add_i32 m0, s51, 0x2000
	s_nop 0
	global_load_lds_dwordx4 v134, s[16:17]
	s_mov_b32 m0, s48
	s_add_u32 s100, s14, s38
	s_addc_u32 s101, s15, s39
	v_mov_b32_e32 v0, v131
	global_load_lds_dwordx4 v130, s[100:101]
	s_mov_b32 m0, s49
	s_nop 0
	global_load_lds_dwordx4 v131, s[100:101]
	s_waitcnt vmcnt(8)
	s_waitcnt lgkmcnt(0)
	s_setprio 1
	s_barrier
	v_mfma_f32_16x16x32_bf16 v[62:65], v[138:141], v[170:173], v[62:65]
	v_mfma_f32_16x16x32_bf16 v[58:61], v[146:149], v[170:173], v[58:61]
	v_mfma_f32_16x16x32_bf16 v[46:49], v[138:141], v[178:181], v[46:49]
	v_mfma_f32_16x16x32_bf16 v[42:45], v[146:149], v[178:181], v[42:45]
	v_mfma_f32_16x16x32_bf16 v[30:33], v[138:141], v[186:189], v[30:33]
	v_mfma_f32_16x16x32_bf16 v[26:29], v[146:149], v[186:189], v[26:29]
	v_mfma_f32_16x16x32_bf16 v[14:17], v[138:141], v[194:197], v[14:17]
	v_mfma_f32_16x16x32_bf16 v[10:13], v[146:149], v[194:197], v[10:13]
	v_mfma_f32_16x16x32_bf16 v[62:65], v[142:145], v[174:177], v[62:65]
	v_mfma_f32_16x16x32_bf16 v[58:61], v[150:153], v[174:177], v[58:61]
	v_mfma_f32_16x16x32_bf16 v[46:49], v[142:145], v[182:185], v[46:49]
	v_mfma_f32_16x16x32_bf16 v[42:45], v[150:153], v[182:185], v[42:45]
	v_mfma_f32_16x16x32_bf16 v[30:33], v[142:145], v[190:193], v[30:33]
	v_mfma_f32_16x16x32_bf16 v[26:29], v[150:153], v[190:193], v[26:29]
	v_mfma_f32_16x16x32_bf16 v[14:17], v[142:145], v[198:201], v[14:17]
	v_mfma_f32_16x16x32_bf16 v[10:13], v[150:153], v[198:201], v[10:13]
	s_setprio 0
	s_setprio 1
	v_mfma_f32_16x16x32_bf16 v[54:57], v[154:157], v[170:173], v[54:57]
	v_mfma_f32_16x16x32_bf16 v[50:53], v[162:165], v[170:173], v[50:53]
	v_mfma_f32_16x16x32_bf16 v[38:41], v[154:157], v[178:181], v[38:41]
	v_mfma_f32_16x16x32_bf16 v[34:37], v[162:165], v[178:181], v[34:37]
	v_mfma_f32_16x16x32_bf16 v[22:25], v[154:157], v[186:189], v[22:25]
	v_mfma_f32_16x16x32_bf16 v[18:21], v[162:165], v[186:189], v[18:21]
	v_mfma_f32_16x16x32_bf16 v[6:9], v[154:157], v[194:197], v[6:9]
	v_mfma_f32_16x16x32_bf16 v[2:5], v[162:165], v[194:197], v[2:5]
	v_mfma_f32_16x16x32_bf16 v[54:57], v[158:161], v[174:177], v[54:57]
	v_mfma_f32_16x16x32_bf16 v[50:53], v[166:169], v[174:177], v[50:53]
	v_mfma_f32_16x16x32_bf16 v[38:41], v[158:161], v[182:185], v[38:41]
	v_mfma_f32_16x16x32_bf16 v[34:37], v[166:169], v[182:185], v[34:37]
	v_mfma_f32_16x16x32_bf16 v[22:25], v[158:161], v[190:193], v[22:25]
	v_mfma_f32_16x16x32_bf16 v[18:21], v[166:169], v[190:193], v[18:21]
	v_mfma_f32_16x16x32_bf16 v[6:9], v[158:161], v[198:201], v[6:9]
	v_mfma_f32_16x16x32_bf16 v[2:5], v[166:169], v[198:201], v[2:5]
	s_setprio 0
	s_barrier
	s_add_i32 s50, s50, 2
	s_add_u32 s2, s2, 0x100
	s_addc_u32 s3, s3, 0
	s_cmp_gt_u32 s50, 41
	s_cbranch_scc0 .LBB0_953
	s_cmpk_lt_u32 s25, 0x100
	s_cbranch_scc0 .LBB0_956
	s_barrier

.LBB0_1087:
	s_add_u32 s2, s6, 0x40080
	s_addc_u32 s3, s7, 0
	s_add_u32 s8, s8, 0x100
	s_addc_u32 s9, s9, 0
	s_mov_b32 s22, -2
	s_add_u32 s4, s2, 0xfffc0080
	s_addc_u32 s5, s3, -1
	s_add_i32 s23, 0, 0x10000
	s_cmp_eq_u32 s22, 12
	s_cselect_b32 s5, s49, s5
	s_cselect_b32 s4, s48, s4
	s_waitcnt vmcnt(0)
	v_add_u32_e32 v0, s23, v145
	s_cselect_b32 s7, s97, s9
	s_cselect_b32 s6, s96, s8
	s_add_i32 s25, 0, 0x14000
	ds_read_b128 v[146:149], v0
	ds_read_b128 v[152:155], v0 offset:1024
	ds_read_b128 v[156:159], v0 offset:2048
	ds_read_b128 v[160:163], v0 offset:3072
	ds_read_b128 v[164:167], v0 offset:16384
	ds_read_b128 v[168:171], v0 offset:17408
	ds_read_b128 v[172:175], v0 offset:18432
	ds_read_b128 v[176:179], v0 offset:19456
	ds_read_b128 v[180:183], v150
	ds_read_b128 v[184:187], v150 offset:1024
	ds_read_b128 v[188:191], v150 offset:2048
	ds_read_b128 v[192:195], v150 offset:3072
	ds_read_b128 v[196:199], v150 offset:4096
	ds_read_b128 v[200:203], v150 offset:5120
	ds_read_b128 v[204:207], v150 offset:6144
	ds_read_b128 v[208:211], v150 offset:7168
	s_add_i32 m0, s60, 0xc000
	s_nop 0
	global_load_lds_dwordx4 v131, s[2:3]
	s_add_i32 m0, s60, 0xe000
	s_nop 0
	global_load_lds_dwordx4 v133, s[2:3]
	s_waitcnt vmcnt(8)
	s_waitcnt lgkmcnt(0)
	s_setprio 1
	s_barrier
	v_mfma_f32_16x16x32_bf16 v[126:129], v[146:149], v[180:183], 0
	v_mfma_f32_16x16x32_bf16 v[122:125], v[156:159], v[180:183], 0
	v_mfma_f32_16x16x32_bf16 v[110:113], v[146:149], v[188:191], 0
	v_mfma_f32_16x16x32_bf16 v[106:109], v[156:159], v[188:191], 0
	v_mfma_f32_16x16x32_bf16 v[94:97], v[146:149], v[196:199], 0
	v_mfma_f32_16x16x32_bf16 v[90:93], v[156:159], v[196:199], 0
	v_mfma_f32_16x16x32_bf16 v[78:81], v[146:149], v[204:207], 0
	v_mfma_f32_16x16x32_bf16 v[74:77], v[156:159], v[204:207], 0
	v_mfma_f32_16x16x32_bf16 v[126:129], v[152:155], v[184:187], v[126:129]
	v_mfma_f32_16x16x32_bf16 v[122:125], v[160:163], v[184:187], v[122:125]
	v_mfma_f32_16x16x32_bf16 v[110:113], v[152:155], v[192:195], v[110:113]
	v_mfma_f32_16x16x32_bf16 v[106:109], v[160:163], v[192:195], v[106:109]
	v_mfma_f32_16x16x32_bf16 v[94:97], v[152:155], v[200:203], v[94:97]
	v_mfma_f32_16x16x32_bf16 v[90:93], v[160:163], v[200:203], v[90:93]
	v_mfma_f32_16x16x32_bf16 v[78:81], v[152:155], v[208:211], v[78:81]
	v_mfma_f32_16x16x32_bf16 v[74:77], v[160:163], v[208:211], v[74:77]
	s_setprio 0
	s_setprio 1
	v_mfma_f32_16x16x32_bf16 v[118:121], v[164:167], v[180:183], 0
	v_mfma_f32_16x16x32_bf16 v[114:117], v[172:175], v[180:183], 0
	v_mfma_f32_16x16x32_bf16 v[102:105], v[164:167], v[188:191], 0
	v_mfma_f32_16x16x32_bf16 v[98:101], v[172:175], v[188:191], 0
	v_mfma_f32_16x16x32_bf16 v[86:89], v[164:167], v[196:199], 0
	v_mfma_f32_16x16x32_bf16 v[82:85], v[172:175], v[196:199], 0
	v_mfma_f32_16x16x32_bf16 v[70:73], v[164:167], v[204:207], 0
	v_mfma_f32_16x16x32_bf16 v[66:69], v[172:175], v[204:207], 0
	v_mfma_f32_16x16x32_bf16 v[118:121], v[168:171], v[184:187], v[118:121]
	v_mfma_f32_16x16x32_bf16 v[114:117], v[176:179], v[184:187], v[114:117]
	v_mfma_f32_16x16x32_bf16 v[102:105], v[168:171], v[192:195], v[102:105]
	v_mfma_f32_16x16x32_bf16 v[98:101], v[176:179], v[192:195], v[98:101]
	v_mfma_f32_16x16x32_bf16 v[86:89], v[168:171], v[200:203], v[86:89]
	v_mfma_f32_16x16x32_bf16 v[82:85], v[176:179], v[200:203], v[82:85]
	v_mfma_f32_16x16x32_bf16 v[70:73], v[168:171], v[208:211], v[70:73]
	v_mfma_f32_16x16x32_bf16 v[66:69], v[176:179], v[208:211], v[66:69]
	s_setprio 0
	s_barrier
	s_add_i32 s23, s23, s42
	ds_read_b128 v[180:183], v150 offset:16384
	ds_read_b128 v[184:187], v150 offset:17408
	ds_read_b128 v[188:191], v150 offset:18432
	ds_read_b128 v[192:195], v150 offset:19456
	ds_read_b128 v[196:199], v150 offset:20480
	ds_read_b128 v[200:203], v150 offset:21504
	ds_read_b128 v[204:207], v150 offset:22528
	ds_read_b128 v[208:211], v150 offset:23552
	s_mov_b32 m0, s23
	s_nop 0
	global_load_lds_dwordx4 v137, s[6:7]
	s_add_i32 m0, s23, 0x2000
	s_add_u32 s46, s6, 0x40000
	global_load_lds_dwordx4 v139, s[6:7]
	s_addc_u32 s47, s7, 0
	s_add_i32 s23, s25, s42
	s_mov_b32 m0, s23
	s_nop 0
	global_load_lds_dwordx4 v137, s[46:47]
	s_add_i32 m0, s23, 0x2000
	s_nop 0
	global_load_lds_dwordx4 v139, s[46:47]
	s_mov_b32 m0, s60
	s_nop 0
	global_load_lds_dwordx4 v131, s[4:5]
	s_mov_b32 m0, s61
	s_nop 0
	global_load_lds_dwordx4 v133, s[4:5]
	s_waitcnt vmcnt(8)
	s_waitcnt lgkmcnt(0)
	s_setprio 1
	s_barrier
	v_mfma_f32_16x16x32_bf16 v[62:65], v[146:149], v[180:183], 0
	v_mfma_f32_16x16x32_bf16 v[58:61], v[156:159], v[180:183], 0
	v_mfma_f32_16x16x32_bf16 v[46:49], v[146:149], v[188:191], 0
	v_mfma_f32_16x16x32_bf16 v[42:45], v[156:159], v[188:191], 0
	v_mfma_f32_16x16x32_bf16 v[30:33], v[146:149], v[196:199], 0
	v_mfma_f32_16x16x32_bf16 v[26:29], v[156:159], v[196:199], 0
	v_mfma_f32_16x16x32_bf16 v[14:17], v[146:149], v[204:207], 0
	v_mfma_f32_16x16x32_bf16 v[10:13], v[156:159], v[204:207], 0
	v_mfma_f32_16x16x32_bf16 v[62:65], v[152:155], v[184:187], v[62:65]
	v_mfma_f32_16x16x32_bf16 v[58:61], v[160:163], v[184:187], v[58:61]
	v_mfma_f32_16x16x32_bf16 v[46:49], v[152:155], v[192:195], v[46:49]
	v_mfma_f32_16x16x32_bf16 v[42:45], v[160:163], v[192:195], v[42:45]
	v_mfma_f32_16x16x32_bf16 v[30:33], v[152:155], v[200:203], v[30:33]
	v_mfma_f32_16x16x32_bf16 v[26:29], v[160:163], v[200:203], v[26:29]
	v_mfma_f32_16x16x32_bf16 v[14:17], v[152:155], v[208:211], v[14:17]
	v_mfma_f32_16x16x32_bf16 v[10:13], v[160:163], v[208:211], v[10:13]
	s_setprio 0
	s_setprio 1
	v_mfma_f32_16x16x32_bf16 v[54:57], v[164:167], v[180:183], 0
	v_mfma_f32_16x16x32_bf16 v[50:53], v[172:175], v[180:183], 0
	v_mfma_f32_16x16x32_bf16 v[38:41], v[164:167], v[188:191], 0
	v_mfma_f32_16x16x32_bf16 v[34:37], v[172:175], v[188:191], 0
	v_mfma_f32_16x16x32_bf16 v[22:25], v[164:167], v[196:199], 0
	v_mfma_f32_16x16x32_bf16 v[18:21], v[172:175], v[196:199], 0
	v_mfma_f32_16x16x32_bf16 v[6:9], v[164:167], v[204:207], 0
	v_mfma_f32_16x16x32_bf16 v[2:5], v[172:175], v[204:207], 0
	v_mfma_f32_16x16x32_bf16 v[54:57], v[168:171], v[184:187], v[54:57]
	v_mfma_f32_16x16x32_bf16 v[50:53], v[176:179], v[184:187], v[50:53]
	v_mfma_f32_16x16x32_bf16 v[38:41], v[168:171], v[192:195], v[38:41]
	v_mfma_f32_16x16x32_bf16 v[34:37], v[176:179], v[192:195], v[34:37]
	v_mfma_f32_16x16x32_bf16 v[22:25], v[168:171], v[200:203], v[22:25]
	v_mfma_f32_16x16x32_bf16 v[18:21], v[176:179], v[200:203], v[18:21]
	v_mfma_f32_16x16x32_bf16 v[6:9], v[168:171], v[208:211], v[6:9]
	v_mfma_f32_16x16x32_bf16 v[2:5], v[176:179], v[208:211], v[2:5]
	s_setprio 0
	s_barrier
	s_add_i32 s23, 0, 0x18000
	s_add_i32 s25, 0, 0x1c000
	ds_read_b128 v[146:149], v0 offset:32768
	ds_read_b128 v[152:155], v0 offset:33792
	ds_read_b128 v[156:159], v0 offset:34816
	ds_read_b128 v[160:163], v0 offset:35840
	ds_read_b128 v[164:167], v0 offset:49152
	ds_read_b128 v[168:171], v0 offset:50176
	ds_read_b128 v[172:175], v0 offset:51200
	ds_read_b128 v[176:179], v0 offset:52224
	s_add_u32 s46, s4, 0x40000
	s_mov_b32 m0, s66
	ds_read_b128 v[180:183], v150 offset:32768
	ds_read_b128 v[184:187], v150 offset:33792
	ds_read_b128 v[188:191], v150 offset:34816
	ds_read_b128 v[192:195], v150 offset:35840
	ds_read_b128 v[196:199], v150 offset:36864
	ds_read_b128 v[200:203], v150 offset:37888
	ds_read_b128 v[204:207], v150 offset:38912
	ds_read_b128 v[208:211], v150 offset:39936
	s_addc_u32 s47, s5, 0
	s_nop 0
	global_load_lds_dwordx4 v131, s[46:47]
	s_mov_b32 m0, s67
	s_nop 0
	global_load_lds_dwordx4 v133, s[46:47]
	s_waitcnt vmcnt(8)
	s_waitcnt lgkmcnt(0)
	s_setprio 1
	s_barrier
	v_mfma_f32_16x16x32_bf16 v[126:129], v[146:149], v[180:183], v[126:129]
	v_mfma_f32_16x16x32_bf16 v[122:125], v[156:159], v[180:183], v[122:125]
	v_mfma_f32_16x16x32_bf16 v[110:113], v[146:149], v[188:191], v[110:113]
	v_mfma_f32_16x16x32_bf16 v[106:109], v[156:159], v[188:191], v[106:109]
	v_mfma_f32_16x16x32_bf16 v[94:97], v[146:149], v[196:199], v[94:97]
	v_mfma_f32_16x16x32_bf16 v[90:93], v[156:159], v[196:199], v[90:93]
	v_mfma_f32_16x16x32_bf16 v[78:81], v[146:149], v[204:207], v[78:81]
	v_mfma_f32_16x16x32_bf16 v[74:77], v[156:159], v[204:207], v[74:77]
	v_mfma_f32_16x16x32_bf16 v[126:129], v[152:155], v[184:187], v[126:129]
	v_mfma_f32_16x16x32_bf16 v[122:125], v[160:163], v[184:187], v[122:125]
	v_mfma_f32_16x16x32_bf16 v[110:113], v[152:155], v[192:195], v[110:113]
	v_mfma_f32_16x16x32_bf16 v[106:109], v[160:163], v[192:195], v[106:109]
	v_mfma_f32_16x16x32_bf16 v[94:97], v[152:155], v[200:203], v[94:97]
	v_mfma_f32_16x16x32_bf16 v[90:93], v[160:163], v[200:203], v[90:93]
	v_mfma_f32_16x16x32_bf16 v[78:81], v[152:155], v[208:211], v[78:81]
	v_mfma_f32_16x16x32_bf16 v[74:77], v[160:163], v[208:211], v[74:77]
	s_setprio 0
	s_setprio 1
	v_mfma_f32_16x16x32_bf16 v[118:121], v[164:167], v[180:183], v[118:121]
	v_mfma_f32_16x16x32_bf16 v[114:117], v[172:175], v[180:183], v[114:117]
	v_mfma_f32_16x16x32_bf16 v[102:105], v[164:167], v[188:191], v[102:105]
	v_mfma_f32_16x16x32_bf16 v[98:101], v[172:175], v[188:191], v[98:101]
	v_mfma_f32_16x16x32_bf16 v[86:89], v[164:167], v[196:199], v[86:89]
	v_mfma_f32_16x16x32_bf16 v[82:85], v[172:175], v[196:199], v[82:85]
	v_mfma_f32_16x16x32_bf16 v[70:73], v[164:167], v[204:207], v[70:73]
	v_mfma_f32_16x16x32_bf16 v[66:69], v[172:175], v[204:207], v[66:69]
	v_mfma_f32_16x16x32_bf16 v[118:121], v[168:171], v[184:187], v[118:121]
	v_mfma_f32_16x16x32_bf16 v[114:117], v[176:179], v[184:187], v[114:117]
	v_mfma_f32_16x16x32_bf16 v[102:105], v[168:171], v[192:195], v[102:105]
	v_mfma_f32_16x16x32_bf16 v[98:101], v[176:179], v[192:195], v[98:101]
	v_mfma_f32_16x16x32_bf16 v[86:89], v[168:171], v[200:203], v[86:89]
	v_mfma_f32_16x16x32_bf16 v[82:85], v[176:179], v[200:203], v[82:85]
	v_mfma_f32_16x16x32_bf16 v[70:73], v[168:171], v[208:211], v[70:73]
	v_mfma_f32_16x16x32_bf16 v[66:69], v[176:179], v[208:211], v[66:69]
	s_setprio 0
	s_barrier
	ds_read_b128 v[180:183], v150 offset:49152
	ds_read_b128 v[184:187], v150 offset:50176
	ds_read_b128 v[188:191], v150 offset:51200
	ds_read_b128 v[192:195], v150 offset:52224
	ds_read_b128 v[196:199], v150 offset:53248
	ds_read_b128 v[200:203], v150 offset:54272
	ds_read_b128 v[204:207], v150 offset:55296
	ds_read_b128 v[208:211], v150 offset:56320
	s_add_i32 s23, s23, s42
	s_add_u32 s100, s6, s38
	s_addc_u32 s101, s7, s39
	s_mov_b32 m0, s23
	s_nop 0
	global_load_lds_dwordx4 v137, s[100:101]
	s_add_i32 m0, s23, 0x2000
	s_nop 0
	s_add_u32 s6, s6, 0x40080
	s_addc_u32 s7, s7, 0
	s_add_i32 s23, s25, s42
	global_load_lds_dwordx4 v139, s[100:101]
	s_mov_b32 m0, s23
	s_nop 0
	global_load_lds_dwordx4 v137, s[6:7]
	s_add_i32 m0, s23, 0x2000
	s_nop 0
	global_load_lds_dwordx4 v139, s[6:7]
	s_mov_b32 m0, s70
	s_add_u32 s100, s4, s38
	s_addc_u32 s101, s5, s39
	v_mov_b32_e32 v0, v133
	global_load_lds_dwordx4 v131, s[100:101]
	s_mov_b32 m0, s71
	s_nop 0
	global_load_lds_dwordx4 v133, s[100:101]
	s_waitcnt vmcnt(8)
	s_waitcnt lgkmcnt(0)
	s_setprio 1
	s_barrier
	v_mfma_f32_16x16x32_bf16 v[62:65], v[146:149], v[180:183], v[62:65]
	v_mfma_f32_16x16x32_bf16 v[58:61], v[156:159], v[180:183], v[58:61]
	v_mfma_f32_16x16x32_bf16 v[46:49], v[146:149], v[188:191], v[46:49]
	v_mfma_f32_16x16x32_bf16 v[42:45], v[156:159], v[188:191], v[42:45]
	v_mfma_f32_16x16x32_bf16 v[30:33], v[146:149], v[196:199], v[30:33]
	v_mfma_f32_16x16x32_bf16 v[26:29], v[156:159], v[196:199], v[26:29]
	v_mfma_f32_16x16x32_bf16 v[14:17], v[146:149], v[204:207], v[14:17]
	v_mfma_f32_16x16x32_bf16 v[10:13], v[156:159], v[204:207], v[10:13]
	v_mfma_f32_16x16x32_bf16 v[62:65], v[152:155], v[184:187], v[62:65]
	v_mfma_f32_16x16x32_bf16 v[58:61], v[160:163], v[184:187], v[58:61]
	v_mfma_f32_16x16x32_bf16 v[46:49], v[152:155], v[192:195], v[46:49]
	v_mfma_f32_16x16x32_bf16 v[42:45], v[160:163], v[192:195], v[42:45]
	v_mfma_f32_16x16x32_bf16 v[30:33], v[152:155], v[200:203], v[30:33]
	v_mfma_f32_16x16x32_bf16 v[26:29], v[160:163], v[200:203], v[26:29]
	v_mfma_f32_16x16x32_bf16 v[14:17], v[152:155], v[208:211], v[14:17]
	v_mfma_f32_16x16x32_bf16 v[10:13], v[160:163], v[208:211], v[10:13]
	s_setprio 0
	s_setprio 1
	v_mfma_f32_16x16x32_bf16 v[54:57], v[164:167], v[180:183], v[54:57]
	v_mfma_f32_16x16x32_bf16 v[50:53], v[172:175], v[180:183], v[50:53]
	v_mfma_f32_16x16x32_bf16 v[38:41], v[164:167], v[188:191], v[38:41]
	v_mfma_f32_16x16x32_bf16 v[34:37], v[172:175], v[188:191], v[34:37]
	v_mfma_f32_16x16x32_bf16 v[22:25], v[164:167], v[196:199], v[22:25]
	v_mfma_f32_16x16x32_bf16 v[18:21], v[172:175], v[196:199], v[18:21]
	v_mfma_f32_16x16x32_bf16 v[6:9], v[164:167], v[204:207], v[6:9]
	v_mfma_f32_16x16x32_bf16 v[2:5], v[172:175], v[204:207], v[2:5]
	v_mfma_f32_16x16x32_bf16 v[54:57], v[168:171], v[184:187], v[54:57]
	v_mfma_f32_16x16x32_bf16 v[50:53], v[176:179], v[184:187], v[50:53]
	v_mfma_f32_16x16x32_bf16 v[38:41], v[168:171], v[192:195], v[38:41]
	v_mfma_f32_16x16x32_bf16 v[34:37], v[176:179], v[192:195], v[34:37]
	v_mfma_f32_16x16x32_bf16 v[22:25], v[168:171], v[200:203], v[22:25]
	v_mfma_f32_16x16x32_bf16 v[18:21], v[176:179], v[200:203], v[18:21]
	v_mfma_f32_16x16x32_bf16 v[6:9], v[168:171], v[208:211], v[6:9]
	v_mfma_f32_16x16x32_bf16 v[2:5], v[176:179], v[208:211], v[2:5]
	s_setprio 0
	s_barrier
	s_add_i32 s22, s22, 2
	s_add_u32 s2, s2, 0x100
	s_addc_u32 s3, s3, 0
	s_add_u32 s8, s8, 0x100
	s_addc_u32 s9, s9, 0
	s_cmp_gt_u32 s22, 13
	s_cbranch_scc0 .LBB0_1088
	s_branch .Lpeel_exit_1088
.LBB0_1088:
	s_add_u32 s4, s2, 0xfffc0080
	s_addc_u32 s5, s3, -1
	s_add_i32 s23, 0, 0x10000
	s_cmp_eq_u32 s22, 12
	s_cselect_b32 s5, s49, s5
	s_cselect_b32 s4, s48, s4
	v_add_u32_e32 v0, s23, v145
	s_cselect_b32 s7, s97, s9
	s_cselect_b32 s6, s96, s8
	s_add_i32 s25, 0, 0x14000
	ds_read_b128 v[146:149], v0
	ds_read_b128 v[152:155], v0 offset:1024
	ds_read_b128 v[156:159], v0 offset:2048
	ds_read_b128 v[160:163], v0 offset:3072
	ds_read_b128 v[164:167], v0 offset:16384
	ds_read_b128 v[168:171], v0 offset:17408
	ds_read_b128 v[172:175], v0 offset:18432
	ds_read_b128 v[176:179], v0 offset:19456
	ds_read_b128 v[180:183], v150
	ds_read_b128 v[184:187], v150 offset:1024
	ds_read_b128 v[188:191], v150 offset:2048
	ds_read_b128 v[192:195], v150 offset:3072
	ds_read_b128 v[196:199], v150 offset:4096
	ds_read_b128 v[200:203], v150 offset:5120
	ds_read_b128 v[204:207], v150 offset:6144
	ds_read_b128 v[208:211], v150 offset:7168
	s_add_i32 m0, s60, 0xc000
	s_nop 0
	global_load_lds_dwordx4 v131, s[2:3]
	s_add_i32 m0, s60, 0xe000
	s_nop 0
	global_load_lds_dwordx4 v133, s[2:3]
	s_waitcnt vmcnt(8)
	s_waitcnt lgkmcnt(0)
	s_setprio 1
	s_barrier
	v_mfma_f32_16x16x32_bf16 v[126:129], v[146:149], v[180:183], v[126:129]
	v_mfma_f32_16x16x32_bf16 v[122:125], v[156:159], v[180:183], v[122:125]
	v_mfma_f32_16x16x32_bf16 v[110:113], v[146:149], v[188:191], v[110:113]
	v_mfma_f32_16x16x32_bf16 v[106:109], v[156:159], v[188:191], v[106:109]
	v_mfma_f32_16x16x32_bf16 v[94:97], v[146:149], v[196:199], v[94:97]
	v_mfma_f32_16x16x32_bf16 v[90:93], v[156:159], v[196:199], v[90:93]
	v_mfma_f32_16x16x32_bf16 v[78:81], v[146:149], v[204:207], v[78:81]
	v_mfma_f32_16x16x32_bf16 v[74:77], v[156:159], v[204:207], v[74:77]
	v_mfma_f32_16x16x32_bf16 v[126:129], v[152:155], v[184:187], v[126:129]
	v_mfma_f32_16x16x32_bf16 v[122:125], v[160:163], v[184:187], v[122:125]
	v_mfma_f32_16x16x32_bf16 v[110:113], v[152:155], v[192:195], v[110:113]
	v_mfma_f32_16x16x32_bf16 v[106:109], v[160:163], v[192:195], v[106:109]
	v_mfma_f32_16x16x32_bf16 v[94:97], v[152:155], v[200:203], v[94:97]
	v_mfma_f32_16x16x32_bf16 v[90:93], v[160:163], v[200:203], v[90:93]
	v_mfma_f32_16x16x32_bf16 v[78:81], v[152:155], v[208:211], v[78:81]
	v_mfma_f32_16x16x32_bf16 v[74:77], v[160:163], v[208:211], v[74:77]
	s_setprio 0
	s_setprio 1
	v_mfma_f32_16x16x32_bf16 v[118:121], v[164:167], v[180:183], v[118:121]
	v_mfma_f32_16x16x32_bf16 v[114:117], v[172:175], v[180:183], v[114:117]
	v_mfma_f32_16x16x32_bf16 v[102:105], v[164:167], v[188:191], v[102:105]
	v_mfma_f32_16x16x32_bf16 v[98:101], v[172:175], v[188:191], v[98:101]
	v_mfma_f32_16x16x32_bf16 v[86:89], v[164:167], v[196:199], v[86:89]
	v_mfma_f32_16x16x32_bf16 v[82:85], v[172:175], v[196:199], v[82:85]
	v_mfma_f32_16x16x32_bf16 v[70:73], v[164:167], v[204:207], v[70:73]
	v_mfma_f32_16x16x32_bf16 v[66:69], v[172:175], v[204:207], v[66:69]
	v_mfma_f32_16x16x32_bf16 v[118:121], v[168:171], v[184:187], v[118:121]
	v_mfma_f32_16x16x32_bf16 v[114:117], v[176:179], v[184:187], v[114:117]
	v_mfma_f32_16x16x32_bf16 v[102:105], v[168:171], v[192:195], v[102:105]
	v_mfma_f32_16x16x32_bf16 v[98:101], v[176:179], v[192:195], v[98:101]
	v_mfma_f32_16x16x32_bf16 v[86:89], v[168:171], v[200:203], v[86:89]
	v_mfma_f32_16x16x32_bf16 v[82:85], v[176:179], v[200:203], v[82:85]
	v_mfma_f32_16x16x32_bf16 v[70:73], v[168:171], v[208:211], v[70:73]
	v_mfma_f32_16x16x32_bf16 v[66:69], v[176:179], v[208:211], v[66:69]
	s_setprio 0
	s_barrier
	s_add_i32 s23, s23, s42
	ds_read_b128 v[180:183], v150 offset:16384
	ds_read_b128 v[184:187], v150 offset:17408
	ds_read_b128 v[188:191], v150 offset:18432
	ds_read_b128 v[192:195], v150 offset:19456
	ds_read_b128 v[196:199], v150 offset:20480
	ds_read_b128 v[200:203], v150 offset:21504
	ds_read_b128 v[204:207], v150 offset:22528
	ds_read_b128 v[208:211], v150 offset:23552
	s_mov_b32 m0, s23
	s_nop 0
	global_load_lds_dwordx4 v137, s[6:7]
	s_add_i32 m0, s23, 0x2000
	s_add_u32 s46, s6, 0x40000
	global_load_lds_dwordx4 v139, s[6:7]
	s_addc_u32 s47, s7, 0
	s_add_i32 s23, s25, s42
	s_mov_b32 m0, s23
	s_nop 0
	global_load_lds_dwordx4 v137, s[46:47]
	s_add_i32 m0, s23, 0x2000
	s_nop 0
	global_load_lds_dwordx4 v139, s[46:47]
	s_mov_b32 m0, s60
	s_nop 0
	global_load_lds_dwordx4 v131, s[4:5]
	s_mov_b32 m0, s61
	s_nop 0
	global_load_lds_dwordx4 v133, s[4:5]
	s_waitcnt vmcnt(8)
	s_waitcnt lgkmcnt(0)
	s_setprio 1
	s_barrier
	v_mfma_f32_16x16x32_bf16 v[62:65], v[146:149], v[180:183], v[62:65]
	v_mfma_f32_16x16x32_bf16 v[58:61], v[156:159], v[180:183], v[58:61]
	v_mfma_f32_16x16x32_bf16 v[46:49], v[146:149], v[188:191], v[46:49]
	v_mfma_f32_16x16x32_bf16 v[42:45], v[156:159], v[188:191], v[42:45]
	v_mfma_f32_16x16x32_bf16 v[30:33], v[146:149], v[196:199], v[30:33]
	v_mfma_f32_16x16x32_bf16 v[26:29], v[156:159], v[196:199], v[26:29]
	v_mfma_f32_16x16x32_bf16 v[14:17], v[146:149], v[204:207], v[14:17]
	v_mfma_f32_16x16x32_bf16 v[10:13], v[156:159], v[204:207], v[10:13]
	v_mfma_f32_16x16x32_bf16 v[62:65], v[152:155], v[184:187], v[62:65]
	v_mfma_f32_16x16x32_bf16 v[58:61], v[160:163], v[184:187], v[58:61]
	v_mfma_f32_16x16x32_bf16 v[46:49], v[152:155], v[192:195], v[46:49]
	v_mfma_f32_16x16x32_bf16 v[42:45], v[160:163], v[192:195], v[42:45]
	v_mfma_f32_16x16x32_bf16 v[30:33], v[152:155], v[200:203], v[30:33]
	v_mfma_f32_16x16x32_bf16 v[26:29], v[160:163], v[200:203], v[26:29]
	v_mfma_f32_16x16x32_bf16 v[14:17], v[152:155], v[208:211], v[14:17]
	v_mfma_f32_16x16x32_bf16 v[10:13], v[160:163], v[208:211], v[10:13]
	s_setprio 0
	s_setprio 1
	v_mfma_f32_16x16x32_bf16 v[54:57], v[164:167], v[180:183], v[54:57]
	v_mfma_f32_16x16x32_bf16 v[50:53], v[172:175], v[180:183], v[50:53]
	v_mfma_f32_16x16x32_bf16 v[38:41], v[164:167], v[188:191], v[38:41]
	v_mfma_f32_16x16x32_bf16 v[34:37], v[172:175], v[188:191], v[34:37]
	v_mfma_f32_16x16x32_bf16 v[22:25], v[164:167], v[196:199], v[22:25]
	v_mfma_f32_16x16x32_bf16 v[18:21], v[172:175], v[196:199], v[18:21]
	v_mfma_f32_16x16x32_bf16 v[6:9], v[164:167], v[204:207], v[6:9]
	v_mfma_f32_16x16x32_bf16 v[2:5], v[172:175], v[204:207], v[2:5]
	v_mfma_f32_16x16x32_bf16 v[54:57], v[168:171], v[184:187], v[54:57]
	v_mfma_f32_16x16x32_bf16 v[50:53], v[176:179], v[184:187], v[50:53]
	v_mfma_f32_16x16x32_bf16 v[38:41], v[168:171], v[192:195], v[38:41]
	v_mfma_f32_16x16x32_bf16 v[34:37], v[176:179], v[192:195], v[34:37]
	v_mfma_f32_16x16x32_bf16 v[22:25], v[168:171], v[200:203], v[22:25]
	v_mfma_f32_16x16x32_bf16 v[18:21], v[176:179], v[200:203], v[18:21]
	v_mfma_f32_16x16x32_bf16 v[6:9], v[168:171], v[208:211], v[6:9]
	v_mfma_f32_16x16x32_bf16 v[2:5], v[176:179], v[208:211], v[2:5]
	s_setprio 0
	s_barrier
	s_add_i32 s23, 0, 0x18000
	s_add_i32 s25, 0, 0x1c000
	ds_read_b128 v[146:149], v0 offset:32768
	ds_read_b128 v[152:155], v0 offset:33792
	ds_read_b128 v[156:159], v0 offset:34816
	ds_read_b128 v[160:163], v0 offset:35840
	ds_read_b128 v[164:167], v0 offset:49152
	ds_read_b128 v[168:171], v0 offset:50176
	ds_read_b128 v[172:175], v0 offset:51200
	ds_read_b128 v[176:179], v0 offset:52224
	s_add_u32 s46, s4, 0x40000
	s_mov_b32 m0, s66
	ds_read_b128 v[180:183], v150 offset:32768
	ds_read_b128 v[184:187], v150 offset:33792
	ds_read_b128 v[188:191], v150 offset:34816
	ds_read_b128 v[192:195], v150 offset:35840
	ds_read_b128 v[196:199], v150 offset:36864
	ds_read_b128 v[200:203], v150 offset:37888
	ds_read_b128 v[204:207], v150 offset:38912
	ds_read_b128 v[208:211], v150 offset:39936
	s_addc_u32 s47, s5, 0
	s_nop 0
	global_load_lds_dwordx4 v131, s[46:47]
	s_mov_b32 m0, s67
	s_nop 0
	global_load_lds_dwordx4 v133, s[46:47]
	s_waitcnt vmcnt(8)
	s_waitcnt lgkmcnt(0)
	s_setprio 1
	s_barrier
	v_mfma_f32_16x16x32_bf16 v[126:129], v[146:149], v[180:183], v[126:129]
	v_mfma_f32_16x16x32_bf16 v[122:125], v[156:159], v[180:183], v[122:125]
	v_mfma_f32_16x16x32_bf16 v[110:113], v[146:149], v[188:191], v[110:113]
	v_mfma_f32_16x16x32_bf16 v[106:109], v[156:159], v[188:191], v[106:109]
	v_mfma_f32_16x16x32_bf16 v[94:97], v[146:149], v[196:199], v[94:97]
	v_mfma_f32_16x16x32_bf16 v[90:93], v[156:159], v[196:199], v[90:93]
	v_mfma_f32_16x16x32_bf16 v[78:81], v[146:149], v[204:207], v[78:81]
	v_mfma_f32_16x16x32_bf16 v[74:77], v[156:159], v[204:207], v[74:77]
	v_mfma_f32_16x16x32_bf16 v[126:129], v[152:155], v[184:187], v[126:129]
	v_mfma_f32_16x16x32_bf16 v[122:125], v[160:163], v[184:187], v[122:125]
	v_mfma_f32_16x16x32_bf16 v[110:113], v[152:155], v[192:195], v[110:113]
	v_mfma_f32_16x16x32_bf16 v[106:109], v[160:163], v[192:195], v[106:109]
	v_mfma_f32_16x16x32_bf16 v[94:97], v[152:155], v[200:203], v[94:97]
	v_mfma_f32_16x16x32_bf16 v[90:93], v[160:163], v[200:203], v[90:93]
	v_mfma_f32_16x16x32_bf16 v[78:81], v[152:155], v[208:211], v[78:81]
	v_mfma_f32_16x16x32_bf16 v[74:77], v[160:163], v[208:211], v[74:77]
	s_setprio 0
	s_setprio 1
	v_mfma_f32_16x16x32_bf16 v[118:121], v[164:167], v[180:183], v[118:121]
	v_mfma_f32_16x16x32_bf16 v[114:117], v[172:175], v[180:183], v[114:117]
	v_mfma_f32_16x16x32_bf16 v[102:105], v[164:167], v[188:191], v[102:105]
	v_mfma_f32_16x16x32_bf16 v[98:101], v[172:175], v[188:191], v[98:101]
	v_mfma_f32_16x16x32_bf16 v[86:89], v[164:167], v[196:199], v[86:89]
	v_mfma_f32_16x16x32_bf16 v[82:85], v[172:175], v[196:199], v[82:85]
	v_mfma_f32_16x16x32_bf16 v[70:73], v[164:167], v[204:207], v[70:73]
	v_mfma_f32_16x16x32_bf16 v[66:69], v[172:175], v[204:207], v[66:69]
	v_mfma_f32_16x16x32_bf16 v[118:121], v[168:171], v[184:187], v[118:121]
	v_mfma_f32_16x16x32_bf16 v[114:117], v[176:179], v[184:187], v[114:117]
	v_mfma_f32_16x16x32_bf16 v[102:105], v[168:171], v[192:195], v[102:105]
	v_mfma_f32_16x16x32_bf16 v[98:101], v[176:179], v[192:195], v[98:101]
	v_mfma_f32_16x16x32_bf16 v[86:89], v[168:171], v[200:203], v[86:89]
	v_mfma_f32_16x16x32_bf16 v[82:85], v[176:179], v[200:203], v[82:85]
	v_mfma_f32_16x16x32_bf16 v[70:73], v[168:171], v[208:211], v[70:73]
	v_mfma_f32_16x16x32_bf16 v[66:69], v[176:179], v[208:211], v[66:69]
	s_setprio 0
	s_barrier
	ds_read_b128 v[180:183], v150 offset:49152
	ds_read_b128 v[184:187], v150 offset:50176
	ds_read_b128 v[188:191], v150 offset:51200
	ds_read_b128 v[192:195], v150 offset:52224
	ds_read_b128 v[196:199], v150 offset:53248
	ds_read_b128 v[200:203], v150 offset:54272
	ds_read_b128 v[204:207], v150 offset:55296
	ds_read_b128 v[208:211], v150 offset:56320
	s_add_i32 s23, s23, s42
	s_add_u32 s100, s6, s38
	s_addc_u32 s101, s7, s39
	s_mov_b32 m0, s23
	s_nop 0
	global_load_lds_dwordx4 v137, s[100:101]
	s_add_i32 m0, s23, 0x2000
	s_nop 0
	s_add_u32 s6, s6, 0x40080
	s_addc_u32 s7, s7, 0
	s_add_i32 s23, s25, s42
	global_load_lds_dwordx4 v139, s[100:101]
	s_mov_b32 m0, s23
	s_nop 0
	global_load_lds_dwordx4 v137, s[6:7]
	s_add_i32 m0, s23, 0x2000
	s_nop 0
	global_load_lds_dwordx4 v139, s[6:7]
	s_mov_b32 m0, s70
	s_add_u32 s100, s4, s38
	s_addc_u32 s101, s5, s39
	v_mov_b32_e32 v0, v133
	global_load_lds_dwordx4 v131, s[100:101]
	s_mov_b32 m0, s71
	s_nop 0
	global_load_lds_dwordx4 v133, s[100:101]
	s_waitcnt vmcnt(8)
	s_waitcnt lgkmcnt(0)
	s_setprio 1
	s_barrier
	v_mfma_f32_16x16x32_bf16 v[62:65], v[146:149], v[180:183], v[62:65]
	v_mfma_f32_16x16x32_bf16 v[58:61], v[156:159], v[180:183], v[58:61]
	v_mfma_f32_16x16x32_bf16 v[46:49], v[146:149], v[188:191], v[46:49]
	v_mfma_f32_16x16x32_bf16 v[42:45], v[156:159], v[188:191], v[42:45]
	v_mfma_f32_16x16x32_bf16 v[30:33], v[146:149], v[196:199], v[30:33]
	v_mfma_f32_16x16x32_bf16 v[26:29], v[156:159], v[196:199], v[26:29]
	v_mfma_f32_16x16x32_bf16 v[14:17], v[146:149], v[204:207], v[14:17]
	v_mfma_f32_16x16x32_bf16 v[10:13], v[156:159], v[204:207], v[10:13]
	v_mfma_f32_16x16x32_bf16 v[62:65], v[152:155], v[184:187], v[62:65]
	v_mfma_f32_16x16x32_bf16 v[58:61], v[160:163], v[184:187], v[58:61]
	v_mfma_f32_16x16x32_bf16 v[46:49], v[152:155], v[192:195], v[46:49]
	v_mfma_f32_16x16x32_bf16 v[42:45], v[160:163], v[192:195], v[42:45]
	v_mfma_f32_16x16x32_bf16 v[30:33], v[152:155], v[200:203], v[30:33]
	v_mfma_f32_16x16x32_bf16 v[26:29], v[160:163], v[200:203], v[26:29]
	v_mfma_f32_16x16x32_bf16 v[14:17], v[152:155], v[208:211], v[14:17]
	v_mfma_f32_16x16x32_bf16 v[10:13], v[160:163], v[208:211], v[10:13]
	s_setprio 0
	s_setprio 1
	v_mfma_f32_16x16x32_bf16 v[54:57], v[164:167], v[180:183], v[54:57]
	v_mfma_f32_16x16x32_bf16 v[50:53], v[172:175], v[180:183], v[50:53]
	v_mfma_f32_16x16x32_bf16 v[38:41], v[164:167], v[188:191], v[38:41]
	v_mfma_f32_16x16x32_bf16 v[34:37], v[172:175], v[188:191], v[34:37]
	v_mfma_f32_16x16x32_bf16 v[22:25], v[164:167], v[196:199], v[22:25]
	v_mfma_f32_16x16x32_bf16 v[18:21], v[172:175], v[196:199], v[18:21]
	v_mfma_f32_16x16x32_bf16 v[6:9], v[164:167], v[204:207], v[6:9]
	v_mfma_f32_16x16x32_bf16 v[2:5], v[172:175], v[204:207], v[2:5]
	v_mfma_f32_16x16x32_bf16 v[54:57], v[168:171], v[184:187], v[54:57]
	v_mfma_f32_16x16x32_bf16 v[50:53], v[176:179], v[184:187], v[50:53]
	v_mfma_f32_16x16x32_bf16 v[38:41], v[168:171], v[192:195], v[38:41]
	v_mfma_f32_16x16x32_bf16 v[34:37], v[176:179], v[192:195], v[34:37]
	v_mfma_f32_16x16x32_bf16 v[22:25], v[168:171], v[200:203], v[22:25]
	v_mfma_f32_16x16x32_bf16 v[18:21], v[176:179], v[200:203], v[18:21]
	v_mfma_f32_16x16x32_bf16 v[6:9], v[168:171], v[208:211], v[6:9]
	v_mfma_f32_16x16x32_bf16 v[2:5], v[176:179], v[208:211], v[2:5]
	s_setprio 0
	s_barrier
	s_add_i32 s22, s22, 2
	s_add_u32 s2, s2, 0x100
	s_addc_u32 s3, s3, 0
	s_add_u32 s8, s8, 0x100
	s_addc_u32 s9, s9, 0
	s_cmp_gt_u32 s22, 13
	s_cbranch_scc0 .LBB0_1088

.LBB0_1473:
	s_add_u32 s16, s4, s14
	s_addc_u32 s17, s5, s15
	s_add_u32 s22, s16, 0x100
	s_addc_u32 s23, s17, 0
	s_and_b64 s[10:11], s[12:13], exec
	s_cselect_b32 s11, s5, s23
	s_cselect_b32 s10, s4, s22
	s_add_u32 s14, s6, s14
	s_addc_u32 s15, s7, s15
	s_add_u32 s14, s14, 0x100
	s_addc_u32 s15, s15, 0
	s_add_i32 s69, 0, 0x10000
	s_and_b64 s[12:13], s[12:13], exec
	s_cselect_b32 s13, s7, s15
	s_cselect_b32 s12, s6, s14
	s_add_i32 s15, 0, 0x14000
	s_add_u32 s46, s16, 0x80080
	s_addc_u32 s47, s17, 0
	s_add_i32 s71, s69, s41
	s_add_i32 m0, s42, 0xc000
	s_add_i32 s74, s42, 0xe000
	s_add_i32 s67, s71, 0x2000
	v_add_u32_e32 v0, s69, v136
	s_add_u32 s22, s12, 0x40000
	ds_read_b128 v[138:141], v0
	ds_read_b128 v[142:145], v0 offset:1024
	ds_read_b128 v[146:149], v0 offset:2048
	ds_read_b128 v[150:153], v0 offset:3072
	s_addc_u32 s23, s13, 0
	s_add_i32 s68, s15, s41
	ds_read_b128 v[154:157], v0 offset:16384
	ds_read_b128 v[158:161], v0 offset:17408
	ds_read_b128 v[162:165], v0 offset:18432
	ds_read_b128 v[166:169], v0 offset:19456
	s_add_i32 s66, s68, 0x2000
	s_add_i32 s65, 0, 0x18000
	s_add_i32 s64, 0, 0x1c000
	s_add_u32 s16, s10, 0x80000
	s_addc_u32 s17, s11, 0
	s_add_i32 s61, s65, s41
	s_add_i32 s60, s61, 0x2000
	s_add_u32 s14, s12, 0x40080
	s_addc_u32 s15, s13, 0
	s_add_i32 s70, s64, s41
	s_add_i32 s69, s70, 0x2000
	ds_read_b128 v[170:173], v137
	ds_read_b128 v[174:177], v137 offset:1024
	ds_read_b128 v[178:181], v137 offset:2048
	ds_read_b128 v[182:185], v137 offset:3072
	ds_read_b128 v[186:189], v137 offset:4096
	ds_read_b128 v[190:193], v137 offset:5120
	ds_read_b128 v[194:197], v137 offset:6144
	ds_read_b128 v[198:201], v137 offset:7168
	s_nop 0
	global_load_lds_dwordx4 v130, s[46:47]
	s_mov_b32 m0, s74
	s_nop 0
	global_load_lds_dwordx4 v132, s[46:47]
	s_waitcnt vmcnt(8)
	s_waitcnt lgkmcnt(0)
	s_setprio 1
	s_barrier
	v_mfma_f32_16x16x32_bf16 v[126:129], v[138:141], v[170:173], v[126:129]
	v_mfma_f32_16x16x32_bf16 v[122:125], v[146:149], v[170:173], v[122:125]
	v_mfma_f32_16x16x32_bf16 v[118:121], v[138:141], v[178:181], v[118:121]
	v_mfma_f32_16x16x32_bf16 v[110:113], v[146:149], v[178:181], v[110:113]
	v_mfma_f32_16x16x32_bf16 v[102:105], v[138:141], v[186:189], v[102:105]
	v_mfma_f32_16x16x32_bf16 v[94:97], v[146:149], v[186:189], v[94:97]
	v_mfma_f32_16x16x32_bf16 v[86:89], v[138:141], v[194:197], v[86:89]
	v_mfma_f32_16x16x32_bf16 v[78:81], v[146:149], v[194:197], v[78:81]
	v_mfma_f32_16x16x32_bf16 v[126:129], v[142:145], v[174:177], v[126:129]
	v_mfma_f32_16x16x32_bf16 v[122:125], v[150:153], v[174:177], v[122:125]
	v_mfma_f32_16x16x32_bf16 v[118:121], v[142:145], v[182:185], v[118:121]
	v_mfma_f32_16x16x32_bf16 v[110:113], v[150:153], v[182:185], v[110:113]
	v_mfma_f32_16x16x32_bf16 v[102:105], v[142:145], v[190:193], v[102:105]
	v_mfma_f32_16x16x32_bf16 v[94:97], v[150:153], v[190:193], v[94:97]
	v_mfma_f32_16x16x32_bf16 v[86:89], v[142:145], v[198:201], v[86:89]
	v_mfma_f32_16x16x32_bf16 v[78:81], v[150:153], v[198:201], v[78:81]
	s_setprio 0
	s_setprio 1
	v_mfma_f32_16x16x32_bf16 v[114:117], v[154:157], v[170:173], v[114:117]
	v_mfma_f32_16x16x32_bf16 v[106:109], v[162:165], v[170:173], v[106:109]
	v_mfma_f32_16x16x32_bf16 v[98:101], v[154:157], v[178:181], v[98:101]
	v_mfma_f32_16x16x32_bf16 v[90:93], v[162:165], v[178:181], v[90:93]
	v_mfma_f32_16x16x32_bf16 v[82:85], v[154:157], v[186:189], v[82:85]
	v_mfma_f32_16x16x32_bf16 v[74:77], v[162:165], v[186:189], v[74:77]
	v_mfma_f32_16x16x32_bf16 v[70:73], v[154:157], v[194:197], v[70:73]
	v_mfma_f32_16x16x32_bf16 v[62:65], v[162:165], v[194:197], v[62:65]
	v_mfma_f32_16x16x32_bf16 v[114:117], v[158:161], v[174:177], v[114:117]
	v_mfma_f32_16x16x32_bf16 v[106:109], v[166:169], v[174:177], v[106:109]
	v_mfma_f32_16x16x32_bf16 v[98:101], v[158:161], v[182:185], v[98:101]
	v_mfma_f32_16x16x32_bf16 v[90:93], v[166:169], v[182:185], v[90:93]
	v_mfma_f32_16x16x32_bf16 v[82:85], v[158:161], v[190:193], v[82:85]
	v_mfma_f32_16x16x32_bf16 v[74:77], v[166:169], v[190:193], v[74:77]
	v_mfma_f32_16x16x32_bf16 v[70:73], v[158:161], v[198:201], v[70:73]
	v_mfma_f32_16x16x32_bf16 v[62:65], v[166:169], v[198:201], v[62:65]
	s_setprio 0
	s_barrier
	s_mov_b32 m0, s71
	ds_read_b128 v[170:173], v137 offset:16384
	ds_read_b128 v[174:177], v137 offset:17408
	ds_read_b128 v[178:181], v137 offset:18432
	ds_read_b128 v[182:185], v137 offset:19456
	ds_read_b128 v[186:189], v137 offset:20480
	ds_read_b128 v[190:193], v137 offset:21504
	ds_read_b128 v[194:197], v137 offset:22528
	ds_read_b128 v[198:201], v137 offset:23552
	s_nop 0
	global_load_lds_dwordx4 v131, s[12:13]
	s_mov_b32 m0, s67
	s_nop 0
	global_load_lds_dwordx4 v133, s[12:13]
	s_mov_b32 m0, s68
	s_nop 0
	global_load_lds_dwordx4 v131, s[22:23]
	s_mov_b32 m0, s66
	s_nop 0
	global_load_lds_dwordx4 v133, s[22:23]
	s_mov_b32 m0, s42
	s_nop 0
	global_load_lds_dwordx4 v130, s[10:11]
	s_mov_b32 m0, s43
	s_nop 0
	global_load_lds_dwordx4 v132, s[10:11]
	s_waitcnt vmcnt(8)
	s_waitcnt lgkmcnt(0)
	s_setprio 1
	s_barrier
	v_mfma_f32_16x16x32_bf16 v[66:69], v[138:141], v[170:173], v[66:69]
	v_mfma_f32_16x16x32_bf16 v[58:61], v[146:149], v[170:173], v[58:61]
	v_mfma_f32_16x16x32_bf16 v[54:57], v[138:141], v[178:181], v[54:57]
	v_mfma_f32_16x16x32_bf16 v[46:49], v[146:149], v[178:181], v[46:49]
	v_mfma_f32_16x16x32_bf16 v[38:41], v[138:141], v[186:189], v[38:41]
	v_mfma_f32_16x16x32_bf16 v[30:33], v[146:149], v[186:189], v[30:33]
	v_mfma_f32_16x16x32_bf16 v[22:25], v[138:141], v[194:197], v[22:25]
	v_mfma_f32_16x16x32_bf16 v[14:17], v[146:149], v[194:197], v[14:17]
	v_mfma_f32_16x16x32_bf16 v[66:69], v[142:145], v[174:177], v[66:69]
	v_mfma_f32_16x16x32_bf16 v[58:61], v[150:153], v[174:177], v[58:61]
	v_mfma_f32_16x16x32_bf16 v[54:57], v[142:145], v[182:185], v[54:57]
	v_mfma_f32_16x16x32_bf16 v[46:49], v[150:153], v[182:185], v[46:49]
	v_mfma_f32_16x16x32_bf16 v[38:41], v[142:145], v[190:193], v[38:41]
	v_mfma_f32_16x16x32_bf16 v[30:33], v[150:153], v[190:193], v[30:33]
	v_mfma_f32_16x16x32_bf16 v[22:25], v[142:145], v[198:201], v[22:25]
	v_mfma_f32_16x16x32_bf16 v[14:17], v[150:153], v[198:201], v[14:17]
	s_setprio 0
	s_setprio 1
	v_mfma_f32_16x16x32_bf16 v[50:53], v[154:157], v[170:173], v[50:53]
	v_mfma_f32_16x16x32_bf16 v[42:45], v[162:165], v[170:173], v[42:45]
	v_mfma_f32_16x16x32_bf16 v[34:37], v[154:157], v[178:181], v[34:37]
	v_mfma_f32_16x16x32_bf16 v[26:29], v[162:165], v[178:181], v[26:29]
	v_mfma_f32_16x16x32_bf16 v[18:21], v[154:157], v[186:189], v[18:21]
	v_mfma_f32_16x16x32_bf16 v[10:13], v[162:165], v[186:189], v[10:13]
	v_mfma_f32_16x16x32_bf16 v[6:9], v[154:157], v[194:197], v[6:9]
	v_mfma_f32_16x16x32_bf16 v[2:5], v[162:165], v[194:197], v[2:5]
	v_mfma_f32_16x16x32_bf16 v[50:53], v[158:161], v[174:177], v[50:53]
	v_mfma_f32_16x16x32_bf16 v[42:45], v[166:169], v[174:177], v[42:45]
	v_mfma_f32_16x16x32_bf16 v[34:37], v[158:161], v[182:185], v[34:37]
	v_mfma_f32_16x16x32_bf16 v[26:29], v[166:169], v[182:185], v[26:29]
	v_mfma_f32_16x16x32_bf16 v[18:21], v[158:161], v[190:193], v[18:21]
	v_mfma_f32_16x16x32_bf16 v[10:13], v[166:169], v[190:193], v[10:13]
	v_mfma_f32_16x16x32_bf16 v[6:9], v[158:161], v[198:201], v[6:9]
	v_mfma_f32_16x16x32_bf16 v[2:5], v[166:169], v[198:201], v[2:5]
	s_setprio 0
	s_barrier
	ds_read_b128 v[138:141], v0 offset:32768
	ds_read_b128 v[142:145], v0 offset:33792
	ds_read_b128 v[146:149], v0 offset:34816
	ds_read_b128 v[150:153], v0 offset:35840
	ds_read_b128 v[154:157], v0 offset:49152
	ds_read_b128 v[158:161], v0 offset:50176
	ds_read_b128 v[162:165], v0 offset:51200
	ds_read_b128 v[166:169], v0 offset:52224
	s_mov_b32 m0, s50
	ds_read_b128 v[170:173], v137 offset:32768
	ds_read_b128 v[174:177], v137 offset:33792
	ds_read_b128 v[178:181], v137 offset:34816
	ds_read_b128 v[182:185], v137 offset:35840
	ds_read_b128 v[186:189], v137 offset:36864
	ds_read_b128 v[190:193], v137 offset:37888
	ds_read_b128 v[194:197], v137 offset:38912
	ds_read_b128 v[198:201], v137 offset:39936
	s_nop 0
	global_load_lds_dwordx4 v130, s[16:17]
	s_mov_b32 m0, s51
	s_nop 0
	global_load_lds_dwordx4 v132, s[16:17]
	s_waitcnt vmcnt(8)
	s_waitcnt lgkmcnt(0)
	s_setprio 1
	s_barrier
	v_mfma_f32_16x16x32_bf16 v[126:129], v[138:141], v[170:173], v[126:129]
	v_mfma_f32_16x16x32_bf16 v[122:125], v[146:149], v[170:173], v[122:125]
	v_mfma_f32_16x16x32_bf16 v[118:121], v[138:141], v[178:181], v[118:121]
	v_mfma_f32_16x16x32_bf16 v[110:113], v[146:149], v[178:181], v[110:113]
	v_mfma_f32_16x16x32_bf16 v[102:105], v[138:141], v[186:189], v[102:105]
	v_mfma_f32_16x16x32_bf16 v[94:97], v[146:149], v[186:189], v[94:97]
	v_mfma_f32_16x16x32_bf16 v[86:89], v[138:141], v[194:197], v[86:89]
	v_mfma_f32_16x16x32_bf16 v[78:81], v[146:149], v[194:197], v[78:81]
	v_mfma_f32_16x16x32_bf16 v[126:129], v[142:145], v[174:177], v[126:129]
	v_mfma_f32_16x16x32_bf16 v[122:125], v[150:153], v[174:177], v[122:125]
	v_mfma_f32_16x16x32_bf16 v[118:121], v[142:145], v[182:185], v[118:121]
	v_mfma_f32_16x16x32_bf16 v[110:113], v[150:153], v[182:185], v[110:113]
	v_mfma_f32_16x16x32_bf16 v[102:105], v[142:145], v[190:193], v[102:105]
	v_mfma_f32_16x16x32_bf16 v[94:97], v[150:153], v[190:193], v[94:97]
	v_mfma_f32_16x16x32_bf16 v[86:89], v[142:145], v[198:201], v[86:89]
	v_mfma_f32_16x16x32_bf16 v[78:81], v[150:153], v[198:201], v[78:81]
	s_setprio 0
	s_setprio 1
	v_mfma_f32_16x16x32_bf16 v[114:117], v[154:157], v[170:173], v[114:117]
	v_mfma_f32_16x16x32_bf16 v[106:109], v[162:165], v[170:173], v[106:109]
	v_mfma_f32_16x16x32_bf16 v[98:101], v[154:157], v[178:181], v[98:101]
	v_mfma_f32_16x16x32_bf16 v[90:93], v[162:165], v[178:181], v[90:93]
	v_mfma_f32_16x16x32_bf16 v[82:85], v[154:157], v[186:189], v[82:85]
	v_mfma_f32_16x16x32_bf16 v[74:77], v[162:165], v[186:189], v[74:77]
	v_mfma_f32_16x16x32_bf16 v[70:73], v[154:157], v[194:197], v[70:73]
	v_mfma_f32_16x16x32_bf16 v[62:65], v[162:165], v[194:197], v[62:65]
	v_mfma_f32_16x16x32_bf16 v[114:117], v[158:161], v[174:177], v[114:117]
	v_mfma_f32_16x16x32_bf16 v[106:109], v[166:169], v[174:177], v[106:109]
	v_mfma_f32_16x16x32_bf16 v[98:101], v[158:161], v[182:185], v[98:101]
	v_mfma_f32_16x16x32_bf16 v[90:93], v[166:169], v[182:185], v[90:93]
	v_mfma_f32_16x16x32_bf16 v[82:85], v[158:161], v[190:193], v[82:85]
	v_mfma_f32_16x16x32_bf16 v[74:77], v[166:169], v[190:193], v[74:77]
	v_mfma_f32_16x16x32_bf16 v[70:73], v[158:161], v[198:201], v[70:73]
	v_mfma_f32_16x16x32_bf16 v[62:65], v[166:169], v[198:201], v[62:65]
	s_setprio 0
	s_barrier
	ds_read_b128 v[170:173], v137 offset:49152
	ds_read_b128 v[174:177], v137 offset:50176
	ds_read_b128 v[178:181], v137 offset:51200
	ds_read_b128 v[182:185], v137 offset:52224
	ds_read_b128 v[186:189], v137 offset:53248
	ds_read_b128 v[190:193], v137 offset:54272
	ds_read_b128 v[194:197], v137 offset:55296
	ds_read_b128 v[198:201], v137 offset:56320
	s_mov_b32 m0, s61
	s_add_u32 s100, s12, s38
	s_addc_u32 s101, s13, s39
	global_load_lds_dwordx4 v131, s[100:101]
	s_mov_b32 m0, s60
	s_nop 0
	global_load_lds_dwordx4 v133, s[100:101]
	s_mov_b32 m0, s70
	s_nop 0
	global_load_lds_dwordx4 v131, s[14:15]
	s_mov_b32 m0, s69
	s_nop 0
	global_load_lds_dwordx4 v133, s[14:15]
	s_mov_b32 m0, s58
	s_add_u32 s100, s10, s38
	s_addc_u32 s101, s11, s39
	v_mov_b32_e32 v0, v132
	global_load_lds_dwordx4 v130, s[100:101]
	s_mov_b32 m0, s59
	s_nop 0
	global_load_lds_dwordx4 v132, s[100:101]
	s_waitcnt vmcnt(8)
	s_waitcnt lgkmcnt(0)
	s_setprio 1
	s_barrier
	v_mfma_f32_16x16x32_bf16 v[66:69], v[138:141], v[170:173], v[66:69]
	v_mfma_f32_16x16x32_bf16 v[58:61], v[146:149], v[170:173], v[58:61]
	v_mfma_f32_16x16x32_bf16 v[54:57], v[138:141], v[178:181], v[54:57]
	v_mfma_f32_16x16x32_bf16 v[46:49], v[146:149], v[178:181], v[46:49]
	v_mfma_f32_16x16x32_bf16 v[38:41], v[138:141], v[186:189], v[38:41]
	v_mfma_f32_16x16x32_bf16 v[30:33], v[146:149], v[186:189], v[30:33]
	v_mfma_f32_16x16x32_bf16 v[22:25], v[138:141], v[194:197], v[22:25]
	v_mfma_f32_16x16x32_bf16 v[14:17], v[146:149], v[194:197], v[14:17]
	v_mfma_f32_16x16x32_bf16 v[66:69], v[142:145], v[174:177], v[66:69]
	v_mfma_f32_16x16x32_bf16 v[58:61], v[150:153], v[174:177], v[58:61]
	v_mfma_f32_16x16x32_bf16 v[54:57], v[142:145], v[182:185], v[54:57]
	v_mfma_f32_16x16x32_bf16 v[46:49], v[150:153], v[182:185], v[46:49]
	v_mfma_f32_16x16x32_bf16 v[38:41], v[142:145], v[190:193], v[38:41]
	v_mfma_f32_16x16x32_bf16 v[30:33], v[150:153], v[190:193], v[30:33]
	v_mfma_f32_16x16x32_bf16 v[22:25], v[142:145], v[198:201], v[22:25]
	v_mfma_f32_16x16x32_bf16 v[14:17], v[150:153], v[198:201], v[14:17]
	s_setprio 0
	s_setprio 1
	v_mfma_f32_16x16x32_bf16 v[50:53], v[154:157], v[170:173], v[50:53]
	v_mfma_f32_16x16x32_bf16 v[42:45], v[162:165], v[170:173], v[42:45]
	v_mfma_f32_16x16x32_bf16 v[34:37], v[154:157], v[178:181], v[34:37]
	v_mfma_f32_16x16x32_bf16 v[26:29], v[162:165], v[178:181], v[26:29]
	v_mfma_f32_16x16x32_bf16 v[18:21], v[154:157], v[186:189], v[18:21]
	v_mfma_f32_16x16x32_bf16 v[10:13], v[162:165], v[186:189], v[10:13]
	v_mfma_f32_16x16x32_bf16 v[6:9], v[154:157], v[194:197], v[6:9]
	v_mfma_f32_16x16x32_bf16 v[2:5], v[162:165], v[194:197], v[2:5]
	v_mfma_f32_16x16x32_bf16 v[50:53], v[158:161], v[174:177], v[50:53]
	v_mfma_f32_16x16x32_bf16 v[42:45], v[166:169], v[174:177], v[42:45]
	v_mfma_f32_16x16x32_bf16 v[34:37], v[158:161], v[182:185], v[34:37]
	v_mfma_f32_16x16x32_bf16 v[26:29], v[166:169], v[182:185], v[26:29]
	v_mfma_f32_16x16x32_bf16 v[18:21], v[158:161], v[190:193], v[18:21]
	v_mfma_f32_16x16x32_bf16 v[10:13], v[166:169], v[190:193], v[10:13]
	v_mfma_f32_16x16x32_bf16 v[6:9], v[158:161], v[198:201], v[6:9]
	v_mfma_f32_16x16x32_bf16 v[2:5], v[166:169], v[198:201], v[2:5]
	s_setprio 0
	s_barrier
	s_andn2_b64 vcc, exec, s[8:9]
	s_mov_b64 s[12:13], -1
	s_mov_b64 s[8:9], 0
	s_mov_b64 s[14:15], 0x100
	s_cbranch_vccz .LBB0_1473
	s_cmpk_lt_u32 s24, 0x100
	s_cbranch_scc0 .LBB0_1476
	s_barrier

.LBB0_1481:
	s_add_u32 s16, s4, s14
	s_addc_u32 s17, s5, s15
	s_add_u32 s22, s16, 0x100
	s_addc_u32 s23, s17, 0
	s_and_b64 s[10:11], s[12:13], exec
	s_cselect_b32 s11, s5, s23
	s_cselect_b32 s10, s4, s22
	s_add_u32 s14, s6, s14
	s_addc_u32 s15, s7, s15
	s_add_u32 s14, s14, 0x900
	s_addc_u32 s15, s15, 0
	s_add_i32 s70, 0, 0x10000
	s_and_b64 s[12:13], s[12:13], exec
	s_cselect_b32 s13, s58, s15
	s_cselect_b32 s12, s51, s14
	s_add_i32 s15, 0, 0x14000
	s_add_u32 s46, s16, 0x40080
	s_addc_u32 s47, s17, 0
	s_add_i32 s74, s70, s40
	s_add_i32 m0, s41, 0xc000
	s_add_i32 s75, s41, 0xe000
	s_add_i32 s68, s74, 0x2000
	v_add_u32_e32 v0, s70, v136
	s_add_u32 s22, s12, 0x80000
	ds_read_b128 v[138:141], v0
	ds_read_b128 v[142:145], v0 offset:1024
	ds_read_b128 v[146:149], v0 offset:2048
	ds_read_b128 v[150:153], v0 offset:3072
	s_addc_u32 s23, s13, 0
	s_add_i32 s69, s15, s40
	ds_read_b128 v[154:157], v0 offset:16384
	ds_read_b128 v[158:161], v0 offset:17408
	ds_read_b128 v[162:165], v0 offset:18432
	ds_read_b128 v[166:169], v0 offset:19456
	s_add_i32 s67, s69, 0x2000
	s_add_i32 s66, 0, 0x18000
	s_add_i32 s65, 0, 0x1c000
	s_add_u32 s16, s10, 0x40000
	s_addc_u32 s17, s11, 0
	s_add_i32 s64, s66, s40
	s_add_i32 s61, s64, 0x2000
	s_add_u32 s14, s12, 0x80080
	s_addc_u32 s15, s13, 0
	s_add_i32 s71, s65, s40
	s_add_i32 s70, s71, 0x2000
	ds_read_b128 v[170:173], v137
	ds_read_b128 v[174:177], v137 offset:1024
	ds_read_b128 v[178:181], v137 offset:2048
	ds_read_b128 v[182:185], v137 offset:3072
	ds_read_b128 v[186:189], v137 offset:4096
	ds_read_b128 v[190:193], v137 offset:5120
	ds_read_b128 v[194:197], v137 offset:6144
	ds_read_b128 v[198:201], v137 offset:7168
	s_nop 0
	global_load_lds_dwordx4 v130, s[46:47]
	s_mov_b32 m0, s75
	s_nop 0
	global_load_lds_dwordx4 v132, s[46:47]
	s_waitcnt vmcnt(8)
	s_waitcnt lgkmcnt(0)
	s_setprio 1
	s_barrier
	v_mfma_f32_16x16x32_bf16 v[126:129], v[138:141], v[170:173], v[126:129]
	v_mfma_f32_16x16x32_bf16 v[122:125], v[146:149], v[170:173], v[122:125]
	v_mfma_f32_16x16x32_bf16 v[118:121], v[138:141], v[178:181], v[118:121]
	v_mfma_f32_16x16x32_bf16 v[110:113], v[146:149], v[178:181], v[110:113]
	v_mfma_f32_16x16x32_bf16 v[102:105], v[138:141], v[186:189], v[102:105]
	v_mfma_f32_16x16x32_bf16 v[94:97], v[146:149], v[186:189], v[94:97]
	v_mfma_f32_16x16x32_bf16 v[86:89], v[138:141], v[194:197], v[86:89]
	v_mfma_f32_16x16x32_bf16 v[78:81], v[146:149], v[194:197], v[78:81]
	v_mfma_f32_16x16x32_bf16 v[126:129], v[142:145], v[174:177], v[126:129]
	v_mfma_f32_16x16x32_bf16 v[122:125], v[150:153], v[174:177], v[122:125]
	v_mfma_f32_16x16x32_bf16 v[118:121], v[142:145], v[182:185], v[118:121]
	v_mfma_f32_16x16x32_bf16 v[110:113], v[150:153], v[182:185], v[110:113]
	v_mfma_f32_16x16x32_bf16 v[102:105], v[142:145], v[190:193], v[102:105]
	v_mfma_f32_16x16x32_bf16 v[94:97], v[150:153], v[190:193], v[94:97]
	v_mfma_f32_16x16x32_bf16 v[86:89], v[142:145], v[198:201], v[86:89]
	v_mfma_f32_16x16x32_bf16 v[78:81], v[150:153], v[198:201], v[78:81]
	s_setprio 0
	s_setprio 1
	v_mfma_f32_16x16x32_bf16 v[114:117], v[154:157], v[170:173], v[114:117]
	v_mfma_f32_16x16x32_bf16 v[106:109], v[162:165], v[170:173], v[106:109]
	v_mfma_f32_16x16x32_bf16 v[98:101], v[154:157], v[178:181], v[98:101]
	v_mfma_f32_16x16x32_bf16 v[90:93], v[162:165], v[178:181], v[90:93]
	v_mfma_f32_16x16x32_bf16 v[82:85], v[154:157], v[186:189], v[82:85]
	v_mfma_f32_16x16x32_bf16 v[74:77], v[162:165], v[186:189], v[74:77]
	v_mfma_f32_16x16x32_bf16 v[70:73], v[154:157], v[194:197], v[70:73]
	v_mfma_f32_16x16x32_bf16 v[62:65], v[162:165], v[194:197], v[62:65]
	v_mfma_f32_16x16x32_bf16 v[114:117], v[158:161], v[174:177], v[114:117]
	v_mfma_f32_16x16x32_bf16 v[106:109], v[166:169], v[174:177], v[106:109]
	v_mfma_f32_16x16x32_bf16 v[98:101], v[158:161], v[182:185], v[98:101]
	v_mfma_f32_16x16x32_bf16 v[90:93], v[166:169], v[182:185], v[90:93]
	v_mfma_f32_16x16x32_bf16 v[82:85], v[158:161], v[190:193], v[82:85]
	v_mfma_f32_16x16x32_bf16 v[74:77], v[166:169], v[190:193], v[74:77]
	v_mfma_f32_16x16x32_bf16 v[70:73], v[158:161], v[198:201], v[70:73]
	v_mfma_f32_16x16x32_bf16 v[62:65], v[166:169], v[198:201], v[62:65]
	s_setprio 0
	s_barrier
	s_mov_b32 m0, s74
	ds_read_b128 v[170:173], v137 offset:16384
	ds_read_b128 v[174:177], v137 offset:17408
	ds_read_b128 v[178:181], v137 offset:18432
	ds_read_b128 v[182:185], v137 offset:19456
	ds_read_b128 v[186:189], v137 offset:20480
	ds_read_b128 v[190:193], v137 offset:21504
	ds_read_b128 v[194:197], v137 offset:22528
	ds_read_b128 v[198:201], v137 offset:23552
	s_nop 0
	global_load_lds_dwordx4 v131, s[12:13]
	s_mov_b32 m0, s68
	s_nop 0
	global_load_lds_dwordx4 v133, s[12:13]
	s_mov_b32 m0, s69
	s_nop 0
	global_load_lds_dwordx4 v131, s[22:23]
	s_mov_b32 m0, s67
	s_nop 0
	global_load_lds_dwordx4 v133, s[22:23]
	s_mov_b32 m0, s41
	s_nop 0
	global_load_lds_dwordx4 v130, s[10:11]
	s_mov_b32 m0, s42
	s_nop 0
	global_load_lds_dwordx4 v132, s[10:11]
	s_waitcnt vmcnt(8)
	s_waitcnt lgkmcnt(0)
	s_setprio 1
	s_barrier
	v_mfma_f32_16x16x32_bf16 v[66:69], v[138:141], v[170:173], v[66:69]
	v_mfma_f32_16x16x32_bf16 v[58:61], v[146:149], v[170:173], v[58:61]
	v_mfma_f32_16x16x32_bf16 v[54:57], v[138:141], v[178:181], v[54:57]
	v_mfma_f32_16x16x32_bf16 v[46:49], v[146:149], v[178:181], v[46:49]
	v_mfma_f32_16x16x32_bf16 v[38:41], v[138:141], v[186:189], v[38:41]
	v_mfma_f32_16x16x32_bf16 v[30:33], v[146:149], v[186:189], v[30:33]
	v_mfma_f32_16x16x32_bf16 v[22:25], v[138:141], v[194:197], v[22:25]
	v_mfma_f32_16x16x32_bf16 v[14:17], v[146:149], v[194:197], v[14:17]
	v_mfma_f32_16x16x32_bf16 v[66:69], v[142:145], v[174:177], v[66:69]
	v_mfma_f32_16x16x32_bf16 v[58:61], v[150:153], v[174:177], v[58:61]
	v_mfma_f32_16x16x32_bf16 v[54:57], v[142:145], v[182:185], v[54:57]
	v_mfma_f32_16x16x32_bf16 v[46:49], v[150:153], v[182:185], v[46:49]
	v_mfma_f32_16x16x32_bf16 v[38:41], v[142:145], v[190:193], v[38:41]
	v_mfma_f32_16x16x32_bf16 v[30:33], v[150:153], v[190:193], v[30:33]
	v_mfma_f32_16x16x32_bf16 v[22:25], v[142:145], v[198:201], v[22:25]
	v_mfma_f32_16x16x32_bf16 v[14:17], v[150:153], v[198:201], v[14:17]
	s_setprio 0
	s_setprio 1
	v_mfma_f32_16x16x32_bf16 v[50:53], v[154:157], v[170:173], v[50:53]
	v_mfma_f32_16x16x32_bf16 v[42:45], v[162:165], v[170:173], v[42:45]
	v_mfma_f32_16x16x32_bf16 v[34:37], v[154:157], v[178:181], v[34:37]
	v_mfma_f32_16x16x32_bf16 v[26:29], v[162:165], v[178:181], v[26:29]
	v_mfma_f32_16x16x32_bf16 v[18:21], v[154:157], v[186:189], v[18:21]
	v_mfma_f32_16x16x32_bf16 v[10:13], v[162:165], v[186:189], v[10:13]
	v_mfma_f32_16x16x32_bf16 v[6:9], v[154:157], v[194:197], v[6:9]
	v_mfma_f32_16x16x32_bf16 v[2:5], v[162:165], v[194:197], v[2:5]
	v_mfma_f32_16x16x32_bf16 v[50:53], v[158:161], v[174:177], v[50:53]
	v_mfma_f32_16x16x32_bf16 v[42:45], v[166:169], v[174:177], v[42:45]
	v_mfma_f32_16x16x32_bf16 v[34:37], v[158:161], v[182:185], v[34:37]
	v_mfma_f32_16x16x32_bf16 v[26:29], v[166:169], v[182:185], v[26:29]
	v_mfma_f32_16x16x32_bf16 v[18:21], v[158:161], v[190:193], v[18:21]
	v_mfma_f32_16x16x32_bf16 v[10:13], v[166:169], v[190:193], v[10:13]
	v_mfma_f32_16x16x32_bf16 v[6:9], v[158:161], v[198:201], v[6:9]
	v_mfma_f32_16x16x32_bf16 v[2:5], v[166:169], v[198:201], v[2:5]
	s_setprio 0
	s_barrier
	ds_read_b128 v[138:141], v0 offset:32768
	ds_read_b128 v[142:145], v0 offset:33792
	ds_read_b128 v[146:149], v0 offset:34816
	ds_read_b128 v[150:153], v0 offset:35840
	ds_read_b128 v[154:157], v0 offset:49152
	ds_read_b128 v[158:161], v0 offset:50176
	ds_read_b128 v[162:165], v0 offset:51200
	ds_read_b128 v[166:169], v0 offset:52224
	s_mov_b32 m0, s43
	ds_read_b128 v[170:173], v137 offset:32768
	ds_read_b128 v[174:177], v137 offset:33792
	ds_read_b128 v[178:181], v137 offset:34816
	ds_read_b128 v[182:185], v137 offset:35840
	ds_read_b128 v[186:189], v137 offset:36864
	ds_read_b128 v[190:193], v137 offset:37888
	ds_read_b128 v[194:197], v137 offset:38912
	ds_read_b128 v[198:201], v137 offset:39936
	s_nop 0
	global_load_lds_dwordx4 v130, s[16:17]
	s_mov_b32 m0, s50
	s_nop 0
	global_load_lds_dwordx4 v132, s[16:17]
	s_waitcnt vmcnt(8)
	s_waitcnt lgkmcnt(0)
	s_setprio 1
	s_barrier
	v_mfma_f32_16x16x32_bf16 v[126:129], v[138:141], v[170:173], v[126:129]
	v_mfma_f32_16x16x32_bf16 v[122:125], v[146:149], v[170:173], v[122:125]
	v_mfma_f32_16x16x32_bf16 v[118:121], v[138:141], v[178:181], v[118:121]
	v_mfma_f32_16x16x32_bf16 v[110:113], v[146:149], v[178:181], v[110:113]
	v_mfma_f32_16x16x32_bf16 v[102:105], v[138:141], v[186:189], v[102:105]
	v_mfma_f32_16x16x32_bf16 v[94:97], v[146:149], v[186:189], v[94:97]
	v_mfma_f32_16x16x32_bf16 v[86:89], v[138:141], v[194:197], v[86:89]
	v_mfma_f32_16x16x32_bf16 v[78:81], v[146:149], v[194:197], v[78:81]
	v_mfma_f32_16x16x32_bf16 v[126:129], v[142:145], v[174:177], v[126:129]
	v_mfma_f32_16x16x32_bf16 v[122:125], v[150:153], v[174:177], v[122:125]
	v_mfma_f32_16x16x32_bf16 v[118:121], v[142:145], v[182:185], v[118:121]
	v_mfma_f32_16x16x32_bf16 v[110:113], v[150:153], v[182:185], v[110:113]
	v_mfma_f32_16x16x32_bf16 v[102:105], v[142:145], v[190:193], v[102:105]
	v_mfma_f32_16x16x32_bf16 v[94:97], v[150:153], v[190:193], v[94:97]
	v_mfma_f32_16x16x32_bf16 v[86:89], v[142:145], v[198:201], v[86:89]
	v_mfma_f32_16x16x32_bf16 v[78:81], v[150:153], v[198:201], v[78:81]
	s_setprio 0
	s_setprio 1
	v_mfma_f32_16x16x32_bf16 v[114:117], v[154:157], v[170:173], v[114:117]
	v_mfma_f32_16x16x32_bf16 v[106:109], v[162:165], v[170:173], v[106:109]
	v_mfma_f32_16x16x32_bf16 v[98:101], v[154:157], v[178:181], v[98:101]
	v_mfma_f32_16x16x32_bf16 v[90:93], v[162:165], v[178:181], v[90:93]
	v_mfma_f32_16x16x32_bf16 v[82:85], v[154:157], v[186:189], v[82:85]
	v_mfma_f32_16x16x32_bf16 v[74:77], v[162:165], v[186:189], v[74:77]
	v_mfma_f32_16x16x32_bf16 v[70:73], v[154:157], v[194:197], v[70:73]
	v_mfma_f32_16x16x32_bf16 v[62:65], v[162:165], v[194:197], v[62:65]
	v_mfma_f32_16x16x32_bf16 v[114:117], v[158:161], v[174:177], v[114:117]
	v_mfma_f32_16x16x32_bf16 v[106:109], v[166:169], v[174:177], v[106:109]
	v_mfma_f32_16x16x32_bf16 v[98:101], v[158:161], v[182:185], v[98:101]
	v_mfma_f32_16x16x32_bf16 v[90:93], v[166:169], v[182:185], v[90:93]
	v_mfma_f32_16x16x32_bf16 v[82:85], v[158:161], v[190:193], v[82:85]
	v_mfma_f32_16x16x32_bf16 v[74:77], v[166:169], v[190:193], v[74:77]
	v_mfma_f32_16x16x32_bf16 v[70:73], v[158:161], v[198:201], v[70:73]
	v_mfma_f32_16x16x32_bf16 v[62:65], v[166:169], v[198:201], v[62:65]
	s_setprio 0
	s_barrier
	ds_read_b128 v[170:173], v137 offset:49152
	ds_read_b128 v[174:177], v137 offset:50176
	ds_read_b128 v[178:181], v137 offset:51200
	ds_read_b128 v[182:185], v137 offset:52224
	ds_read_b128 v[186:189], v137 offset:53248
	ds_read_b128 v[190:193], v137 offset:54272
	ds_read_b128 v[194:197], v137 offset:55296
	ds_read_b128 v[198:201], v137 offset:56320
	s_mov_b32 m0, s64
	s_add_u32 s100, s12, s38
	s_addc_u32 s101, s13, s39
	global_load_lds_dwordx4 v131, s[100:101]
	s_mov_b32 m0, s61
	s_nop 0
	global_load_lds_dwordx4 v133, s[100:101]
	s_mov_b32 m0, s71
	s_nop 0
	global_load_lds_dwordx4 v131, s[14:15]
	s_mov_b32 m0, s70
	s_nop 0
	global_load_lds_dwordx4 v133, s[14:15]
	s_mov_b32 m0, s59
	s_add_u32 s100, s10, s38
	s_addc_u32 s101, s11, s39
	v_mov_b32_e32 v0, v132
	global_load_lds_dwordx4 v130, s[100:101]
	s_mov_b32 m0, s60
	s_nop 0
	global_load_lds_dwordx4 v132, s[100:101]
	s_waitcnt vmcnt(8)
	s_waitcnt lgkmcnt(0)
	s_setprio 1
	s_barrier
	v_mfma_f32_16x16x32_bf16 v[66:69], v[138:141], v[170:173], v[66:69]
	v_mfma_f32_16x16x32_bf16 v[58:61], v[146:149], v[170:173], v[58:61]
	v_mfma_f32_16x16x32_bf16 v[54:57], v[138:141], v[178:181], v[54:57]
	v_mfma_f32_16x16x32_bf16 v[46:49], v[146:149], v[178:181], v[46:49]
	v_mfma_f32_16x16x32_bf16 v[38:41], v[138:141], v[186:189], v[38:41]
	v_mfma_f32_16x16x32_bf16 v[30:33], v[146:149], v[186:189], v[30:33]
	v_mfma_f32_16x16x32_bf16 v[22:25], v[138:141], v[194:197], v[22:25]
	v_mfma_f32_16x16x32_bf16 v[14:17], v[146:149], v[194:197], v[14:17]
	v_mfma_f32_16x16x32_bf16 v[66:69], v[142:145], v[174:177], v[66:69]
	v_mfma_f32_16x16x32_bf16 v[58:61], v[150:153], v[174:177], v[58:61]
	v_mfma_f32_16x16x32_bf16 v[54:57], v[142:145], v[182:185], v[54:57]
	v_mfma_f32_16x16x32_bf16 v[46:49], v[150:153], v[182:185], v[46:49]
	v_mfma_f32_16x16x32_bf16 v[38:41], v[142:145], v[190:193], v[38:41]
	v_mfma_f32_16x16x32_bf16 v[30:33], v[150:153], v[190:193], v[30:33]
	v_mfma_f32_16x16x32_bf16 v[22:25], v[142:145], v[198:201], v[22:25]
	v_mfma_f32_16x16x32_bf16 v[14:17], v[150:153], v[198:201], v[14:17]
	s_setprio 0
	s_setprio 1
	v_mfma_f32_16x16x32_bf16 v[50:53], v[154:157], v[170:173], v[50:53]
	v_mfma_f32_16x16x32_bf16 v[42:45], v[162:165], v[170:173], v[42:45]
	v_mfma_f32_16x16x32_bf16 v[34:37], v[154:157], v[178:181], v[34:37]
	v_mfma_f32_16x16x32_bf16 v[26:29], v[162:165], v[178:181], v[26:29]
	v_mfma_f32_16x16x32_bf16 v[18:21], v[154:157], v[186:189], v[18:21]
	v_mfma_f32_16x16x32_bf16 v[10:13], v[162:165], v[186:189], v[10:13]
	v_mfma_f32_16x16x32_bf16 v[6:9], v[154:157], v[194:197], v[6:9]
	v_mfma_f32_16x16x32_bf16 v[2:5], v[162:165], v[194:197], v[2:5]
	v_mfma_f32_16x16x32_bf16 v[50:53], v[158:161], v[174:177], v[50:53]
	v_mfma_f32_16x16x32_bf16 v[42:45], v[166:169], v[174:177], v[42:45]
	v_mfma_f32_16x16x32_bf16 v[34:37], v[158:161], v[182:185], v[34:37]
	v_mfma_f32_16x16x32_bf16 v[26:29], v[166:169], v[182:185], v[26:29]
	v_mfma_f32_16x16x32_bf16 v[18:21], v[158:161], v[190:193], v[18:21]
	v_mfma_f32_16x16x32_bf16 v[10:13], v[166:169], v[190:193], v[10:13]
	v_mfma_f32_16x16x32_bf16 v[6:9], v[158:161], v[198:201], v[6:9]
	v_mfma_f32_16x16x32_bf16 v[2:5], v[166:169], v[198:201], v[2:5]
	s_setprio 0
	s_barrier
	s_andn2_b64 vcc, exec, s[8:9]
	s_mov_b64 s[12:13], -1
	s_mov_b64 s[8:9], 0
	s_mov_b64 s[14:15], 0x100
	s_cbranch_vccz .LBB0_1481
	s_cmpk_lt_u32 s24, 0x100
	s_cbranch_scc0 .LBB0_1484
	s_barrier

.LBB0_1570:
	s_add_u32 s48, s41, s6
	s_addc_u32 s49, s42, s7
	s_add_u32 s8, s48, 0x9800100
	s_addc_u32 s9, s49, 0
	s_add_u32 s10, s43, s6
	s_addc_u32 s11, s46, s7
	s_cmpk_eq_i32 s6, 0x700
	s_cselect_b32 s9, s3, s9
	s_cselect_b32 s8, s2, s8
	s_cselect_b32 s11, s26, s11
	s_cselect_b32 s10, s25, s10
	s_add_i32 s50, 0, 0x10000
	v_add_u32_e32 v0, s50, v169
	s_add_i32 s51, 0, 0x14000
	ds_read_b128 v[172:175], v0
	ds_read_b128 v[176:179], v0 offset:1024
	ds_read_b128 v[180:183], v0 offset:2048
	ds_read_b128 v[184:187], v0 offset:3072
	ds_read_b128 v[188:191], v0 offset:16384
	ds_read_b128 v[192:195], v0 offset:17408
	ds_read_b128 v[196:199], v0 offset:18432
	ds_read_b128 v[200:203], v0 offset:19456
	ds_read_b128 v[204:207], v170
	ds_read_b128 v[208:211], v170 offset:1024
	ds_read_b128 v[212:215], v170 offset:2048
	ds_read_b128 v[216:219], v170 offset:3072
	ds_read_b128 v[220:223], v170 offset:4096
	ds_read_b128 v[224:227], v170 offset:5120
	ds_read_b128 v[232:235], v170 offset:6144
	ds_read_b128 v[242:245], v170 offset:7168
	s_mov_b64 s[58:59], 0x9840080
	s_add_u32 s100, s48, s58
	s_addc_u32 s101, s49, s59
	s_add_i32 m0, s17, 0xc000
	s_nop 0
	global_load_lds_dwordx4 v164, s[100:101]
	s_add_i32 m0, s17, 0xe000
	s_nop 0
	global_load_lds_dwordx4 v166, s[100:101]
	s_waitcnt vmcnt(8)
	s_waitcnt lgkmcnt(0)
	s_setprio 1
	s_barrier
	v_mfma_f32_16x16x32_bf16 v[160:163], v[172:175], v[204:207], v[160:163]
	v_mfma_f32_16x16x32_bf16 v[156:159], v[180:183], v[204:207], v[156:159]
	v_mfma_f32_16x16x32_bf16 v[112:115], v[172:175], v[212:215], v[112:115]
	v_mfma_f32_16x16x32_bf16 v[108:111], v[180:183], v[212:215], v[108:111]
	v_mfma_f32_16x16x32_bf16 v[96:99], v[172:175], v[220:223], v[96:99]
	v_mfma_f32_16x16x32_bf16 v[92:95], v[180:183], v[220:223], v[92:95]
	v_mfma_f32_16x16x32_bf16 v[80:83], v[172:175], v[232:235], v[80:83]
	v_mfma_f32_16x16x32_bf16 v[76:79], v[180:183], v[232:235], v[76:79]
	v_mfma_f32_16x16x32_bf16 v[160:163], v[176:179], v[208:211], v[160:163]
	v_mfma_f32_16x16x32_bf16 v[156:159], v[184:187], v[208:211], v[156:159]
	v_mfma_f32_16x16x32_bf16 v[112:115], v[176:179], v[216:219], v[112:115]
	v_mfma_f32_16x16x32_bf16 v[108:111], v[184:187], v[216:219], v[108:111]
	v_mfma_f32_16x16x32_bf16 v[96:99], v[176:179], v[224:227], v[96:99]
	v_mfma_f32_16x16x32_bf16 v[92:95], v[184:187], v[224:227], v[92:95]
	v_mfma_f32_16x16x32_bf16 v[80:83], v[176:179], v[242:245], v[80:83]
	v_mfma_f32_16x16x32_bf16 v[76:79], v[184:187], v[242:245], v[76:79]
	s_setprio 0
	s_setprio 1
	v_mfma_f32_16x16x32_bf16 v[128:131], v[188:191], v[204:207], v[128:131]
	v_mfma_f32_16x16x32_bf16 v[120:123], v[196:199], v[204:207], v[120:123]
	v_mfma_f32_16x16x32_bf16 v[104:107], v[188:191], v[212:215], v[104:107]
	v_mfma_f32_16x16x32_bf16 v[100:103], v[196:199], v[212:215], v[100:103]
	v_mfma_f32_16x16x32_bf16 v[88:91], v[188:191], v[220:223], v[88:91]
	v_mfma_f32_16x16x32_bf16 v[84:87], v[196:199], v[220:223], v[84:87]
	v_mfma_f32_16x16x32_bf16 v[72:75], v[188:191], v[232:235], v[72:75]
	v_mfma_f32_16x16x32_bf16 v[68:71], v[196:199], v[232:235], v[68:71]
	v_mfma_f32_16x16x32_bf16 v[128:131], v[192:195], v[208:211], v[128:131]
	v_mfma_f32_16x16x32_bf16 v[120:123], v[200:203], v[208:211], v[120:123]
	v_mfma_f32_16x16x32_bf16 v[104:107], v[192:195], v[216:219], v[104:107]
	v_mfma_f32_16x16x32_bf16 v[100:103], v[200:203], v[216:219], v[100:103]
	v_mfma_f32_16x16x32_bf16 v[88:91], v[192:195], v[224:227], v[88:91]
	v_mfma_f32_16x16x32_bf16 v[84:87], v[200:203], v[224:227], v[84:87]
	v_mfma_f32_16x16x32_bf16 v[72:75], v[192:195], v[242:245], v[72:75]
	v_mfma_f32_16x16x32_bf16 v[68:71], v[200:203], v[242:245], v[68:71]
	s_setprio 0
	s_barrier
	s_add_i32 s48, s50, s16
	ds_read_b128 v[204:207], v170 offset:16384
	ds_read_b128 v[208:211], v170 offset:17408
	ds_read_b128 v[212:215], v170 offset:18432
	ds_read_b128 v[216:219], v170 offset:19456
	ds_read_b128 v[220:223], v170 offset:20480
	ds_read_b128 v[224:227], v170 offset:21504
	ds_read_b128 v[232:235], v170 offset:22528
	ds_read_b128 v[242:245], v170 offset:23552
	s_mov_b32 m0, s48
	s_nop 0
	global_load_lds_dwordx4 v167, s[10:11]
	s_add_i32 m0, s48, 0x2000
	s_add_u32 s48, s10, 0x40000
	global_load_lds_dwordx4 v168, s[10:11]
	s_addc_u32 s49, s11, 0
	s_add_i32 s50, s51, s16
	s_mov_b32 m0, s50
	s_nop 0
	global_load_lds_dwordx4 v167, s[48:49]
	s_add_i32 m0, s50, 0x2000
	s_nop 0
	global_load_lds_dwordx4 v168, s[48:49]
	s_mov_b32 m0, s17
	s_nop 0
	global_load_lds_dwordx4 v164, s[8:9]
	s_mov_b32 m0, s22
	s_nop 0
	global_load_lds_dwordx4 v166, s[8:9]
	s_waitcnt vmcnt(8)
	s_waitcnt lgkmcnt(0)
	s_setprio 1
	s_barrier
	v_mfma_f32_16x16x32_bf16 v[64:67], v[172:175], v[204:207], v[64:67]
	v_mfma_f32_16x16x32_bf16 v[60:63], v[180:183], v[204:207], v[60:63]
	v_mfma_f32_16x16x32_bf16 v[48:51], v[172:175], v[212:215], v[48:51]
	v_mfma_f32_16x16x32_bf16 v[44:47], v[180:183], v[212:215], v[44:47]
	v_mfma_f32_16x16x32_bf16 v[32:35], v[172:175], v[220:223], v[32:35]
	v_mfma_f32_16x16x32_bf16 v[28:31], v[180:183], v[220:223], v[28:31]
	v_mfma_f32_16x16x32_bf16 v[16:19], v[172:175], v[232:235], v[16:19]
	v_mfma_f32_16x16x32_bf16 v[12:15], v[180:183], v[232:235], v[12:15]
	v_mfma_f32_16x16x32_bf16 v[64:67], v[176:179], v[208:211], v[64:67]
	v_mfma_f32_16x16x32_bf16 v[60:63], v[184:187], v[208:211], v[60:63]
	v_mfma_f32_16x16x32_bf16 v[48:51], v[176:179], v[216:219], v[48:51]
	v_mfma_f32_16x16x32_bf16 v[44:47], v[184:187], v[216:219], v[44:47]
	v_mfma_f32_16x16x32_bf16 v[32:35], v[176:179], v[224:227], v[32:35]
	v_mfma_f32_16x16x32_bf16 v[28:31], v[184:187], v[224:227], v[28:31]
	v_mfma_f32_16x16x32_bf16 v[16:19], v[176:179], v[242:245], v[16:19]
	v_mfma_f32_16x16x32_bf16 v[12:15], v[184:187], v[242:245], v[12:15]
	s_setprio 0
	s_setprio 1
	v_mfma_f32_16x16x32_bf16 v[56:59], v[188:191], v[204:207], v[56:59]
	v_mfma_f32_16x16x32_bf16 v[52:55], v[196:199], v[204:207], v[52:55]
	v_mfma_f32_16x16x32_bf16 v[40:43], v[188:191], v[212:215], v[40:43]
	v_mfma_f32_16x16x32_bf16 v[36:39], v[196:199], v[212:215], v[36:39]
	v_mfma_f32_16x16x32_bf16 v[24:27], v[188:191], v[220:223], v[24:27]
	v_mfma_f32_16x16x32_bf16 v[20:23], v[196:199], v[220:223], v[20:23]
	v_mfma_f32_16x16x32_bf16 v[8:11], v[188:191], v[232:235], v[8:11]
	v_mfma_f32_16x16x32_bf16 v[2:5], v[196:199], v[232:235], v[4:7]
	v_mfma_f32_16x16x32_bf16 v[56:59], v[192:195], v[208:211], v[56:59]
	v_mfma_f32_16x16x32_bf16 v[52:55], v[200:203], v[208:211], v[52:55]
	v_mfma_f32_16x16x32_bf16 v[40:43], v[192:195], v[216:219], v[40:43]
	v_mfma_f32_16x16x32_bf16 v[36:39], v[200:203], v[216:219], v[36:39]
	v_mfma_f32_16x16x32_bf16 v[24:27], v[192:195], v[224:227], v[24:27]
	v_mfma_f32_16x16x32_bf16 v[20:23], v[200:203], v[224:227], v[20:23]
	v_mfma_f32_16x16x32_bf16 v[8:11], v[192:195], v[242:245], v[8:11]
	v_mfma_f32_16x16x32_bf16 v[2:5], v[200:203], v[242:245], v[2:5]
	s_setprio 0
	s_barrier
	s_add_i32 s50, 0, 0x18000
	s_add_i32 s51, 0, 0x1c000
	ds_read_b128 v[172:175], v0 offset:32768
	ds_read_b128 v[176:179], v0 offset:33792
	ds_read_b128 v[180:183], v0 offset:34816
	ds_read_b128 v[184:187], v0 offset:35840
	ds_read_b128 v[188:191], v0 offset:49152
	ds_read_b128 v[192:195], v0 offset:50176
	ds_read_b128 v[196:199], v0 offset:51200
	ds_read_b128 v[200:203], v0 offset:52224
	s_add_u32 s48, s8, 0x40000
	s_mov_b32 m0, s23
	ds_read_b128 v[204:207], v170 offset:32768
	ds_read_b128 v[208:211], v170 offset:33792
	ds_read_b128 v[212:215], v170 offset:34816
	ds_read_b128 v[216:219], v170 offset:35840
	ds_read_b128 v[220:223], v170 offset:36864
	ds_read_b128 v[224:227], v170 offset:37888
	ds_read_b128 v[232:235], v170 offset:38912
	ds_read_b128 v[242:245], v170 offset:39936
	s_addc_u32 s49, s9, 0
	s_nop 0
	global_load_lds_dwordx4 v164, s[48:49]
	s_mov_b32 m0, s24
	s_nop 0
	global_load_lds_dwordx4 v166, s[48:49]
	s_waitcnt vmcnt(8)
	s_waitcnt lgkmcnt(0)
	s_setprio 1
	s_barrier
	v_mfma_f32_16x16x32_bf16 v[160:163], v[172:175], v[204:207], v[160:163]
	v_mfma_f32_16x16x32_bf16 v[156:159], v[180:183], v[204:207], v[156:159]
	v_mfma_f32_16x16x32_bf16 v[112:115], v[172:175], v[212:215], v[112:115]
	v_mfma_f32_16x16x32_bf16 v[108:111], v[180:183], v[212:215], v[108:111]
	v_mfma_f32_16x16x32_bf16 v[96:99], v[172:175], v[220:223], v[96:99]
	v_mfma_f32_16x16x32_bf16 v[92:95], v[180:183], v[220:223], v[92:95]
	v_mfma_f32_16x16x32_bf16 v[80:83], v[172:175], v[232:235], v[80:83]
	v_mfma_f32_16x16x32_bf16 v[76:79], v[180:183], v[232:235], v[76:79]
	v_mfma_f32_16x16x32_bf16 v[160:163], v[176:179], v[208:211], v[160:163]
	v_mfma_f32_16x16x32_bf16 v[156:159], v[184:187], v[208:211], v[156:159]
	v_mfma_f32_16x16x32_bf16 v[112:115], v[176:179], v[216:219], v[112:115]
	v_mfma_f32_16x16x32_bf16 v[108:111], v[184:187], v[216:219], v[108:111]
	v_mfma_f32_16x16x32_bf16 v[96:99], v[176:179], v[224:227], v[96:99]
	v_mfma_f32_16x16x32_bf16 v[92:95], v[184:187], v[224:227], v[92:95]
	v_mfma_f32_16x16x32_bf16 v[80:83], v[176:179], v[242:245], v[80:83]
	v_mfma_f32_16x16x32_bf16 v[76:79], v[184:187], v[242:245], v[76:79]
	s_setprio 0
	s_setprio 1
	v_mfma_f32_16x16x32_bf16 v[128:131], v[188:191], v[204:207], v[128:131]
	v_mfma_f32_16x16x32_bf16 v[120:123], v[196:199], v[204:207], v[120:123]
	v_mfma_f32_16x16x32_bf16 v[104:107], v[188:191], v[212:215], v[104:107]
	v_mfma_f32_16x16x32_bf16 v[100:103], v[196:199], v[212:215], v[100:103]
	v_mfma_f32_16x16x32_bf16 v[88:91], v[188:191], v[220:223], v[88:91]
	v_mfma_f32_16x16x32_bf16 v[84:87], v[196:199], v[220:223], v[84:87]
	v_mfma_f32_16x16x32_bf16 v[72:75], v[188:191], v[232:235], v[72:75]
	v_mfma_f32_16x16x32_bf16 v[68:71], v[196:199], v[232:235], v[68:71]
	v_mfma_f32_16x16x32_bf16 v[128:131], v[192:195], v[208:211], v[128:131]
	v_mfma_f32_16x16x32_bf16 v[120:123], v[200:203], v[208:211], v[120:123]
	v_mfma_f32_16x16x32_bf16 v[104:107], v[192:195], v[216:219], v[104:107]
	v_mfma_f32_16x16x32_bf16 v[100:103], v[200:203], v[216:219], v[100:103]
	v_mfma_f32_16x16x32_bf16 v[88:91], v[192:195], v[224:227], v[88:91]
	v_mfma_f32_16x16x32_bf16 v[84:87], v[200:203], v[224:227], v[84:87]
	v_mfma_f32_16x16x32_bf16 v[72:75], v[192:195], v[242:245], v[72:75]
	v_mfma_f32_16x16x32_bf16 v[68:71], v[200:203], v[242:245], v[68:71]
	s_setprio 0
	s_barrier
	ds_read_b128 v[204:207], v170 offset:49152
	ds_read_b128 v[208:211], v170 offset:50176
	ds_read_b128 v[212:215], v170 offset:51200
	ds_read_b128 v[216:219], v170 offset:52224
	ds_read_b128 v[220:223], v170 offset:53248
	ds_read_b128 v[224:227], v170 offset:54272
	ds_read_b128 v[232:235], v170 offset:55296
	ds_read_b128 v[242:245], v170 offset:56320
	s_add_i32 s48, s50, s16
	s_add_u32 s100, s10, s38
	s_addc_u32 s101, s11, s39
	s_mov_b32 m0, s48
	s_nop 0
	global_load_lds_dwordx4 v167, s[100:101]
	s_add_i32 m0, s48, 0x2000
	s_nop 0
	s_add_u32 s10, s10, 0x40080
	s_addc_u32 s11, s11, 0
	s_add_i32 s48, s51, s16
	global_load_lds_dwordx4 v168, s[100:101]
	s_mov_b32 m0, s48
	s_nop 0
	global_load_lds_dwordx4 v167, s[10:11]
	s_add_i32 m0, s48, 0x2000
	s_nop 0
	global_load_lds_dwordx4 v168, s[10:11]
	s_mov_b32 m0, s37
	s_add_u32 s100, s8, s38
	s_addc_u32 s101, s9, s39
	v_mov_b32_e32 v0, v166
	global_load_lds_dwordx4 v164, s[100:101]
	s_mov_b32 m0, s40
	s_nop 0
	global_load_lds_dwordx4 v166, s[100:101]
	s_waitcnt vmcnt(8)
	s_waitcnt lgkmcnt(0)
	s_setprio 1
	s_barrier
	v_mfma_f32_16x16x32_bf16 v[64:67], v[172:175], v[204:207], v[64:67]
	v_mfma_f32_16x16x32_bf16 v[60:63], v[180:183], v[204:207], v[60:63]
	v_mfma_f32_16x16x32_bf16 v[48:51], v[172:175], v[212:215], v[48:51]
	v_mfma_f32_16x16x32_bf16 v[44:47], v[180:183], v[212:215], v[44:47]
	v_mfma_f32_16x16x32_bf16 v[32:35], v[172:175], v[220:223], v[32:35]
	v_mfma_f32_16x16x32_bf16 v[28:31], v[180:183], v[220:223], v[28:31]
	v_mfma_f32_16x16x32_bf16 v[16:19], v[172:175], v[232:235], v[16:19]
	v_mfma_f32_16x16x32_bf16 v[12:15], v[180:183], v[232:235], v[12:15]
	v_mfma_f32_16x16x32_bf16 v[64:67], v[176:179], v[208:211], v[64:67]
	v_mfma_f32_16x16x32_bf16 v[60:63], v[184:187], v[208:211], v[60:63]
	v_mfma_f32_16x16x32_bf16 v[48:51], v[176:179], v[216:219], v[48:51]
	v_mfma_f32_16x16x32_bf16 v[44:47], v[184:187], v[216:219], v[44:47]
	v_mfma_f32_16x16x32_bf16 v[32:35], v[176:179], v[224:227], v[32:35]
	v_mfma_f32_16x16x32_bf16 v[28:31], v[184:187], v[224:227], v[28:31]
	v_mfma_f32_16x16x32_bf16 v[16:19], v[176:179], v[242:245], v[16:19]
	v_mfma_f32_16x16x32_bf16 v[12:15], v[184:187], v[242:245], v[12:15]
	s_setprio 0
	s_setprio 1
	v_mfma_f32_16x16x32_bf16 v[56:59], v[188:191], v[204:207], v[56:59]
	v_mfma_f32_16x16x32_bf16 v[52:55], v[196:199], v[204:207], v[52:55]
	v_mfma_f32_16x16x32_bf16 v[40:43], v[188:191], v[212:215], v[40:43]
	v_mfma_f32_16x16x32_bf16 v[36:39], v[196:199], v[212:215], v[36:39]
	v_mfma_f32_16x16x32_bf16 v[24:27], v[188:191], v[220:223], v[24:27]
	v_mfma_f32_16x16x32_bf16 v[20:23], v[196:199], v[220:223], v[20:23]
	v_mfma_f32_16x16x32_bf16 v[6:9], v[188:191], v[232:235], v[8:11]
	v_mfma_f32_16x16x32_bf16 v[2:5], v[196:199], v[232:235], v[2:5]
	v_mfma_f32_16x16x32_bf16 v[56:59], v[192:195], v[208:211], v[56:59]
	v_mfma_f32_16x16x32_bf16 v[52:55], v[200:203], v[208:211], v[52:55]
	v_mfma_f32_16x16x32_bf16 v[40:43], v[192:195], v[216:219], v[40:43]
	v_mfma_f32_16x16x32_bf16 v[36:39], v[200:203], v[216:219], v[36:39]
	v_mfma_f32_16x16x32_bf16 v[24:27], v[192:195], v[224:227], v[24:27]
	v_mfma_f32_16x16x32_bf16 v[20:23], v[200:203], v[224:227], v[20:23]
	v_mfma_f32_16x16x32_bf16 v[8:11], v[192:195], v[242:245], v[6:9]
	v_mfma_f32_16x16x32_bf16 v[4:7], v[200:203], v[242:245], v[2:5]
	s_setprio 0
	s_barrier
	s_add_i32 s47, s47, 2
	s_add_u32 s6, s6, 0x100
	s_addc_u32 s7, s7, 0
	s_cmp_gt_u32 s47, 13
	s_cbranch_scc1 .LBB0_1573

.LBB0_1681:
	s_add_u32 s48, s6, s2
	s_addc_u32 s49, s7, s3
	s_add_u32 s10, s48, 0x100
	s_addc_u32 s11, s49, 0
	s_add_u32 s12, s37, s2
	s_addc_u32 s13, s40, s3
	s_add_i32 s47, 0, 0x10000
	s_cmp_eq_u32 s46, 12
	s_cselect_b32 s11, s7, s11
	s_cselect_b32 s10, s6, s10
	v_add_u32_e32 v0, s47, v136
	s_cselect_b32 s13, s9, s13
	s_cselect_b32 s12, s8, s12
	s_add_i32 s50, 0, 0x14000
	ds_read_b128 v[138:141], v0
	ds_read_b128 v[142:145], v0 offset:1024
	ds_read_b128 v[146:149], v0 offset:2048
	ds_read_b128 v[150:153], v0 offset:3072
	ds_read_b128 v[154:157], v0 offset:16384
	ds_read_b128 v[158:161], v0 offset:17408
	ds_read_b128 v[162:165], v0 offset:18432
	ds_read_b128 v[166:169], v0 offset:19456
	ds_read_b128 v[170:173], v137
	ds_read_b128 v[174:177], v137 offset:1024
	ds_read_b128 v[178:181], v137 offset:2048
	ds_read_b128 v[182:185], v137 offset:3072
	ds_read_b128 v[186:189], v137 offset:4096
	ds_read_b128 v[190:193], v137 offset:5120
	ds_read_b128 v[194:197], v137 offset:6144
	ds_read_b128 v[198:201], v137 offset:7168
	s_add_i32 m0, s23, 0xc000
	s_add_u32 s100, s48, s56
	s_addc_u32 s101, s49, s57
	global_load_lds_dwordx4 v130, s[100:101]
	s_add_i32 m0, s23, 0xe000
	s_nop 0
	global_load_lds_dwordx4 v132, s[100:101]
	s_waitcnt vmcnt(8)
	s_waitcnt lgkmcnt(0)
	s_setprio 1
	s_barrier
	v_mfma_f32_16x16x32_bf16 v[126:129], v[138:141], v[170:173], v[126:129]
	v_mfma_f32_16x16x32_bf16 v[122:125], v[146:149], v[170:173], v[122:125]
	v_mfma_f32_16x16x32_bf16 v[110:113], v[138:141], v[178:181], v[110:113]
	v_mfma_f32_16x16x32_bf16 v[106:109], v[146:149], v[178:181], v[106:109]
	v_mfma_f32_16x16x32_bf16 v[94:97], v[138:141], v[186:189], v[94:97]
	v_mfma_f32_16x16x32_bf16 v[90:93], v[146:149], v[186:189], v[90:93]
	v_mfma_f32_16x16x32_bf16 v[78:81], v[138:141], v[194:197], v[78:81]
	v_mfma_f32_16x16x32_bf16 v[74:77], v[146:149], v[194:197], v[74:77]
	v_mfma_f32_16x16x32_bf16 v[126:129], v[142:145], v[174:177], v[126:129]
	v_mfma_f32_16x16x32_bf16 v[122:125], v[150:153], v[174:177], v[122:125]
	v_mfma_f32_16x16x32_bf16 v[110:113], v[142:145], v[182:185], v[110:113]
	v_mfma_f32_16x16x32_bf16 v[106:109], v[150:153], v[182:185], v[106:109]
	v_mfma_f32_16x16x32_bf16 v[94:97], v[142:145], v[190:193], v[94:97]
	v_mfma_f32_16x16x32_bf16 v[90:93], v[150:153], v[190:193], v[90:93]
	v_mfma_f32_16x16x32_bf16 v[78:81], v[142:145], v[198:201], v[78:81]
	v_mfma_f32_16x16x32_bf16 v[74:77], v[150:153], v[198:201], v[74:77]
	s_setprio 0
	s_setprio 1
	v_mfma_f32_16x16x32_bf16 v[118:121], v[154:157], v[170:173], v[118:121]
	v_mfma_f32_16x16x32_bf16 v[114:117], v[162:165], v[170:173], v[114:117]
	v_mfma_f32_16x16x32_bf16 v[102:105], v[154:157], v[178:181], v[102:105]
	v_mfma_f32_16x16x32_bf16 v[98:101], v[162:165], v[178:181], v[98:101]
	v_mfma_f32_16x16x32_bf16 v[86:89], v[154:157], v[186:189], v[86:89]
	v_mfma_f32_16x16x32_bf16 v[82:85], v[162:165], v[186:189], v[82:85]
	v_mfma_f32_16x16x32_bf16 v[70:73], v[154:157], v[194:197], v[70:73]
	v_mfma_f32_16x16x32_bf16 v[66:69], v[162:165], v[194:197], v[66:69]
	v_mfma_f32_16x16x32_bf16 v[118:121], v[158:161], v[174:177], v[118:121]
	v_mfma_f32_16x16x32_bf16 v[114:117], v[166:169], v[174:177], v[114:117]
	v_mfma_f32_16x16x32_bf16 v[102:105], v[158:161], v[182:185], v[102:105]
	v_mfma_f32_16x16x32_bf16 v[98:101], v[166:169], v[182:185], v[98:101]
	v_mfma_f32_16x16x32_bf16 v[86:89], v[158:161], v[190:193], v[86:89]
	v_mfma_f32_16x16x32_bf16 v[82:85], v[166:169], v[190:193], v[82:85]
	v_mfma_f32_16x16x32_bf16 v[70:73], v[158:161], v[198:201], v[70:73]
	v_mfma_f32_16x16x32_bf16 v[66:69], v[166:169], v[198:201], v[66:69]
	s_setprio 0
	s_barrier
	s_add_i32 s47, s47, s22
	ds_read_b128 v[170:173], v137 offset:16384
	ds_read_b128 v[174:177], v137 offset:17408
	ds_read_b128 v[178:181], v137 offset:18432
	ds_read_b128 v[182:185], v137 offset:19456
	ds_read_b128 v[186:189], v137 offset:20480
	ds_read_b128 v[190:193], v137 offset:21504
	ds_read_b128 v[194:197], v137 offset:22528
	ds_read_b128 v[198:201], v137 offset:23552
	s_mov_b32 m0, s47
	s_nop 0
	global_load_lds_dwordx4 v134, s[12:13]
	s_add_i32 m0, s47, 0x2000
	s_add_u32 s48, s12, 0x40000
	global_load_lds_dwordx4 v135, s[12:13]
	s_addc_u32 s49, s13, 0
	s_add_i32 s47, s50, s22
	s_mov_b32 m0, s47
	s_nop 0
	global_load_lds_dwordx4 v134, s[48:49]
	s_add_i32 m0, s47, 0x2000
	s_nop 0
	global_load_lds_dwordx4 v135, s[48:49]
	s_mov_b32 m0, s23
	s_nop 0
	global_load_lds_dwordx4 v130, s[10:11]
	s_mov_b32 m0, s24
	s_nop 0
	global_load_lds_dwordx4 v132, s[10:11]
	s_waitcnt vmcnt(8)
	s_waitcnt lgkmcnt(0)
	s_setprio 1
	s_barrier
	v_mfma_f32_16x16x32_bf16 v[62:65], v[138:141], v[170:173], v[62:65]
	v_mfma_f32_16x16x32_bf16 v[58:61], v[146:149], v[170:173], v[58:61]
	v_mfma_f32_16x16x32_bf16 v[46:49], v[138:141], v[178:181], v[46:49]
	v_mfma_f32_16x16x32_bf16 v[42:45], v[146:149], v[178:181], v[42:45]
	v_mfma_f32_16x16x32_bf16 v[30:33], v[138:141], v[186:189], v[30:33]
	v_mfma_f32_16x16x32_bf16 v[26:29], v[146:149], v[186:189], v[26:29]
	v_mfma_f32_16x16x32_bf16 v[14:17], v[138:141], v[194:197], v[14:17]
	v_mfma_f32_16x16x32_bf16 v[10:13], v[146:149], v[194:197], v[10:13]
	v_mfma_f32_16x16x32_bf16 v[62:65], v[142:145], v[174:177], v[62:65]
	v_mfma_f32_16x16x32_bf16 v[58:61], v[150:153], v[174:177], v[58:61]
	v_mfma_f32_16x16x32_bf16 v[46:49], v[142:145], v[182:185], v[46:49]
	v_mfma_f32_16x16x32_bf16 v[42:45], v[150:153], v[182:185], v[42:45]
	v_mfma_f32_16x16x32_bf16 v[30:33], v[142:145], v[190:193], v[30:33]
	v_mfma_f32_16x16x32_bf16 v[26:29], v[150:153], v[190:193], v[26:29]
	v_mfma_f32_16x16x32_bf16 v[14:17], v[142:145], v[198:201], v[14:17]
	v_mfma_f32_16x16x32_bf16 v[10:13], v[150:153], v[198:201], v[10:13]
	s_setprio 0
	s_setprio 1
	v_mfma_f32_16x16x32_bf16 v[54:57], v[154:157], v[170:173], v[54:57]
	v_mfma_f32_16x16x32_bf16 v[50:53], v[162:165], v[170:173], v[50:53]
	v_mfma_f32_16x16x32_bf16 v[38:41], v[154:157], v[178:181], v[38:41]
	v_mfma_f32_16x16x32_bf16 v[34:37], v[162:165], v[178:181], v[34:37]
	v_mfma_f32_16x16x32_bf16 v[22:25], v[154:157], v[186:189], v[22:25]
	v_mfma_f32_16x16x32_bf16 v[18:21], v[162:165], v[186:189], v[18:21]
	v_mfma_f32_16x16x32_bf16 v[6:9], v[154:157], v[194:197], v[6:9]
	v_mfma_f32_16x16x32_bf16 v[2:5], v[162:165], v[194:197], v[2:5]
	v_mfma_f32_16x16x32_bf16 v[54:57], v[158:161], v[174:177], v[54:57]
	v_mfma_f32_16x16x32_bf16 v[50:53], v[166:169], v[174:177], v[50:53]
	v_mfma_f32_16x16x32_bf16 v[38:41], v[158:161], v[182:185], v[38:41]
	v_mfma_f32_16x16x32_bf16 v[34:37], v[166:169], v[182:185], v[34:37]
	v_mfma_f32_16x16x32_bf16 v[22:25], v[158:161], v[190:193], v[22:25]
	v_mfma_f32_16x16x32_bf16 v[18:21], v[166:169], v[190:193], v[18:21]
	v_mfma_f32_16x16x32_bf16 v[6:9], v[158:161], v[198:201], v[6:9]
	v_mfma_f32_16x16x32_bf16 v[2:5], v[166:169], v[198:201], v[2:5]
	s_setprio 0
	s_barrier
	s_add_i32 s47, 0, 0x18000
	s_add_i32 s50, 0, 0x1c000
	ds_read_b128 v[138:141], v0 offset:32768
	ds_read_b128 v[142:145], v0 offset:33792
	ds_read_b128 v[146:149], v0 offset:34816
	ds_read_b128 v[150:153], v0 offset:35840
	ds_read_b128 v[154:157], v0 offset:49152
	ds_read_b128 v[158:161], v0 offset:50176
	ds_read_b128 v[162:165], v0 offset:51200
	ds_read_b128 v[166:169], v0 offset:52224
	s_add_u32 s48, s10, 0x40000
	s_mov_b32 m0, s25
	ds_read_b128 v[170:173], v137 offset:32768
	ds_read_b128 v[174:177], v137 offset:33792
	ds_read_b128 v[178:181], v137 offset:34816
	ds_read_b128 v[182:185], v137 offset:35840
	ds_read_b128 v[186:189], v137 offset:36864
	ds_read_b128 v[190:193], v137 offset:37888
	ds_read_b128 v[194:197], v137 offset:38912
	ds_read_b128 v[198:201], v137 offset:39936
	s_addc_u32 s49, s11, 0
	s_nop 0
	global_load_lds_dwordx4 v130, s[48:49]
	s_mov_b32 m0, s26
	s_nop 0
	global_load_lds_dwordx4 v132, s[48:49]
	s_waitcnt vmcnt(8)
	s_waitcnt lgkmcnt(0)
	s_setprio 1
	s_barrier
	v_mfma_f32_16x16x32_bf16 v[126:129], v[138:141], v[170:173], v[126:129]
	v_mfma_f32_16x16x32_bf16 v[122:125], v[146:149], v[170:173], v[122:125]
	v_mfma_f32_16x16x32_bf16 v[110:113], v[138:141], v[178:181], v[110:113]
	v_mfma_f32_16x16x32_bf16 v[106:109], v[146:149], v[178:181], v[106:109]
	v_mfma_f32_16x16x32_bf16 v[94:97], v[138:141], v[186:189], v[94:97]
	v_mfma_f32_16x16x32_bf16 v[90:93], v[146:149], v[186:189], v[90:93]
	v_mfma_f32_16x16x32_bf16 v[78:81], v[138:141], v[194:197], v[78:81]
	v_mfma_f32_16x16x32_bf16 v[74:77], v[146:149], v[194:197], v[74:77]
	v_mfma_f32_16x16x32_bf16 v[126:129], v[142:145], v[174:177], v[126:129]
	v_mfma_f32_16x16x32_bf16 v[122:125], v[150:153], v[174:177], v[122:125]
	v_mfma_f32_16x16x32_bf16 v[110:113], v[142:145], v[182:185], v[110:113]
	v_mfma_f32_16x16x32_bf16 v[106:109], v[150:153], v[182:185], v[106:109]
	v_mfma_f32_16x16x32_bf16 v[94:97], v[142:145], v[190:193], v[94:97]
	v_mfma_f32_16x16x32_bf16 v[90:93], v[150:153], v[190:193], v[90:93]
	v_mfma_f32_16x16x32_bf16 v[78:81], v[142:145], v[198:201], v[78:81]
	v_mfma_f32_16x16x32_bf16 v[74:77], v[150:153], v[198:201], v[74:77]
	s_setprio 0
	s_setprio 1
	v_mfma_f32_16x16x32_bf16 v[118:121], v[154:157], v[170:173], v[118:121]
	v_mfma_f32_16x16x32_bf16 v[114:117], v[162:165], v[170:173], v[114:117]
	v_mfma_f32_16x16x32_bf16 v[102:105], v[154:157], v[178:181], v[102:105]
	v_mfma_f32_16x16x32_bf16 v[98:101], v[162:165], v[178:181], v[98:101]
	v_mfma_f32_16x16x32_bf16 v[86:89], v[154:157], v[186:189], v[86:89]
	v_mfma_f32_16x16x32_bf16 v[82:85], v[162:165], v[186:189], v[82:85]
	v_mfma_f32_16x16x32_bf16 v[70:73], v[154:157], v[194:197], v[70:73]
	v_mfma_f32_16x16x32_bf16 v[66:69], v[162:165], v[194:197], v[66:69]
	v_mfma_f32_16x16x32_bf16 v[118:121], v[158:161], v[174:177], v[118:121]
	v_mfma_f32_16x16x32_bf16 v[114:117], v[166:169], v[174:177], v[114:117]
	v_mfma_f32_16x16x32_bf16 v[102:105], v[158:161], v[182:185], v[102:105]
	v_mfma_f32_16x16x32_bf16 v[98:101], v[166:169], v[182:185], v[98:101]
	v_mfma_f32_16x16x32_bf16 v[86:89], v[158:161], v[190:193], v[86:89]
	v_mfma_f32_16x16x32_bf16 v[82:85], v[166:169], v[190:193], v[82:85]
	v_mfma_f32_16x16x32_bf16 v[70:73], v[158:161], v[198:201], v[70:73]
	v_mfma_f32_16x16x32_bf16 v[66:69], v[166:169], v[198:201], v[66:69]
	s_setprio 0
	s_barrier
	ds_read_b128 v[170:173], v137 offset:49152
	ds_read_b128 v[174:177], v137 offset:50176
	ds_read_b128 v[178:181], v137 offset:51200
	ds_read_b128 v[182:185], v137 offset:52224
	ds_read_b128 v[186:189], v137 offset:53248
	ds_read_b128 v[190:193], v137 offset:54272
	ds_read_b128 v[194:197], v137 offset:55296
	ds_read_b128 v[198:201], v137 offset:56320
	s_add_i32 s47, s47, s22
	s_add_u32 s100, s12, s38
	s_addc_u32 s101, s13, s39
	s_mov_b32 m0, s47
	s_nop 0
	global_load_lds_dwordx4 v134, s[100:101]
	s_add_i32 m0, s47, 0x2000
	s_nop 0
	s_add_u32 s12, s12, 0x40080
	s_addc_u32 s13, s13, 0
	s_add_i32 s47, s50, s22
	global_load_lds_dwordx4 v135, s[100:101]
	s_mov_b32 m0, s47
	s_nop 0
	global_load_lds_dwordx4 v134, s[12:13]
	s_add_i32 m0, s47, 0x2000
	s_nop 0
	global_load_lds_dwordx4 v135, s[12:13]
	s_mov_b32 m0, s42
	s_add_u32 s100, s10, s38
	s_addc_u32 s101, s11, s39
	v_mov_b32_e32 v0, v132
	global_load_lds_dwordx4 v130, s[100:101]
	s_mov_b32 m0, s43
	s_nop 0
	global_load_lds_dwordx4 v132, s[100:101]
	s_waitcnt vmcnt(8)
	s_waitcnt lgkmcnt(0)
	s_setprio 1
	s_barrier
	v_mfma_f32_16x16x32_bf16 v[62:65], v[138:141], v[170:173], v[62:65]
	v_mfma_f32_16x16x32_bf16 v[58:61], v[146:149], v[170:173], v[58:61]
	v_mfma_f32_16x16x32_bf16 v[46:49], v[138:141], v[178:181], v[46:49]
	v_mfma_f32_16x16x32_bf16 v[42:45], v[146:149], v[178:181], v[42:45]
	v_mfma_f32_16x16x32_bf16 v[30:33], v[138:141], v[186:189], v[30:33]
	v_mfma_f32_16x16x32_bf16 v[26:29], v[146:149], v[186:189], v[26:29]
	v_mfma_f32_16x16x32_bf16 v[14:17], v[138:141], v[194:197], v[14:17]
	v_mfma_f32_16x16x32_bf16 v[10:13], v[146:149], v[194:197], v[10:13]
	v_mfma_f32_16x16x32_bf16 v[62:65], v[142:145], v[174:177], v[62:65]
	v_mfma_f32_16x16x32_bf16 v[58:61], v[150:153], v[174:177], v[58:61]
	v_mfma_f32_16x16x32_bf16 v[46:49], v[142:145], v[182:185], v[46:49]
	v_mfma_f32_16x16x32_bf16 v[42:45], v[150:153], v[182:185], v[42:45]
	v_mfma_f32_16x16x32_bf16 v[30:33], v[142:145], v[190:193], v[30:33]
	v_mfma_f32_16x16x32_bf16 v[26:29], v[150:153], v[190:193], v[26:29]
	v_mfma_f32_16x16x32_bf16 v[14:17], v[142:145], v[198:201], v[14:17]
	v_mfma_f32_16x16x32_bf16 v[10:13], v[150:153], v[198:201], v[10:13]
	s_setprio 0
	s_setprio 1
	v_mfma_f32_16x16x32_bf16 v[54:57], v[154:157], v[170:173], v[54:57]
	v_mfma_f32_16x16x32_bf16 v[50:53], v[162:165], v[170:173], v[50:53]
	v_mfma_f32_16x16x32_bf16 v[38:41], v[154:157], v[178:181], v[38:41]
	v_mfma_f32_16x16x32_bf16 v[34:37], v[162:165], v[178:181], v[34:37]
	v_mfma_f32_16x16x32_bf16 v[22:25], v[154:157], v[186:189], v[22:25]
	v_mfma_f32_16x16x32_bf16 v[18:21], v[162:165], v[186:189], v[18:21]
	v_mfma_f32_16x16x32_bf16 v[6:9], v[154:157], v[194:197], v[6:9]
	v_mfma_f32_16x16x32_bf16 v[2:5], v[162:165], v[194:197], v[2:5]
	v_mfma_f32_16x16x32_bf16 v[54:57], v[158:161], v[174:177], v[54:57]
	v_mfma_f32_16x16x32_bf16 v[50:53], v[166:169], v[174:177], v[50:53]
	v_mfma_f32_16x16x32_bf16 v[38:41], v[158:161], v[182:185], v[38:41]
	v_mfma_f32_16x16x32_bf16 v[34:37], v[166:169], v[182:185], v[34:37]
	v_mfma_f32_16x16x32_bf16 v[22:25], v[158:161], v[190:193], v[22:25]
	v_mfma_f32_16x16x32_bf16 v[18:21], v[166:169], v[190:193], v[18:21]
	v_mfma_f32_16x16x32_bf16 v[6:9], v[158:161], v[198:201], v[6:9]
	v_mfma_f32_16x16x32_bf16 v[2:5], v[166:169], v[198:201], v[2:5]
	s_setprio 0
	s_barrier
	s_add_i32 s46, s46, 2
	s_add_u32 s2, s2, 0x100
	s_addc_u32 s3, s3, 0
	s_cmp_gt_u32 s46, 13
	s_cbranch_scc0 .LBB0_1681
	s_cmpk_lt_u32 s17, 0x100
	s_cbranch_scc0 .LBB0_1684
	s_barrier

.LBB0_1807:
	s_add_u32 s68, s4, s14
	s_addc_u32 s69, s5, s15
	s_add_u32 s16, s68, 0x100
	s_addc_u32 s17, s69, 0
	s_add_u32 s22, s50, s14
	s_addc_u32 s23, s51, s15
	s_add_i32 s67, 0, 0x10000
	s_cmp_eq_u32 s66, 12
	s_cselect_b32 s17, s5, s17
	s_cselect_b32 s16, s4, s16
	v_add_u32_e32 v0, s67, v126
	s_cselect_b32 s23, s13, s23
	s_cselect_b32 s22, s12, s22
	s_add_i32 s70, 0, 0x14000
	ds_read_b128 v[128:131], v0
	ds_read_b128 v[142:145], v0 offset:1024
	ds_read_b128 v[146:149], v0 offset:2048
	ds_read_b128 v[150:153], v0 offset:3072
	ds_read_b128 v[154:157], v0 offset:16384
	ds_read_b128 v[160:163], v0 offset:17408
	ds_read_b128 v[164:167], v0 offset:18432
	ds_read_b128 v[168:171], v0 offset:19456
	ds_read_b128 v[172:175], v127
	ds_read_b128 v[176:179], v127 offset:1024
	ds_read_b128 v[180:183], v127 offset:2048
	ds_read_b128 v[184:187], v127 offset:3072
	ds_read_b128 v[188:191], v127 offset:4096
	ds_read_b128 v[192:195], v127 offset:5120
	ds_read_b128 v[196:199], v127 offset:6144
	ds_read_b128 v[200:203], v127 offset:7168
	s_add_i32 m0, s43, 0xc000
	s_add_u32 s100, s68, s56
	s_addc_u32 s101, s69, s57
	global_load_lds_dwordx4 v122, s[100:101]
	s_add_i32 m0, s43, 0xe000
	s_nop 0
	global_load_lds_dwordx4 v123, s[100:101]
	s_waitcnt vmcnt(8)
	s_waitcnt lgkmcnt(0)
	s_setprio 1
	s_barrier
	v_mfma_f32_16x16x32_bf16 v[138:141], v[128:131], v[172:175], v[138:141]
	v_mfma_f32_16x16x32_bf16 v[132:135], v[146:149], v[172:175], v[134:137]
	v_mfma_f32_16x16x32_bf16 v[110:113], v[128:131], v[180:183], v[110:113]
	v_mfma_f32_16x16x32_bf16 v[106:109], v[146:149], v[180:183], v[106:109]
	v_mfma_f32_16x16x32_bf16 v[94:97], v[128:131], v[188:191], v[94:97]
	v_mfma_f32_16x16x32_bf16 v[90:93], v[146:149], v[188:191], v[90:93]
	v_mfma_f32_16x16x32_bf16 v[78:81], v[128:131], v[196:199], v[78:81]
	v_mfma_f32_16x16x32_bf16 v[74:77], v[146:149], v[196:199], v[74:77]
	v_mfma_f32_16x16x32_bf16 v[138:141], v[142:145], v[176:179], v[138:141]
	v_mfma_f32_16x16x32_bf16 v[132:135], v[150:153], v[176:179], v[132:135]
	v_mfma_f32_16x16x32_bf16 v[110:113], v[142:145], v[184:187], v[110:113]
	v_mfma_f32_16x16x32_bf16 v[106:109], v[150:153], v[184:187], v[106:109]
	v_mfma_f32_16x16x32_bf16 v[94:97], v[142:145], v[192:195], v[94:97]
	v_mfma_f32_16x16x32_bf16 v[90:93], v[150:153], v[192:195], v[90:93]
	v_mfma_f32_16x16x32_bf16 v[78:81], v[142:145], v[200:203], v[78:81]
	v_mfma_f32_16x16x32_bf16 v[74:77], v[150:153], v[200:203], v[74:77]
	s_setprio 0
	s_setprio 1
	v_mfma_f32_16x16x32_bf16 v[118:121], v[154:157], v[172:175], v[118:121]
	v_mfma_f32_16x16x32_bf16 v[114:117], v[164:167], v[172:175], v[114:117]
	v_mfma_f32_16x16x32_bf16 v[102:105], v[154:157], v[180:183], v[102:105]
	v_mfma_f32_16x16x32_bf16 v[98:101], v[164:167], v[180:183], v[98:101]
	v_mfma_f32_16x16x32_bf16 v[86:89], v[154:157], v[188:191], v[86:89]
	v_mfma_f32_16x16x32_bf16 v[82:85], v[164:167], v[188:191], v[82:85]
	v_mfma_f32_16x16x32_bf16 v[70:73], v[154:157], v[196:199], v[70:73]
	v_mfma_f32_16x16x32_bf16 v[66:69], v[164:167], v[196:199], v[66:69]
	v_mfma_f32_16x16x32_bf16 v[118:121], v[160:163], v[176:179], v[118:121]
	v_mfma_f32_16x16x32_bf16 v[114:117], v[168:171], v[176:179], v[114:117]
	v_mfma_f32_16x16x32_bf16 v[102:105], v[160:163], v[184:187], v[102:105]
	v_mfma_f32_16x16x32_bf16 v[98:101], v[168:171], v[184:187], v[98:101]
	v_mfma_f32_16x16x32_bf16 v[86:89], v[160:163], v[192:195], v[86:89]
	v_mfma_f32_16x16x32_bf16 v[82:85], v[168:171], v[192:195], v[82:85]
	v_mfma_f32_16x16x32_bf16 v[70:73], v[160:163], v[200:203], v[70:73]
	v_mfma_f32_16x16x32_bf16 v[66:69], v[168:171], v[200:203], v[66:69]
	s_setprio 0
	s_barrier
	s_add_i32 s67, s67, s42
	ds_read_b128 v[172:175], v127 offset:16384
	ds_read_b128 v[176:179], v127 offset:17408
	ds_read_b128 v[180:183], v127 offset:18432
	ds_read_b128 v[184:187], v127 offset:19456
	ds_read_b128 v[188:191], v127 offset:20480
	ds_read_b128 v[192:195], v127 offset:21504
	ds_read_b128 v[196:199], v127 offset:22528
	ds_read_b128 v[200:203], v127 offset:23552
	s_mov_b32 m0, s67
	s_nop 0
	global_load_lds_dwordx4 v124, s[22:23]
	s_add_i32 m0, s67, 0x2000
	s_add_u32 s68, s22, 0x40000
	global_load_lds_dwordx4 v125, s[22:23]
	s_addc_u32 s69, s23, 0
	s_add_i32 s67, s70, s42
	s_mov_b32 m0, s67
	s_nop 0
	global_load_lds_dwordx4 v124, s[68:69]
	s_add_i32 m0, s67, 0x2000
	s_nop 0
	global_load_lds_dwordx4 v125, s[68:69]
	s_mov_b32 m0, s43
	s_nop 0
	global_load_lds_dwordx4 v122, s[16:17]
	s_mov_b32 m0, s46
	s_nop 0
	global_load_lds_dwordx4 v123, s[16:17]
	s_waitcnt vmcnt(8)
	s_waitcnt lgkmcnt(0)
	s_setprio 1
	s_barrier
	v_mfma_f32_16x16x32_bf16 v[62:65], v[128:131], v[172:175], v[62:65]
	v_mfma_f32_16x16x32_bf16 v[58:61], v[146:149], v[172:175], v[58:61]
	v_mfma_f32_16x16x32_bf16 v[46:49], v[128:131], v[180:183], v[46:49]
	v_mfma_f32_16x16x32_bf16 v[42:45], v[146:149], v[180:183], v[42:45]
	v_mfma_f32_16x16x32_bf16 v[30:33], v[128:131], v[188:191], v[30:33]
	v_mfma_f32_16x16x32_bf16 v[26:29], v[146:149], v[188:191], v[26:29]
	v_mfma_f32_16x16x32_bf16 v[14:17], v[128:131], v[196:199], v[14:17]
	v_mfma_f32_16x16x32_bf16 v[10:13], v[146:149], v[196:199], v[10:13]
	v_mfma_f32_16x16x32_bf16 v[62:65], v[142:145], v[176:179], v[62:65]
	v_mfma_f32_16x16x32_bf16 v[58:61], v[150:153], v[176:179], v[58:61]
	v_mfma_f32_16x16x32_bf16 v[46:49], v[142:145], v[184:187], v[46:49]
	v_mfma_f32_16x16x32_bf16 v[42:45], v[150:153], v[184:187], v[42:45]
	v_mfma_f32_16x16x32_bf16 v[30:33], v[142:145], v[192:195], v[30:33]
	v_mfma_f32_16x16x32_bf16 v[26:29], v[150:153], v[192:195], v[26:29]
	v_mfma_f32_16x16x32_bf16 v[14:17], v[142:145], v[200:203], v[14:17]
	v_mfma_f32_16x16x32_bf16 v[10:13], v[150:153], v[200:203], v[10:13]
	s_setprio 0
	s_setprio 1
	v_mfma_f32_16x16x32_bf16 v[54:57], v[154:157], v[172:175], v[54:57]
	v_mfma_f32_16x16x32_bf16 v[50:53], v[164:167], v[172:175], v[50:53]
	v_mfma_f32_16x16x32_bf16 v[38:41], v[154:157], v[180:183], v[38:41]
	v_mfma_f32_16x16x32_bf16 v[34:37], v[164:167], v[180:183], v[34:37]
	v_mfma_f32_16x16x32_bf16 v[22:25], v[154:157], v[188:191], v[22:25]
	v_mfma_f32_16x16x32_bf16 v[18:21], v[164:167], v[188:191], v[18:21]
	v_mfma_f32_16x16x32_bf16 v[6:9], v[154:157], v[196:199], v[6:9]
	v_mfma_f32_16x16x32_bf16 v[2:5], v[164:167], v[196:199], v[2:5]
	v_mfma_f32_16x16x32_bf16 v[54:57], v[160:163], v[176:179], v[54:57]
	v_mfma_f32_16x16x32_bf16 v[50:53], v[168:171], v[176:179], v[50:53]
	v_mfma_f32_16x16x32_bf16 v[38:41], v[160:163], v[184:187], v[38:41]
	v_mfma_f32_16x16x32_bf16 v[34:37], v[168:171], v[184:187], v[34:37]
	v_mfma_f32_16x16x32_bf16 v[22:25], v[160:163], v[192:195], v[22:25]
	v_mfma_f32_16x16x32_bf16 v[18:21], v[168:171], v[192:195], v[18:21]
	v_mfma_f32_16x16x32_bf16 v[6:9], v[160:163], v[200:203], v[6:9]
	v_mfma_f32_16x16x32_bf16 v[2:5], v[168:171], v[200:203], v[2:5]
	s_setprio 0
	s_barrier
	s_add_i32 s67, 0, 0x18000
	s_add_i32 s70, 0, 0x1c000
	ds_read_b128 v[128:131], v0 offset:32768
	ds_read_b128 v[142:145], v0 offset:33792
	ds_read_b128 v[146:149], v0 offset:34816
	ds_read_b128 v[150:153], v0 offset:35840
	ds_read_b128 v[154:157], v0 offset:49152
	ds_read_b128 v[160:163], v0 offset:50176
	ds_read_b128 v[164:167], v0 offset:51200
	ds_read_b128 v[168:171], v0 offset:52224
	s_add_u32 s68, s16, 0x40000
	s_mov_b32 m0, s47
	ds_read_b128 v[172:175], v127 offset:32768
	ds_read_b128 v[176:179], v127 offset:33792
	ds_read_b128 v[180:183], v127 offset:34816
	ds_read_b128 v[184:187], v127 offset:35840
	ds_read_b128 v[188:191], v127 offset:36864
	ds_read_b128 v[192:195], v127 offset:37888
	ds_read_b128 v[196:199], v127 offset:38912
	ds_read_b128 v[200:203], v127 offset:39936
	s_addc_u32 s69, s17, 0
	s_nop 0
	global_load_lds_dwordx4 v122, s[68:69]
	s_mov_b32 m0, s48
	s_nop 0
	global_load_lds_dwordx4 v123, s[68:69]
	s_waitcnt vmcnt(8)
	s_waitcnt lgkmcnt(0)
	s_setprio 1
	s_barrier
	v_mfma_f32_16x16x32_bf16 v[136:139], v[128:131], v[172:175], v[138:141]
	v_mfma_f32_16x16x32_bf16 v[132:135], v[146:149], v[172:175], v[132:135]
	v_mfma_f32_16x16x32_bf16 v[110:113], v[128:131], v[180:183], v[110:113]
	v_mfma_f32_16x16x32_bf16 v[106:109], v[146:149], v[180:183], v[106:109]
	v_mfma_f32_16x16x32_bf16 v[94:97], v[128:131], v[188:191], v[94:97]
	v_mfma_f32_16x16x32_bf16 v[90:93], v[146:149], v[188:191], v[90:93]
	v_mfma_f32_16x16x32_bf16 v[78:81], v[128:131], v[196:199], v[78:81]
	v_mfma_f32_16x16x32_bf16 v[74:77], v[146:149], v[196:199], v[74:77]
	v_mfma_f32_16x16x32_bf16 v[138:141], v[142:145], v[176:179], v[136:139]
	v_mfma_f32_16x16x32_bf16 v[134:137], v[150:153], v[176:179], v[132:135]
	v_mfma_f32_16x16x32_bf16 v[110:113], v[142:145], v[184:187], v[110:113]
	v_mfma_f32_16x16x32_bf16 v[106:109], v[150:153], v[184:187], v[106:109]
	v_mfma_f32_16x16x32_bf16 v[94:97], v[142:145], v[192:195], v[94:97]
	v_mfma_f32_16x16x32_bf16 v[90:93], v[150:153], v[192:195], v[90:93]
	v_mfma_f32_16x16x32_bf16 v[78:81], v[142:145], v[200:203], v[78:81]
	v_mfma_f32_16x16x32_bf16 v[74:77], v[150:153], v[200:203], v[74:77]
	s_setprio 0
	s_setprio 1
	v_mfma_f32_16x16x32_bf16 v[118:121], v[154:157], v[172:175], v[118:121]
	v_mfma_f32_16x16x32_bf16 v[114:117], v[164:167], v[172:175], v[114:117]
	v_mfma_f32_16x16x32_bf16 v[102:105], v[154:157], v[180:183], v[102:105]
	v_mfma_f32_16x16x32_bf16 v[98:101], v[164:167], v[180:183], v[98:101]
	v_mfma_f32_16x16x32_bf16 v[86:89], v[154:157], v[188:191], v[86:89]
	v_mfma_f32_16x16x32_bf16 v[82:85], v[164:167], v[188:191], v[82:85]
	v_mfma_f32_16x16x32_bf16 v[70:73], v[154:157], v[196:199], v[70:73]
	v_mfma_f32_16x16x32_bf16 v[66:69], v[164:167], v[196:199], v[66:69]
	v_mfma_f32_16x16x32_bf16 v[118:121], v[160:163], v[176:179], v[118:121]
	v_mfma_f32_16x16x32_bf16 v[114:117], v[168:171], v[176:179], v[114:117]
	v_mfma_f32_16x16x32_bf16 v[102:105], v[160:163], v[184:187], v[102:105]
	v_mfma_f32_16x16x32_bf16 v[98:101], v[168:171], v[184:187], v[98:101]
	v_mfma_f32_16x16x32_bf16 v[86:89], v[160:163], v[192:195], v[86:89]
	v_mfma_f32_16x16x32_bf16 v[82:85], v[168:171], v[192:195], v[82:85]
	v_mfma_f32_16x16x32_bf16 v[70:73], v[160:163], v[200:203], v[70:73]
	v_mfma_f32_16x16x32_bf16 v[66:69], v[168:171], v[200:203], v[66:69]
	s_setprio 0
	s_barrier
	ds_read_b128 v[172:175], v127 offset:49152
	ds_read_b128 v[176:179], v127 offset:50176
	ds_read_b128 v[180:183], v127 offset:51200
	ds_read_b128 v[184:187], v127 offset:52224
	ds_read_b128 v[188:191], v127 offset:53248
	ds_read_b128 v[192:195], v127 offset:54272
	ds_read_b128 v[196:199], v127 offset:55296
	ds_read_b128 v[200:203], v127 offset:56320
	s_add_i32 s67, s67, s42
	s_add_u32 s100, s22, s38
	s_addc_u32 s101, s23, s39
	s_mov_b32 m0, s67
	s_nop 0
	global_load_lds_dwordx4 v124, s[100:101]
	s_add_i32 m0, s67, 0x2000
	s_nop 0
	s_add_u32 s22, s22, 0x40080
	s_addc_u32 s23, s23, 0
	s_add_i32 s67, s70, s42
	global_load_lds_dwordx4 v125, s[100:101]
	s_mov_b32 m0, s67
	s_nop 0
	global_load_lds_dwordx4 v124, s[22:23]
	s_add_i32 m0, s67, 0x2000
	s_nop 0
	global_load_lds_dwordx4 v125, s[22:23]
	s_mov_b32 m0, s64
	s_add_u32 s100, s16, s38
	s_addc_u32 s101, s17, s39
	v_mov_b32_e32 v0, v123
	global_load_lds_dwordx4 v122, s[100:101]
	s_mov_b32 m0, s65
	s_nop 0
	global_load_lds_dwordx4 v123, s[100:101]
	s_waitcnt vmcnt(8)
	s_waitcnt lgkmcnt(0)
	s_setprio 1
	s_barrier
	v_mfma_f32_16x16x32_bf16 v[62:65], v[128:131], v[172:175], v[62:65]
	v_mfma_f32_16x16x32_bf16 v[58:61], v[146:149], v[172:175], v[58:61]
	v_mfma_f32_16x16x32_bf16 v[46:49], v[128:131], v[180:183], v[46:49]
	v_mfma_f32_16x16x32_bf16 v[42:45], v[146:149], v[180:183], v[42:45]
	v_mfma_f32_16x16x32_bf16 v[30:33], v[128:131], v[188:191], v[30:33]
	v_mfma_f32_16x16x32_bf16 v[26:29], v[146:149], v[188:191], v[26:29]
	v_mfma_f32_16x16x32_bf16 v[14:17], v[128:131], v[196:199], v[14:17]
	v_mfma_f32_16x16x32_bf16 v[10:13], v[146:149], v[196:199], v[10:13]
	v_mfma_f32_16x16x32_bf16 v[62:65], v[142:145], v[176:179], v[62:65]
	v_mfma_f32_16x16x32_bf16 v[58:61], v[150:153], v[176:179], v[58:61]
	v_mfma_f32_16x16x32_bf16 v[46:49], v[142:145], v[184:187], v[46:49]
	v_mfma_f32_16x16x32_bf16 v[42:45], v[150:153], v[184:187], v[42:45]
	v_mfma_f32_16x16x32_bf16 v[30:33], v[142:145], v[192:195], v[30:33]
	v_mfma_f32_16x16x32_bf16 v[26:29], v[150:153], v[192:195], v[26:29]
	v_mfma_f32_16x16x32_bf16 v[14:17], v[142:145], v[200:203], v[14:17]
	v_mfma_f32_16x16x32_bf16 v[10:13], v[150:153], v[200:203], v[10:13]
	s_setprio 0
	s_setprio 1
	v_mfma_f32_16x16x32_bf16 v[54:57], v[154:157], v[172:175], v[54:57]
	v_mfma_f32_16x16x32_bf16 v[50:53], v[164:167], v[172:175], v[50:53]
	v_mfma_f32_16x16x32_bf16 v[38:41], v[154:157], v[180:183], v[38:41]
	v_mfma_f32_16x16x32_bf16 v[34:37], v[164:167], v[180:183], v[34:37]
	v_mfma_f32_16x16x32_bf16 v[22:25], v[154:157], v[188:191], v[22:25]
	v_mfma_f32_16x16x32_bf16 v[18:21], v[164:167], v[188:191], v[18:21]
	v_mfma_f32_16x16x32_bf16 v[6:9], v[154:157], v[196:199], v[6:9]
	v_mfma_f32_16x16x32_bf16 v[2:5], v[164:167], v[196:199], v[2:5]
	v_mfma_f32_16x16x32_bf16 v[54:57], v[160:163], v[176:179], v[54:57]
	v_mfma_f32_16x16x32_bf16 v[50:53], v[168:171], v[176:179], v[50:53]
	v_mfma_f32_16x16x32_bf16 v[38:41], v[160:163], v[184:187], v[38:41]
	v_mfma_f32_16x16x32_bf16 v[34:37], v[168:171], v[184:187], v[34:37]
	v_mfma_f32_16x16x32_bf16 v[22:25], v[160:163], v[192:195], v[22:25]
	v_mfma_f32_16x16x32_bf16 v[18:21], v[168:171], v[192:195], v[18:21]
	v_mfma_f32_16x16x32_bf16 v[6:9], v[160:163], v[200:203], v[6:9]
	v_mfma_f32_16x16x32_bf16 v[2:5], v[168:171], v[200:203], v[2:5]
	s_setprio 0
	s_barrier
	s_add_i32 s66, s66, 2
	s_add_u32 s14, s14, 0x100
	s_addc_u32 s15, s15, 0
	s_cmp_gt_u32 s66, 13
	s_cbranch_scc0 .LBB0_1807
	s_cmpk_lt_u32 s26, 0x100
	s_cbranch_scc0 .LBB0_1810
	s_barrier

.LBB0_1886:
	s_add_u32 s6, s4, 0xfffc0080
	s_addc_u32 s7, s5, -1
	s_add_i32 s47, 0, 0x10000
	s_cmp_eq_u32 s46, 12
	s_cselect_b32 s7, s3, s7
	s_cselect_b32 s6, s2, s6
	v_add_u32_e32 v0, s47, v127
	s_cselect_b32 s11, s40, s43
	s_cselect_b32 s10, s26, s37
	s_add_i32 s50, 0, 0x14000
	ds_read_b128 v[130:133], v0
	ds_read_b128 v[134:137], v0 offset:1024
	ds_read_b128 v[138:141], v0 offset:2048
	ds_read_b128 v[142:145], v0 offset:3072
	ds_read_b128 v[146:149], v0 offset:16384
	ds_read_b128 v[158:161], v0 offset:17408
	ds_read_b128 v[162:165], v0 offset:18432
	ds_read_b128 v[166:169], v0 offset:19456
	ds_read_b128 v[170:173], v128
	ds_read_b128 v[174:177], v128 offset:1024
	ds_read_b128 v[178:181], v128 offset:2048
	ds_read_b128 v[182:185], v128 offset:3072
	ds_read_b128 v[186:189], v128 offset:4096
	ds_read_b128 v[190:193], v128 offset:5120
	ds_read_b128 v[194:197], v128 offset:6144
	ds_read_b128 v[198:201], v128 offset:7168
	s_add_i32 m0, s17, 0xc000
	s_nop 0
	global_load_lds_dwordx4 v122, s[4:5]
	s_add_i32 m0, s17, 0xe000
	s_nop 0
	global_load_lds_dwordx4 v123, s[4:5]
	s_waitcnt vmcnt(8)
	s_waitcnt lgkmcnt(0)
	s_setprio 1
	s_barrier
	v_mfma_f32_16x16x32_bf16 v[154:157], v[130:133], v[170:173], v[154:157]
	v_mfma_f32_16x16x32_bf16 v[150:153], v[138:141], v[170:173], v[150:153]
	v_mfma_f32_16x16x32_bf16 v[110:113], v[130:133], v[178:181], v[110:113]
	v_mfma_f32_16x16x32_bf16 v[106:109], v[138:141], v[178:181], v[106:109]
	v_mfma_f32_16x16x32_bf16 v[94:97], v[130:133], v[186:189], v[94:97]
	v_mfma_f32_16x16x32_bf16 v[90:93], v[138:141], v[186:189], v[90:93]
	v_mfma_f32_16x16x32_bf16 v[78:81], v[130:133], v[194:197], v[78:81]
	v_mfma_f32_16x16x32_bf16 v[74:77], v[138:141], v[194:197], v[74:77]
	v_mfma_f32_16x16x32_bf16 v[154:157], v[134:137], v[174:177], v[154:157]
	v_mfma_f32_16x16x32_bf16 v[150:153], v[142:145], v[174:177], v[150:153]
	v_mfma_f32_16x16x32_bf16 v[110:113], v[134:137], v[182:185], v[110:113]
	v_mfma_f32_16x16x32_bf16 v[106:109], v[142:145], v[182:185], v[106:109]
	v_mfma_f32_16x16x32_bf16 v[94:97], v[134:137], v[190:193], v[94:97]
	v_mfma_f32_16x16x32_bf16 v[90:93], v[142:145], v[190:193], v[90:93]
	v_mfma_f32_16x16x32_bf16 v[78:81], v[134:137], v[198:201], v[78:81]
	v_mfma_f32_16x16x32_bf16 v[74:77], v[142:145], v[198:201], v[74:77]
	s_setprio 0
	s_setprio 1
	v_mfma_f32_16x16x32_bf16 v[118:121], v[146:149], v[170:173], v[118:121]
	v_mfma_f32_16x16x32_bf16 v[114:117], v[162:165], v[170:173], v[114:117]
	v_mfma_f32_16x16x32_bf16 v[102:105], v[146:149], v[178:181], v[102:105]
	v_mfma_f32_16x16x32_bf16 v[98:101], v[162:165], v[178:181], v[98:101]
	v_mfma_f32_16x16x32_bf16 v[86:89], v[146:149], v[186:189], v[86:89]
	v_mfma_f32_16x16x32_bf16 v[82:85], v[162:165], v[186:189], v[82:85]
	v_mfma_f32_16x16x32_bf16 v[70:73], v[146:149], v[194:197], v[70:73]
	v_mfma_f32_16x16x32_bf16 v[66:69], v[162:165], v[194:197], v[66:69]
	v_mfma_f32_16x16x32_bf16 v[118:121], v[158:161], v[174:177], v[118:121]
	v_mfma_f32_16x16x32_bf16 v[114:117], v[166:169], v[174:177], v[114:117]
	v_mfma_f32_16x16x32_bf16 v[102:105], v[158:161], v[182:185], v[102:105]
	v_mfma_f32_16x16x32_bf16 v[98:101], v[166:169], v[182:185], v[98:101]
	v_mfma_f32_16x16x32_bf16 v[86:89], v[158:161], v[190:193], v[86:89]
	v_mfma_f32_16x16x32_bf16 v[82:85], v[166:169], v[190:193], v[82:85]
	v_mfma_f32_16x16x32_bf16 v[70:73], v[158:161], v[198:201], v[70:73]
	v_mfma_f32_16x16x32_bf16 v[66:69], v[166:169], v[198:201], v[66:69]
	s_setprio 0
	s_barrier
	s_add_i32 s47, s47, s16
	ds_read_b128 v[170:173], v128 offset:16384
	ds_read_b128 v[174:177], v128 offset:17408
	ds_read_b128 v[178:181], v128 offset:18432
	ds_read_b128 v[182:185], v128 offset:19456
	ds_read_b128 v[186:189], v128 offset:20480
	ds_read_b128 v[190:193], v128 offset:21504
	ds_read_b128 v[194:197], v128 offset:22528
	ds_read_b128 v[198:201], v128 offset:23552
	s_mov_b32 m0, s47
	s_nop 0
	global_load_lds_dwordx4 v125, s[10:11]
	s_add_i32 m0, s47, 0x2000
	s_add_u32 s48, s10, 0x40000
	global_load_lds_dwordx4 v126, s[10:11]
	s_addc_u32 s49, s11, 0
	s_add_i32 s47, s50, s16
	s_mov_b32 m0, s47
	s_nop 0
	global_load_lds_dwordx4 v125, s[48:49]
	s_add_i32 m0, s47, 0x2000
	s_nop 0
	global_load_lds_dwordx4 v126, s[48:49]
	s_mov_b32 m0, s17
	s_nop 0
	global_load_lds_dwordx4 v122, s[6:7]
	s_mov_b32 m0, s22
	s_nop 0
	global_load_lds_dwordx4 v123, s[6:7]
	s_waitcnt vmcnt(8)
	s_waitcnt lgkmcnt(0)
	s_setprio 1
	s_barrier
	v_mfma_f32_16x16x32_bf16 v[62:65], v[130:133], v[170:173], v[62:65]
	v_mfma_f32_16x16x32_bf16 v[58:61], v[138:141], v[170:173], v[58:61]
	v_mfma_f32_16x16x32_bf16 v[46:49], v[130:133], v[178:181], v[46:49]
	v_mfma_f32_16x16x32_bf16 v[42:45], v[138:141], v[178:181], v[42:45]
	v_mfma_f32_16x16x32_bf16 v[30:33], v[130:133], v[186:189], v[30:33]
	v_mfma_f32_16x16x32_bf16 v[26:29], v[138:141], v[186:189], v[26:29]
	v_mfma_f32_16x16x32_bf16 v[14:17], v[130:133], v[194:197], v[14:17]
	v_mfma_f32_16x16x32_bf16 v[10:13], v[138:141], v[194:197], v[10:13]
	v_mfma_f32_16x16x32_bf16 v[62:65], v[134:137], v[174:177], v[62:65]
	v_mfma_f32_16x16x32_bf16 v[58:61], v[142:145], v[174:177], v[58:61]
	v_mfma_f32_16x16x32_bf16 v[46:49], v[134:137], v[182:185], v[46:49]
	v_mfma_f32_16x16x32_bf16 v[42:45], v[142:145], v[182:185], v[42:45]
	v_mfma_f32_16x16x32_bf16 v[30:33], v[134:137], v[190:193], v[30:33]
	v_mfma_f32_16x16x32_bf16 v[26:29], v[142:145], v[190:193], v[26:29]
	v_mfma_f32_16x16x32_bf16 v[14:17], v[134:137], v[198:201], v[14:17]
	v_mfma_f32_16x16x32_bf16 v[10:13], v[142:145], v[198:201], v[10:13]
	s_setprio 0
	s_setprio 1
	v_mfma_f32_16x16x32_bf16 v[54:57], v[146:149], v[170:173], v[54:57]
	v_mfma_f32_16x16x32_bf16 v[50:53], v[162:165], v[170:173], v[50:53]
	v_mfma_f32_16x16x32_bf16 v[38:41], v[146:149], v[178:181], v[38:41]
	v_mfma_f32_16x16x32_bf16 v[34:37], v[162:165], v[178:181], v[34:37]
	v_mfma_f32_16x16x32_bf16 v[22:25], v[146:149], v[186:189], v[22:25]
	v_mfma_f32_16x16x32_bf16 v[18:21], v[162:165], v[186:189], v[18:21]
	v_mfma_f32_16x16x32_bf16 v[6:9], v[146:149], v[194:197], v[6:9]
	v_mfma_f32_16x16x32_bf16 v[2:5], v[162:165], v[194:197], v[2:5]
	v_mfma_f32_16x16x32_bf16 v[54:57], v[158:161], v[174:177], v[54:57]
	v_mfma_f32_16x16x32_bf16 v[50:53], v[166:169], v[174:177], v[50:53]
	v_mfma_f32_16x16x32_bf16 v[38:41], v[158:161], v[182:185], v[38:41]
	v_mfma_f32_16x16x32_bf16 v[34:37], v[166:169], v[182:185], v[34:37]
	v_mfma_f32_16x16x32_bf16 v[22:25], v[158:161], v[190:193], v[22:25]
	v_mfma_f32_16x16x32_bf16 v[18:21], v[166:169], v[190:193], v[18:21]
	v_mfma_f32_16x16x32_bf16 v[6:9], v[158:161], v[198:201], v[6:9]
	v_mfma_f32_16x16x32_bf16 v[2:5], v[166:169], v[198:201], v[2:5]
	s_setprio 0
	s_barrier
	s_add_i32 s47, 0, 0x18000
	s_add_i32 s50, 0, 0x1c000
	ds_read_b128 v[130:133], v0 offset:32768
	ds_read_b128 v[134:137], v0 offset:33792
	ds_read_b128 v[138:141], v0 offset:34816
	ds_read_b128 v[142:145], v0 offset:35840
	ds_read_b128 v[146:149], v0 offset:49152
	ds_read_b128 v[158:161], v0 offset:50176
	ds_read_b128 v[162:165], v0 offset:51200
	ds_read_b128 v[166:169], v0 offset:52224
	s_add_u32 s48, s6, 0x40000
	s_mov_b32 m0, s23
	ds_read_b128 v[170:173], v128 offset:32768
	ds_read_b128 v[174:177], v128 offset:33792
	ds_read_b128 v[178:181], v128 offset:34816
	ds_read_b128 v[182:185], v128 offset:35840
	ds_read_b128 v[186:189], v128 offset:36864
	ds_read_b128 v[190:193], v128 offset:37888
	ds_read_b128 v[194:197], v128 offset:38912
	ds_read_b128 v[198:201], v128 offset:39936
	s_addc_u32 s49, s7, 0
	s_nop 0
	global_load_lds_dwordx4 v122, s[48:49]
	s_mov_b32 m0, s24
	s_nop 0
	global_load_lds_dwordx4 v123, s[48:49]
	s_waitcnt vmcnt(8)
	s_waitcnt lgkmcnt(0)
	s_setprio 1
	s_barrier
	v_mfma_f32_16x16x32_bf16 v[154:157], v[130:133], v[170:173], v[154:157]
	v_mfma_f32_16x16x32_bf16 v[150:153], v[138:141], v[170:173], v[150:153]
	v_mfma_f32_16x16x32_bf16 v[110:113], v[130:133], v[178:181], v[110:113]
	v_mfma_f32_16x16x32_bf16 v[106:109], v[138:141], v[178:181], v[106:109]
	v_mfma_f32_16x16x32_bf16 v[94:97], v[130:133], v[186:189], v[94:97]
	v_mfma_f32_16x16x32_bf16 v[90:93], v[138:141], v[186:189], v[90:93]
	v_mfma_f32_16x16x32_bf16 v[78:81], v[130:133], v[194:197], v[78:81]
	v_mfma_f32_16x16x32_bf16 v[74:77], v[138:141], v[194:197], v[74:77]
	v_mfma_f32_16x16x32_bf16 v[154:157], v[134:137], v[174:177], v[154:157]
	v_mfma_f32_16x16x32_bf16 v[150:153], v[142:145], v[174:177], v[150:153]
	v_mfma_f32_16x16x32_bf16 v[110:113], v[134:137], v[182:185], v[110:113]
	v_mfma_f32_16x16x32_bf16 v[106:109], v[142:145], v[182:185], v[106:109]
	v_mfma_f32_16x16x32_bf16 v[94:97], v[134:137], v[190:193], v[94:97]
	v_mfma_f32_16x16x32_bf16 v[90:93], v[142:145], v[190:193], v[90:93]
	v_mfma_f32_16x16x32_bf16 v[78:81], v[134:137], v[198:201], v[78:81]
	v_mfma_f32_16x16x32_bf16 v[74:77], v[142:145], v[198:201], v[74:77]
	s_setprio 0
	s_setprio 1
	v_mfma_f32_16x16x32_bf16 v[118:121], v[146:149], v[170:173], v[118:121]
	v_mfma_f32_16x16x32_bf16 v[114:117], v[162:165], v[170:173], v[114:117]
	v_mfma_f32_16x16x32_bf16 v[102:105], v[146:149], v[178:181], v[102:105]
	v_mfma_f32_16x16x32_bf16 v[98:101], v[162:165], v[178:181], v[98:101]
	v_mfma_f32_16x16x32_bf16 v[86:89], v[146:149], v[186:189], v[86:89]
	v_mfma_f32_16x16x32_bf16 v[82:85], v[162:165], v[186:189], v[82:85]
	v_mfma_f32_16x16x32_bf16 v[70:73], v[146:149], v[194:197], v[70:73]
	v_mfma_f32_16x16x32_bf16 v[66:69], v[162:165], v[194:197], v[66:69]
	v_mfma_f32_16x16x32_bf16 v[118:121], v[158:161], v[174:177], v[118:121]
	v_mfma_f32_16x16x32_bf16 v[114:117], v[166:169], v[174:177], v[114:117]
	v_mfma_f32_16x16x32_bf16 v[102:105], v[158:161], v[182:185], v[102:105]
	v_mfma_f32_16x16x32_bf16 v[98:101], v[166:169], v[182:185], v[98:101]
	v_mfma_f32_16x16x32_bf16 v[86:89], v[158:161], v[190:193], v[86:89]
	v_mfma_f32_16x16x32_bf16 v[82:85], v[166:169], v[190:193], v[82:85]
	v_mfma_f32_16x16x32_bf16 v[70:73], v[158:161], v[198:201], v[70:73]
	v_mfma_f32_16x16x32_bf16 v[66:69], v[166:169], v[198:201], v[66:69]
	s_setprio 0
	s_barrier
	ds_read_b128 v[170:173], v128 offset:49152
	ds_read_b128 v[174:177], v128 offset:50176
	ds_read_b128 v[178:181], v128 offset:51200
	ds_read_b128 v[182:185], v128 offset:52224
	ds_read_b128 v[186:189], v128 offset:53248
	ds_read_b128 v[190:193], v128 offset:54272
	ds_read_b128 v[194:197], v128 offset:55296
	ds_read_b128 v[198:201], v128 offset:56320
	s_add_i32 s47, s47, s16
	s_add_u32 s100, s10, s38
	s_addc_u32 s101, s11, s39
	s_mov_b32 m0, s47
	s_nop 0
	global_load_lds_dwordx4 v125, s[100:101]
	s_add_i32 m0, s47, 0x2000
	s_nop 0
	s_add_u32 s10, s10, 0x40080
	s_addc_u32 s11, s11, 0
	s_add_i32 s47, s50, s16
	global_load_lds_dwordx4 v126, s[100:101]
	s_mov_b32 m0, s47
	s_nop 0
	global_load_lds_dwordx4 v125, s[10:11]
	s_add_i32 m0, s47, 0x2000
	s_nop 0
	global_load_lds_dwordx4 v126, s[10:11]
	s_mov_b32 m0, s41
	s_add_u32 s100, s6, s38
	s_addc_u32 s101, s7, s39
	v_mov_b32_e32 v0, v123
	global_load_lds_dwordx4 v122, s[100:101]
	s_mov_b32 m0, s42
	s_nop 0
	global_load_lds_dwordx4 v123, s[100:101]
	s_waitcnt vmcnt(8)
	s_waitcnt lgkmcnt(0)
	s_setprio 1
	s_barrier
	v_mfma_f32_16x16x32_bf16 v[62:65], v[130:133], v[170:173], v[62:65]
	v_mfma_f32_16x16x32_bf16 v[58:61], v[138:141], v[170:173], v[58:61]
	v_mfma_f32_16x16x32_bf16 v[46:49], v[130:133], v[178:181], v[46:49]
	v_mfma_f32_16x16x32_bf16 v[42:45], v[138:141], v[178:181], v[42:45]
	v_mfma_f32_16x16x32_bf16 v[30:33], v[130:133], v[186:189], v[30:33]
	v_mfma_f32_16x16x32_bf16 v[26:29], v[138:141], v[186:189], v[26:29]
	v_mfma_f32_16x16x32_bf16 v[14:17], v[130:133], v[194:197], v[14:17]
	v_mfma_f32_16x16x32_bf16 v[10:13], v[138:141], v[194:197], v[10:13]
	v_mfma_f32_16x16x32_bf16 v[62:65], v[134:137], v[174:177], v[62:65]
	v_mfma_f32_16x16x32_bf16 v[58:61], v[142:145], v[174:177], v[58:61]
	v_mfma_f32_16x16x32_bf16 v[46:49], v[134:137], v[182:185], v[46:49]
	v_mfma_f32_16x16x32_bf16 v[42:45], v[142:145], v[182:185], v[42:45]
	v_mfma_f32_16x16x32_bf16 v[30:33], v[134:137], v[190:193], v[30:33]
	v_mfma_f32_16x16x32_bf16 v[26:29], v[142:145], v[190:193], v[26:29]
	v_mfma_f32_16x16x32_bf16 v[14:17], v[134:137], v[198:201], v[14:17]
	v_mfma_f32_16x16x32_bf16 v[10:13], v[142:145], v[198:201], v[10:13]
	s_setprio 0
	s_setprio 1
	v_mfma_f32_16x16x32_bf16 v[54:57], v[146:149], v[170:173], v[54:57]
	v_mfma_f32_16x16x32_bf16 v[50:53], v[162:165], v[170:173], v[50:53]
	v_mfma_f32_16x16x32_bf16 v[38:41], v[146:149], v[178:181], v[38:41]
	v_mfma_f32_16x16x32_bf16 v[34:37], v[162:165], v[178:181], v[34:37]
	v_mfma_f32_16x16x32_bf16 v[22:25], v[146:149], v[186:189], v[22:25]
	v_mfma_f32_16x16x32_bf16 v[18:21], v[162:165], v[186:189], v[18:21]
	v_mfma_f32_16x16x32_bf16 v[6:9], v[146:149], v[194:197], v[6:9]
	v_mfma_f32_16x16x32_bf16 v[2:5], v[162:165], v[194:197], v[2:5]
	v_mfma_f32_16x16x32_bf16 v[54:57], v[158:161], v[174:177], v[54:57]
	v_mfma_f32_16x16x32_bf16 v[50:53], v[166:169], v[174:177], v[50:53]
	v_mfma_f32_16x16x32_bf16 v[38:41], v[158:161], v[182:185], v[38:41]
	v_mfma_f32_16x16x32_bf16 v[34:37], v[166:169], v[182:185], v[34:37]
	v_mfma_f32_16x16x32_bf16 v[22:25], v[158:161], v[190:193], v[22:25]
	v_mfma_f32_16x16x32_bf16 v[18:21], v[166:169], v[190:193], v[18:21]
	v_mfma_f32_16x16x32_bf16 v[6:9], v[158:161], v[198:201], v[6:9]
	v_mfma_f32_16x16x32_bf16 v[2:5], v[166:169], v[198:201], v[2:5]
	s_setprio 0
	s_barrier
	s_add_i32 s46, s46, 2
	s_add_u32 s4, s4, 0x100
	s_addc_u32 s5, s5, 0
	s_add_u32 s37, s37, 0x100
	s_addc_u32 s43, s43, 0
	s_cmp_gt_u32 s46, 13
	s_cbranch_scc0 .LBB0_1886
	s_cmpk_lt_u32 s14, 0x100
	s_cbranch_scc0 .LBB0_1889
	s_barrier
